# GEMM loops: skip the dummy next-unit prefetch (112 KiB of LDS-DMA) in the last K-iteration of a workgroup's last unit
# speedup vs baseline: 1.0021x; 1.0021x over previous
;     __device__ __forceinline__ size_t aoff(const Unit& u) const { return (size_t)u.pm * bm * lda * 2; }
;     __device__ __forceinline__ size_t boff(const Unit& u) const { return (size_t)u.pn * BM * ldb * 2; }
;     __device__ __forceinline__ size_t aoff(const Unit& u) const { return ((size_t)u.pm * BM * lda + (size_t)u.pn * akoff) * 2; }
;     __device__ __forceinline__ size_t boff(const Unit& u) const { return (size_t)u.pn * BM * ldb * 2; }
;     __device__ __forceinline__ size_t aoff(const Unit& u) const { return ((size_t)u.pm * BM * lda + (size_t)(u.pn >> 1) * akoff) * 2; }
;     __device__ __forceinline__ size_t boff(const Unit& u) const { return (size_t)u.pn * BM * ldb * 2; }
;     __device__ bool next(int i, Unit& u) const {
;         const long L = (long)i * G + c; if (L >= nwg) return false;
;         int wgid = (int)L; { const int q = nwg / NXCD, r = nwg % NXCD, xcd = wgid % NXCD, off = wgid / NXCD; wgid = (xcd < r ? xcd * (q + 1) : r * (q + 1) + (xcd - r) * q) + off; }
;         const int nig = WGM * nN, gid = wgid / nig, fm = gid * WGM, gsz = (nM - fm) < WGM ? (nM - fm) : WGM;
;         u.pm = fm + ((wgid % nig) % gsz); u.pn = (wgid % nig) / gsz; return true;
;     }
;     ...
;         const bool has_next = S.next(ui + 1, nxt);
;         const char* nA = has_next ? (const char*)g.A + S.aoff(nxt) : cA; const char* nB = has_next ? (const char*)g.Bt + S.boff(nxt) : cB;
.LBB0_195:
	s_add_i32 s70, s70, 1
	s_mul_i32 s2, s70, s62
	s_mul_hi_u32 s3, s70, s53
	s_add_i32 s3, s3, s2
	s_mul_i32 s2, s70, s53
	v_readlane_b32 s4, v255, 29
	s_add_u32 s2, s2, s4
	s_addc_u32 s3, s3, s63
	v_mov_b64_e32 v[2:3], 0x900
	v_cmp_lt_i64_e64 s[4:5], s[2:3], v[2:3]
	v_mov_b64_e32 v[2:3], 0x8ff
	v_cmp_gt_i64_e32 vcc, s[2:3], v[2:3]
	s_nop 3
	s_mov_b32 s101, s4
	s_cbranch_vccnz .LBB0_197
	s_ashr_i32 s3, s2, 31
	s_lshr_b32 s3, s3, 29
	s_add_i32 s3, s2, s3
	s_ashr_i32 s9, s3, 3
	s_and_b32 s3, s3, -8
	s_sub_i32 s2, s2, s3
	s_cmp_lt_i32 s2, 0
	s_cselect_b32 s3, s95, 0x120
	s_mul_i32 s2, s2, s3
	s_add_i32 s2, s2, s9
	s_ashr_i32 s3, s2, 31
	s_lshr_b32 s3, s3, 24
	s_add_i32 s3, s2, s3
	s_ashr_i32 s9, s3, 8
	s_lshl_b32 s9, s9, 3
	s_sub_i32 s20, 0x48, s9
	s_min_i32 s21, s20, 8
	s_abs_i32 s20, s21
	v_cvt_f32_u32_e32 v2, s20
	s_sub_i32 s23, 0, s20
	s_and_b32 s3, s3, 0xffffff00
	s_sub_i32 s2, s2, s3
	v_rcp_iflag_f32_e32 v2, v2
	s_abs_i32 s3, s2
	s_xor_b32 s22, s2, s21
	s_ashr_i32 s22, s22, 31
	v_mul_f32_e32 v2, 0x4f7ffffe, v2
	v_cvt_u32_f32_e32 v2, v2
	s_nop 0
	v_readfirstlane_b32 s24, v2
	s_mul_i32 s23, s23, s24
	s_mul_hi_u32 s23, s24, s23
	s_add_i32 s24, s24, s23
	s_mul_hi_u32 s23, s3, s24
	s_mul_i32 s24, s23, s20
	s_sub_i32 s3, s3, s24
	s_add_i32 s25, s23, 1
	s_sub_i32 s24, s3, s20
	s_cmp_ge_u32 s3, s20
	s_cselect_b32 s23, s25, s23
	s_cselect_b32 s3, s24, s3
	s_add_i32 s24, s23, 1
	s_cmp_ge_u32 s3, s20
	s_cselect_b32 s3, s24, s23
	s_xor_b32 s3, s3, s22
	s_sub_i32 s20, s3, s22
	s_mul_i32 s3, s20, s21
	s_sub_i32 s2, s2, s3
	s_add_i32 s22, s9, s2

; #define PG8_STAGE(bufoff, gbase, voff) do { _Pragma("unroll") for (int _i = 0; _i < 2; ++_i) \
;         __builtin_amdgcn_global_load_lds((const unsigned*)((const char*)(gbase) + (voff)[_i]), (LAS unsigned*)(lds + (bufoff) + ldsw + _i * 8192), 16, 0, 0); } while (0)
; #define PG8_LDA(dst, b, h) do { _Pragma("unroll") for (int m = 0; m < NM; ++m) _Pragma("unroll") for (int k = 0; k < 2; ++k) dst[m][k] = *(const LAS bf16x8*)(lds + PG8_SA(b, h) + aoff + m * 2048 + k * 1024); } while (0)
; #define PG8_LDB(dst, b, h) do { _Pragma("unroll") for (int n = 0; n < 2; ++n) _Pragma("unroll") for (int k = 0; k < 2; ++k) dst[n][k] = *(const LAS bf16x8*)(lds + PG8_SB(b, h) + boff + n * 2048 + k * 1024); } while (0)
; #define PG8_MMA(ai, bj, At, Bt) do { __builtin_amdgcn_s_setprio(1); _Pragma("unroll") for (int m = 0; m < NM; ++m) _Pragma("unroll") for (int n = 0; n < 2; ++n) _Pragma("unroll") for (int k = 0; k < 2; ++k) \
;         acc[ai][bj][m][n] = __builtin_amdgcn_mfma_f32_16x16x32_bf16(Bt[n][k], At[m][k], acc[ai][bj][m][n], 0, 0, 0); __builtin_amdgcn_s_setprio(0); } while (0)
; #define PG8_WAIT_V(n) asm volatile("s_waitcnt vmcnt(" #n ")" ::: "memory")
; #define PG8_WAIT_L(n) asm volatile("s_waitcnt lgkmcnt(" #n ")" ::: "memory")
; #define PG8_BAR __builtin_amdgcn_s_barrier()
; #define PG8_SCHED __builtin_amdgcn_sched_barrier(0)
;     ...
;         for (int t = 0; t < nt; t += 2) {
;             const bool last = (t == nt - 2);
;             const char* a1 = cA + (size_t)(t + 1) * kstep;
;             const char* a2 = last ? nA : cA + (size_t)(t + 2) * kstep; const char* b2 = last ? nB : cB + (size_t)(t + 2) * kstep;
;             const char* a3 = a2 + kstep; const char* b3 = b2 + kstep;
;             if constexpr (SP2) {
;             PG8_LDB(B0, 0, 0); PG8_LDB(B1, 0, 1); PG8_SCHED; PG8_LDA(At, 0, 0); PG8_STAGE(PG8_SA(1, 1), a1 + hstepA, voffA);
;             PG8_WAIT_V(8); PG8_WAIT_L(0); PG8_BAR; PG8_MMA(0, 0, At, B0); PG8_MMA(0, 1, At, B1); PG8_BAR; PG8_SCHED;
;             PG8_LDA(At, 0, 1); PG8_STAGE(PG8_SB(0, 0), b2, voffB); PG8_STAGE(PG8_SB(0, 1), b2 + hstepB, voffB); PG8_STAGE(PG8_SA(0, 0), a2, voffA);
.LBB0_200:
	ds_read_b128 v[26:29], v172
	ds_read_b128 v[30:33], v172 offset:1024
	ds_read_b128 v[42:45], v172 offset:2048
	ds_read_b128 v[46:49], v172 offset:3072
	ds_read_b128 v[146:149], v173
	ds_read_b128 v[150:153], v173 offset:1024
	ds_read_b128 v[164:167], v173 offset:2048
	ds_read_b128 v[168:171], v173 offset:3072
	s_add_u32 s30, s28, 0xfff80080
	s_addc_u32 s31, s29, -1
	s_cmp_eq_u32 s56, 28
	s_cselect_b32 s35, s2, s31
	s_cselect_b32 s34, s3, s30
	s_cselect_b32 s31, s9, s54
	s_cselect_b32 s30, s21, s23
	s_cselect_b32 s100, -1, 0
	s_andn2_b32 s100, s100, s101
	s_add_i32 m0, s43, 0xc000
	ds_read_b128 v[178:181], v174
	ds_read_b128 v[182:185], v174 offset:1024
	ds_read_b128 v[186:189], v174 offset:2048
	ds_read_b128 v[190:193], v174 offset:3072
	ds_read_b128 v[194:197], v174 offset:4096
	ds_read_b128 v[198:201], v174 offset:5120
	ds_read_b128 v[202:205], v174 offset:6144
	ds_read_b128 v[206:209], v174 offset:7168
	global_load_lds_dwordx4 v160, s[28:29]
	s_add_i32 m0, s43, 0xe000
	s_nop 0
	global_load_lds_dwordx4 v162, s[28:29]
	s_waitcnt vmcnt(8)
	s_waitcnt lgkmcnt(0)
	s_barrier
	s_setprio 1
	s_waitcnt lgkmcnt(0)
	v_mfma_f32_16x16x32_bf16 v[142:145], v[26:29], v[178:181], v[142:145]
	v_mfma_f32_16x16x32_bf16 v[138:141], v[42:45], v[178:181], v[138:141]
	v_mfma_f32_16x16x32_bf16 v[126:129], v[26:29], v[186:189], v[126:129]
	v_mfma_f32_16x16x32_bf16 v[122:125], v[42:45], v[186:189], v[122:125]
	v_mfma_f32_16x16x32_bf16 v[110:113], v[26:29], v[194:197], v[110:113]
	v_mfma_f32_16x16x32_bf16 v[106:109], v[42:45], v[194:197], v[106:109]
	v_mfma_f32_16x16x32_bf16 v[94:97], v[26:29], v[202:205], v[94:97]
	v_mfma_f32_16x16x32_bf16 v[90:93], v[42:45], v[202:205], v[90:93]
	v_mfma_f32_16x16x32_bf16 v[142:145], v[30:33], v[182:185], v[142:145]
	v_mfma_f32_16x16x32_bf16 v[138:141], v[46:49], v[182:185], v[138:141]
	v_mfma_f32_16x16x32_bf16 v[126:129], v[30:33], v[190:193], v[126:129]
	v_mfma_f32_16x16x32_bf16 v[122:125], v[46:49], v[190:193], v[122:125]
	v_mfma_f32_16x16x32_bf16 v[110:113], v[30:33], v[198:201], v[110:113]
	v_mfma_f32_16x16x32_bf16 v[106:109], v[46:49], v[198:201], v[106:109]
	v_mfma_f32_16x16x32_bf16 v[94:97], v[30:33], v[206:209], v[94:97]
	v_mfma_f32_16x16x32_bf16 v[90:93], v[46:49], v[206:209], v[90:93]
	s_setprio 0
	s_setprio 1
	v_mfma_f32_16x16x32_bf16 v[134:137], v[146:149], v[178:181], v[134:137]
	v_mfma_f32_16x16x32_bf16 v[130:133], v[164:167], v[178:181], v[130:133]
	v_mfma_f32_16x16x32_bf16 v[118:121], v[146:149], v[186:189], v[118:121]
	v_mfma_f32_16x16x32_bf16 v[114:117], v[164:167], v[186:189], v[114:117]
	v_mfma_f32_16x16x32_bf16 v[102:105], v[146:149], v[194:197], v[102:105]
	v_mfma_f32_16x16x32_bf16 v[98:101], v[164:167], v[194:197], v[98:101]
	v_mfma_f32_16x16x32_bf16 v[86:89], v[146:149], v[202:205], v[86:89]
	v_mfma_f32_16x16x32_bf16 v[82:85], v[164:167], v[202:205], v[82:85]
	v_mfma_f32_16x16x32_bf16 v[134:137], v[150:153], v[182:185], v[134:137]
	v_mfma_f32_16x16x32_bf16 v[130:133], v[168:171], v[182:185], v[130:133]
	v_mfma_f32_16x16x32_bf16 v[118:121], v[150:153], v[190:193], v[118:121]
	v_mfma_f32_16x16x32_bf16 v[114:117], v[168:171], v[190:193], v[114:117]
	v_mfma_f32_16x16x32_bf16 v[102:105], v[150:153], v[198:201], v[102:105]
	v_mfma_f32_16x16x32_bf16 v[98:101], v[168:171], v[198:201], v[98:101]
	v_mfma_f32_16x16x32_bf16 v[86:89], v[150:153], v[206:209], v[86:89]
	v_mfma_f32_16x16x32_bf16 v[82:85], v[168:171], v[206:209], v[82:85]
	s_setprio 0
	s_barrier
	s_mov_b32 m0, s39
	v_lshl_add_u64 v[210:211], s[30:31], 0, v[0:1]
	s_add_u32 s72, s30, 0x80000
	s_addc_u32 s73, s31, 0
	ds_read_b128 v[178:181], v174 offset:16384
	ds_read_b128 v[182:185], v174 offset:17408
	ds_read_b128 v[186:189], v174 offset:18432
	ds_read_b128 v[190:193], v174 offset:19456
	ds_read_b128 v[194:197], v174 offset:20480
	ds_read_b128 v[198:201], v174 offset:21504
	ds_read_b128 v[202:205], v174 offset:22528
	ds_read_b128 v[206:209], v174 offset:23552
	s_cmp_lg_u32 s100, 0
	s_cbranch_scc1 .Ltl_ic_0s
	global_load_lds_dwordx4 v0, s[30:31]
	v_lshl_add_u64 v[212:213], s[30:31], 0, v[158:159]
	s_mov_b32 m0, s40
	s_nop 0
	global_load_lds_dwordx4 v158, s[30:31]
	s_mov_b32 m0, s41
	v_lshl_add_u64 v[216:217], s[34:35], 0, v[156:157]
	global_load_lds_dwordx4 v0, s[72:73]
	s_mov_b32 m0, s42
	s_nop 0
	global_load_lds_dwordx4 v158, s[72:73]
	v_lshl_add_u64 v[214:215], s[34:35], 0, v[154:155]
	s_mov_b32 m0, s43
	s_nop 0
	global_load_lds_dwordx4 v154, s[34:35]
	s_mov_b32 m0, s44
	s_nop 0
	global_load_lds_dwordx4 v156, s[34:35]
	s_waitcnt vmcnt(8)
	s_branch .Ltl_ic_0d

; #define PG8_STAGE(bufoff, gbase, voff) do { _Pragma("unroll") for (int _i = 0; _i < 2; ++_i) \
;         __builtin_amdgcn_global_load_lds((const unsigned*)((const char*)(gbase) + (voff)[_i]), (LAS unsigned*)(lds + (bufoff) + ldsw + _i * 8192), 16, 0, 0); } while (0)
; #define PG8_LDA(dst, b, h) do { _Pragma("unroll") for (int m = 0; m < NM; ++m) _Pragma("unroll") for (int k = 0; k < 2; ++k) dst[m][k] = *(const LAS bf16x8*)(lds + PG8_SA(b, h) + aoff + m * 2048 + k * 1024); } while (0)
; #define PG8_LDB(dst, b, h) do { _Pragma("unroll") for (int n = 0; n < 2; ++n) _Pragma("unroll") for (int k = 0; k < 2; ++k) dst[n][k] = *(const LAS bf16x8*)(lds + PG8_SB(b, h) + boff + n * 2048 + k * 1024); } while (0)
; #define PG8_MMA(ai, bj, At, Bt) do { __builtin_amdgcn_s_setprio(1); _Pragma("unroll") for (int m = 0; m < NM; ++m) _Pragma("unroll") for (int n = 0; n < 2; ++n) _Pragma("unroll") for (int k = 0; k < 2; ++k) \
;         acc[ai][bj][m][n] = __builtin_amdgcn_mfma_f32_16x16x32_bf16(Bt[n][k], At[m][k], acc[ai][bj][m][n], 0, 0, 0); __builtin_amdgcn_s_setprio(0); } while (0)
; #define PG8_WAIT_V(n) asm volatile("s_waitcnt vmcnt(" #n ")" ::: "memory")
; #define PG8_WAIT_L(n) asm volatile("s_waitcnt lgkmcnt(" #n ")" ::: "memory")
; #define PG8_BAR __builtin_amdgcn_s_barrier()
; #define PG8_SCHED __builtin_amdgcn_sched_barrier(0)
;     ...
;             PG8_LDA(At, 0, 1); PG8_STAGE(PG8_SB(0, 0), b2, voffB); PG8_STAGE(PG8_SB(0, 1), b2 + hstepB, voffB); PG8_STAGE(PG8_SA(0, 0), a2, voffA);
;             PG8_WAIT_V(8); PG8_WAIT_L(0); PG8_BAR; PG8_MMA(1, 0, At, B0); PG8_MMA(1, 1, At, B1); PG8_BAR; PG8_SCHED;
;             PG8_LDB(B0, 1, 0); PG8_LDB(B1, 1, 1); PG8_SCHED; PG8_LDA(At, 1, 0); PG8_STAGE(PG8_SA(0, 1), a2 + hstepA, voffA);
.Ltl_ic_0d:
	s_waitcnt lgkmcnt(0)
	s_barrier
	s_setprio 1
	s_waitcnt lgkmcnt(0)
	v_mfma_f32_16x16x32_bf16 v[78:81], v[26:29], v[178:181], v[78:81]
	v_mfma_f32_16x16x32_bf16 v[74:77], v[42:45], v[178:181], v[74:77]
	v_mfma_f32_16x16x32_bf16 v[62:65], v[26:29], v[186:189], v[62:65]
	v_mfma_f32_16x16x32_bf16 v[58:61], v[42:45], v[186:189], v[58:61]
	v_mfma_f32_16x16x32_bf16 v[38:41], v[26:29], v[194:197], v[38:41]
	v_mfma_f32_16x16x32_bf16 v[34:37], v[42:45], v[194:197], v[34:37]
	v_mfma_f32_16x16x32_bf16 v[14:17], v[26:29], v[202:205], v[14:17]
	v_mfma_f32_16x16x32_bf16 v[10:13], v[42:45], v[202:205], v[10:13]
	v_mfma_f32_16x16x32_bf16 v[78:81], v[30:33], v[182:185], v[78:81]
	v_mfma_f32_16x16x32_bf16 v[74:77], v[46:49], v[182:185], v[74:77]
	v_mfma_f32_16x16x32_bf16 v[62:65], v[30:33], v[190:193], v[62:65]
	v_mfma_f32_16x16x32_bf16 v[58:61], v[46:49], v[190:193], v[58:61]
	v_mfma_f32_16x16x32_bf16 v[38:41], v[30:33], v[198:201], v[38:41]
	v_mfma_f32_16x16x32_bf16 v[34:37], v[46:49], v[198:201], v[34:37]
	v_mfma_f32_16x16x32_bf16 v[14:17], v[30:33], v[206:209], v[14:17]
	v_mfma_f32_16x16x32_bf16 v[10:13], v[46:49], v[206:209], v[10:13]
	s_setprio 0
	s_setprio 1
	v_mfma_f32_16x16x32_bf16 v[22:25], v[146:149], v[194:197], v[22:25]
	v_mfma_f32_16x16x32_bf16 v[18:21], v[164:167], v[194:197], v[18:21]
	v_mfma_f32_16x16x32_bf16 v[6:9], v[146:149], v[202:205], v[6:9]
	v_mfma_f32_16x16x32_bf16 v[2:5], v[164:167], v[202:205], v[2:5]
	v_mfma_f32_16x16x32_bf16 v[26:29], v[146:149], v[178:181], v[70:73]
	v_mfma_f32_16x16x32_bf16 v[30:33], v[164:167], v[178:181], v[66:69]
	v_mfma_f32_16x16x32_bf16 v[42:45], v[146:149], v[186:189], v[54:57]
	v_mfma_f32_16x16x32_bf16 v[46:49], v[164:167], v[186:189], v[50:53]
	v_mfma_f32_16x16x32_bf16 v[22:25], v[150:153], v[198:201], v[22:25]
	v_mfma_f32_16x16x32_bf16 v[18:21], v[168:171], v[198:201], v[18:21]
	v_mfma_f32_16x16x32_bf16 v[6:9], v[150:153], v[206:209], v[6:9]
	v_mfma_f32_16x16x32_bf16 v[2:5], v[168:171], v[206:209], v[2:5]
	v_mfma_f32_16x16x32_bf16 v[26:29], v[150:153], v[182:185], v[26:29]
	v_mfma_f32_16x16x32_bf16 v[30:33], v[168:171], v[182:185], v[30:33]
	v_mfma_f32_16x16x32_bf16 v[42:45], v[150:153], v[190:193], v[42:45]
	v_mfma_f32_16x16x32_bf16 v[46:49], v[168:171], v[190:193], v[46:49]
	s_setprio 0
	s_barrier
	ds_read_b128 v[50:53], v175
	ds_read_b128 v[54:57], v175 offset:1024
	ds_read_b128 v[66:69], v175 offset:2048
	ds_read_b128 v[70:73], v175 offset:3072
	ds_read_b128 v[146:149], v176
	ds_read_b128 v[150:153], v176 offset:1024
	ds_read_b128 v[164:167], v176 offset:2048
	ds_read_b128 v[168:171], v176 offset:3072
	s_add_u32 s34, s34, 0x80000
	s_addc_u32 s35, s35, 0
	s_mov_b32 m0, s45
	ds_read_b128 v[178:181], v174 offset:32768
	ds_read_b128 v[182:185], v174 offset:33792
	ds_read_b128 v[186:189], v174 offset:34816
	ds_read_b128 v[190:193], v174 offset:35840
	ds_read_b128 v[194:197], v174 offset:36864
	ds_read_b128 v[198:201], v174 offset:37888
	ds_read_b128 v[202:205], v174 offset:38912
	ds_read_b128 v[206:209], v174 offset:39936
	s_cmp_lg_u32 s100, 0
	s_cbranch_scc1 .Ltl_ic_1s
	global_load_lds_dwordx4 v154, s[34:35]
	s_mov_b32 m0, s46
	s_nop 0
	global_load_lds_dwordx4 v156, s[34:35]
	s_waitcnt vmcnt(8)
	s_branch .Ltl_ic_1d

; #define PG8_STAGE(bufoff, gbase, voff) do { _Pragma("unroll") for (int _i = 0; _i < 2; ++_i) \
;         __builtin_amdgcn_global_load_lds((const unsigned*)((const char*)(gbase) + (voff)[_i]), (LAS unsigned*)(lds + (bufoff) + ldsw + _i * 8192), 16, 0, 0); } while (0)
; #define PG8_LDA(dst, b, h) do { _Pragma("unroll") for (int m = 0; m < NM; ++m) _Pragma("unroll") for (int k = 0; k < 2; ++k) dst[m][k] = *(const LAS bf16x8*)(lds + PG8_SA(b, h) + aoff + m * 2048 + k * 1024); } while (0)
; #define PG8_LDB(dst, b, h) do { _Pragma("unroll") for (int n = 0; n < 2; ++n) _Pragma("unroll") for (int k = 0; k < 2; ++k) dst[n][k] = *(const LAS bf16x8*)(lds + PG8_SB(b, h) + boff + n * 2048 + k * 1024); } while (0)
; #define PG8_MMA(ai, bj, At, Bt) do { __builtin_amdgcn_s_setprio(1); _Pragma("unroll") for (int m = 0; m < NM; ++m) _Pragma("unroll") for (int n = 0; n < 2; ++n) _Pragma("unroll") for (int k = 0; k < 2; ++k) \
;         acc[ai][bj][m][n] = __builtin_amdgcn_mfma_f32_16x16x32_bf16(Bt[n][k], At[m][k], acc[ai][bj][m][n], 0, 0, 0); __builtin_amdgcn_s_setprio(0); } while (0)
; #define PG8_WAIT_V(n) asm volatile("s_waitcnt vmcnt(" #n ")" ::: "memory")
; #define PG8_WAIT_L(n) asm volatile("s_waitcnt lgkmcnt(" #n ")" ::: "memory")
; #define PG8_BAR __builtin_amdgcn_s_barrier()
; #define PG8_SCHED __builtin_amdgcn_sched_barrier(0)
;     ...
;             PG8_LDB(B0, 1, 0); PG8_LDB(B1, 1, 1); PG8_SCHED; PG8_LDA(At, 1, 0); PG8_STAGE(PG8_SA(0, 1), a2 + hstepA, voffA);
;             PG8_WAIT_V(8); PG8_WAIT_L(0); PG8_BAR; PG8_MMA(0, 0, At, B0); PG8_MMA(0, 1, At, B1); PG8_BAR; PG8_SCHED;
;             PG8_LDA(At, 1, 1); PG8_STAGE(PG8_SB(1, 0), b3, voffB); PG8_STAGE(PG8_SB(1, 1), b3 + hstepB, voffB); PG8_STAGE(PG8_SA(1, 0), a3, voffA);
.Ltl_ic_1d:
	s_waitcnt lgkmcnt(0)
	s_barrier
	s_setprio 1
	s_waitcnt lgkmcnt(0)
	v_mfma_f32_16x16x32_bf16 v[142:145], v[50:53], v[178:181], v[142:145]
	v_mfma_f32_16x16x32_bf16 v[138:141], v[66:69], v[178:181], v[138:141]
	v_mfma_f32_16x16x32_bf16 v[126:129], v[50:53], v[186:189], v[126:129]
	v_mfma_f32_16x16x32_bf16 v[122:125], v[66:69], v[186:189], v[122:125]
	v_mfma_f32_16x16x32_bf16 v[110:113], v[50:53], v[194:197], v[110:113]
	v_mfma_f32_16x16x32_bf16 v[106:109], v[66:69], v[194:197], v[106:109]
	v_mfma_f32_16x16x32_bf16 v[94:97], v[50:53], v[202:205], v[94:97]
	v_mfma_f32_16x16x32_bf16 v[90:93], v[66:69], v[202:205], v[90:93]
	v_mfma_f32_16x16x32_bf16 v[142:145], v[54:57], v[182:185], v[142:145]
	v_mfma_f32_16x16x32_bf16 v[138:141], v[70:73], v[182:185], v[138:141]
	v_mfma_f32_16x16x32_bf16 v[126:129], v[54:57], v[190:193], v[126:129]
	v_mfma_f32_16x16x32_bf16 v[122:125], v[70:73], v[190:193], v[122:125]
	v_mfma_f32_16x16x32_bf16 v[110:113], v[54:57], v[198:201], v[110:113]
	v_mfma_f32_16x16x32_bf16 v[106:109], v[70:73], v[198:201], v[106:109]
	v_mfma_f32_16x16x32_bf16 v[94:97], v[54:57], v[206:209], v[94:97]
	v_mfma_f32_16x16x32_bf16 v[90:93], v[70:73], v[206:209], v[90:93]
	s_setprio 0
	s_setprio 1
	v_mfma_f32_16x16x32_bf16 v[134:137], v[146:149], v[178:181], v[134:137]
	v_mfma_f32_16x16x32_bf16 v[130:133], v[164:167], v[178:181], v[130:133]
	v_mfma_f32_16x16x32_bf16 v[118:121], v[146:149], v[186:189], v[118:121]
	v_mfma_f32_16x16x32_bf16 v[114:117], v[164:167], v[186:189], v[114:117]
	v_mfma_f32_16x16x32_bf16 v[102:105], v[146:149], v[194:197], v[102:105]
	v_mfma_f32_16x16x32_bf16 v[98:101], v[164:167], v[194:197], v[98:101]
	v_mfma_f32_16x16x32_bf16 v[86:89], v[146:149], v[202:205], v[86:89]
	v_mfma_f32_16x16x32_bf16 v[82:85], v[164:167], v[202:205], v[82:85]
	v_mfma_f32_16x16x32_bf16 v[134:137], v[150:153], v[182:185], v[134:137]
	v_mfma_f32_16x16x32_bf16 v[130:133], v[168:171], v[182:185], v[130:133]
	v_mfma_f32_16x16x32_bf16 v[118:121], v[150:153], v[190:193], v[118:121]
	v_mfma_f32_16x16x32_bf16 v[114:117], v[168:171], v[190:193], v[114:117]
	v_mfma_f32_16x16x32_bf16 v[102:105], v[150:153], v[198:201], v[102:105]
	v_mfma_f32_16x16x32_bf16 v[98:101], v[168:171], v[198:201], v[98:101]
	v_mfma_f32_16x16x32_bf16 v[86:89], v[150:153], v[206:209], v[86:89]
	v_mfma_f32_16x16x32_bf16 v[82:85], v[168:171], v[206:209], v[82:85]
	s_setprio 0
	s_barrier
	s_mov_b32 m0, s49
	v_lshl_add_u64 v[210:211], v[210:211], 0, s[66:67]
	s_add_u32 s30, s30, 0x80080
	s_addc_u32 s31, s31, 0
	ds_read_b128 v[178:181], v174 offset:49152
	ds_read_b128 v[182:185], v174 offset:50176
	ds_read_b128 v[186:189], v174 offset:51200
	ds_read_b128 v[190:193], v174 offset:52224
	ds_read_b128 v[194:197], v174 offset:53248
	ds_read_b128 v[198:201], v174 offset:54272
	ds_read_b128 v[202:205], v174 offset:55296
	ds_read_b128 v[206:209], v174 offset:56320
	s_cmp_lg_u32 s100, 0
	s_cbranch_scc1 .Ltl_ic_2s
	global_load_lds_dwordx4 v[210:211], off
	v_lshl_add_u64 v[210:211], v[212:213], 0, s[66:67]
	s_mov_b32 m0, s50
	s_nop 0
	global_load_lds_dwordx4 v[210:211], off
	s_mov_b32 m0, s58
	s_nop 0
	global_load_lds_dwordx4 v0, s[30:31]
	s_mov_b32 m0, s59
	s_nop 0
	global_load_lds_dwordx4 v158, s[30:31]
	v_lshl_add_u64 v[210:211], v[214:215], 0, s[66:67]
	s_mov_b32 m0, s51
	s_nop 0
	global_load_lds_dwordx4 v[210:211], off
	v_lshl_add_u64 v[210:211], v[216:217], 0, s[66:67]
	s_mov_b32 m0, s52
	s_nop 0
	global_load_lds_dwordx4 v[210:211], off
	s_waitcnt vmcnt(8)
	s_branch .Ltl_ic_2d

; #define PG8_STAGE(bufoff, gbase, voff) do { _Pragma("unroll") for (int _i = 0; _i < 2; ++_i) \
;         __builtin_amdgcn_global_load_lds((const unsigned*)((const char*)(gbase) + (voff)[_i]), (LAS unsigned*)(lds + (bufoff) + ldsw + _i * 8192), 16, 0, 0); } while (0)
; #define PG8_LDA(dst, b, h) do { _Pragma("unroll") for (int m = 0; m < NM; ++m) _Pragma("unroll") for (int k = 0; k < 2; ++k) dst[m][k] = *(const LAS bf16x8*)(lds + PG8_SA(b, h) + aoff + m * 2048 + k * 1024); } while (0)
; #define PG8_MMA(ai, bj, At, Bt) do { __builtin_amdgcn_s_setprio(1); _Pragma("unroll") for (int m = 0; m < NM; ++m) _Pragma("unroll") for (int n = 0; n < 2; ++n) _Pragma("unroll") for (int k = 0; k < 2; ++k) \
;         acc[ai][bj][m][n] = __builtin_amdgcn_mfma_f32_16x16x32_bf16(Bt[n][k], At[m][k], acc[ai][bj][m][n], 0, 0, 0); __builtin_amdgcn_s_setprio(0); } while (0)
; #define PG8_WAIT_V(n) asm volatile("s_waitcnt vmcnt(" #n ")" ::: "memory")
; #define PG8_WAIT_L(n) asm volatile("s_waitcnt lgkmcnt(" #n ")" ::: "memory")
; #define PG8_BAR __builtin_amdgcn_s_barrier()
; #define PG8_SCHED __builtin_amdgcn_sched_barrier(0)
;     ...
;             PG8_WAIT_V(8); PG8_WAIT_L(0); PG8_BAR; PG8_MMA(0, 0, At, B0); PG8_MMA(0, 1, At, B1); PG8_BAR; PG8_SCHED;
;             PG8_LDA(At, 1, 1); PG8_STAGE(PG8_SB(1, 0), b3, voffB); PG8_STAGE(PG8_SB(1, 1), b3 + hstepB, voffB); PG8_STAGE(PG8_SA(1, 0), a3, voffA);
;             PG8_WAIT_V(8); PG8_WAIT_L(0); PG8_BAR; PG8_MMA(1, 0, At, B0); PG8_MMA(1, 1, At, B1); PG8_BAR; PG8_SCHED;
;     ...
;         if constexpr (ALIGN_EPI) { if (wr == 0) PG8_BAR; }
.Ltl_ic_2d:
	s_waitcnt lgkmcnt(0)
	s_barrier
	s_setprio 1
	s_waitcnt lgkmcnt(0)
	v_mfma_f32_16x16x32_bf16 v[78:81], v[50:53], v[178:181], v[78:81]
	v_mfma_f32_16x16x32_bf16 v[74:77], v[66:69], v[178:181], v[74:77]
	v_mfma_f32_16x16x32_bf16 v[62:65], v[50:53], v[186:189], v[62:65]
	v_mfma_f32_16x16x32_bf16 v[58:61], v[66:69], v[186:189], v[58:61]
	v_mfma_f32_16x16x32_bf16 v[38:41], v[50:53], v[194:197], v[38:41]
	v_mfma_f32_16x16x32_bf16 v[34:37], v[66:69], v[194:197], v[34:37]
	v_mfma_f32_16x16x32_bf16 v[14:17], v[50:53], v[202:205], v[14:17]
	v_mfma_f32_16x16x32_bf16 v[10:13], v[66:69], v[202:205], v[10:13]
	v_mfma_f32_16x16x32_bf16 v[78:81], v[54:57], v[182:185], v[78:81]
	v_mfma_f32_16x16x32_bf16 v[74:77], v[70:73], v[182:185], v[74:77]
	v_mfma_f32_16x16x32_bf16 v[62:65], v[54:57], v[190:193], v[62:65]
	v_mfma_f32_16x16x32_bf16 v[58:61], v[70:73], v[190:193], v[58:61]
	v_mfma_f32_16x16x32_bf16 v[38:41], v[54:57], v[198:201], v[38:41]
	v_mfma_f32_16x16x32_bf16 v[34:37], v[70:73], v[198:201], v[34:37]
	v_mfma_f32_16x16x32_bf16 v[14:17], v[54:57], v[206:209], v[14:17]
	v_mfma_f32_16x16x32_bf16 v[10:13], v[70:73], v[206:209], v[10:13]
	s_setprio 0
	s_setprio 1
	v_mfma_f32_16x16x32_bf16 v[26:29], v[146:149], v[178:181], v[26:29]
	v_mfma_f32_16x16x32_bf16 v[70:73], v[150:153], v[182:185], v[26:29]
	v_mfma_f32_16x16x32_bf16 v[26:29], v[164:167], v[178:181], v[30:33]
	v_mfma_f32_16x16x32_bf16 v[66:69], v[168:171], v[182:185], v[26:29]
	v_mfma_f32_16x16x32_bf16 v[26:29], v[146:149], v[186:189], v[42:45]
	v_mfma_f32_16x16x32_bf16 v[54:57], v[150:153], v[190:193], v[26:29]
	v_mfma_f32_16x16x32_bf16 v[26:29], v[164:167], v[186:189], v[46:49]
	v_mfma_f32_16x16x32_bf16 v[22:25], v[146:149], v[194:197], v[22:25]
	v_mfma_f32_16x16x32_bf16 v[18:21], v[164:167], v[194:197], v[18:21]
	v_mfma_f32_16x16x32_bf16 v[6:9], v[146:149], v[202:205], v[6:9]
	v_mfma_f32_16x16x32_bf16 v[2:5], v[164:167], v[202:205], v[2:5]
	v_mfma_f32_16x16x32_bf16 v[50:53], v[168:171], v[190:193], v[26:29]
	v_mfma_f32_16x16x32_bf16 v[22:25], v[150:153], v[198:201], v[22:25]
	v_mfma_f32_16x16x32_bf16 v[18:21], v[168:171], v[198:201], v[18:21]
	v_mfma_f32_16x16x32_bf16 v[6:9], v[150:153], v[206:209], v[6:9]
	v_mfma_f32_16x16x32_bf16 v[2:5], v[168:171], v[206:209], v[2:5]
	s_setprio 0
	s_barrier
	s_add_i32 s56, s56, 2
	s_add_u32 s28, s28, 0x100
	s_addc_u32 s29, s29, 0
	s_add_u32 s23, s23, 0x100
	s_addc_u32 s54, s54, 0
	s_cmp_gt_u32 s56, 29
	s_cbranch_scc0 .LBB0_200
	s_and_b64 vcc, exec, s[14:15]
	s_cbranch_vccz .LBB0_203
	s_barrier

;     __device__ __forceinline__ size_t aoff(const Unit& u) const { return (size_t)u.pm * bm * lda * 2; }
;     __device__ __forceinline__ size_t boff(const Unit& u) const { return (size_t)u.pn * BM * ldb * 2; }
;     __device__ __forceinline__ size_t aoff(const Unit& u) const { return ((size_t)u.pm * BM * lda + (size_t)u.pn * akoff) * 2; }
;     __device__ __forceinline__ size_t boff(const Unit& u) const { return (size_t)u.pn * BM * ldb * 2; }
;     __device__ __forceinline__ size_t aoff(const Unit& u) const { return ((size_t)u.pm * BM * lda + (size_t)(u.pn >> 1) * akoff) * 2; }
;     __device__ __forceinline__ size_t boff(const Unit& u) const { return (size_t)u.pn * BM * ldb * 2; }
;     __device__ bool next(int i, Unit& u) const {
;         const long L = (long)i * G + c; if (L >= nwg) return false;
;         int wgid = (int)L; { const int q = nwg / NXCD, r = nwg % NXCD, xcd = wgid % NXCD, off = wgid / NXCD; wgid = (xcd < r ? xcd * (q + 1) : r * (q + 1) + (xcd - r) * q) + off; }
;         const int nig = WGM * nN, gid = wgid / nig, fm = gid * WGM, gsz = (nM - fm) < WGM ? (nM - fm) : WGM;
;         u.pm = fm + ((wgid % nig) % gsz); u.pn = (wgid % nig) / gsz; return true;
;     }
;     ...
;         const bool has_next = S.next(ui + 1, nxt);
;         const char* nA = has_next ? (const char*)g.A + S.aoff(nxt) : cA; const char* nB = has_next ? (const char*)g.Bt + S.boff(nxt) : cB;
.LBB0_698:
	s_add_i32 s23, s23, 1
	s_mul_i32 s2, s23, s75
	s_mul_hi_u32 s3, s23, s53
	s_add_i32 s3, s3, s2
	s_mul_i32 s2, s23, s53
	v_readlane_b32 s4, v255, 29
	s_add_u32 s2, s2, s4
	s_addc_u32 s3, s3, s78
	v_mov_b64_e32 v[2:3], 0x288
	v_cmp_lt_i64_e64 s[4:5], s[2:3], v[2:3]
	v_mov_b64_e32 v[2:3], 0x287
	v_cmp_gt_i64_e32 vcc, s[2:3], v[2:3]
	s_nop 3
	s_mov_b32 s101, s4
	s_cbranch_vccnz .LBB0_700
	s_ashr_i32 s3, s2, 31
	s_lshr_b32 s3, s3, 29
	s_add_i32 s3, s2, s3
	s_ashr_i32 s9, s3, 3
	s_and_b32 s3, s3, -8
	s_sub_i32 s2, s2, s3
	s_cmp_lt_i32 s2, 0
	s_movk_i32 s3, 0x52
	s_cselect_b32 s3, s3, 0x51
	s_mul_i32 s2, s2, s3
	s_add_i32 s2, s2, s9
	s_mul_hi_i32 s3, s2, 0x38e38e39
	s_lshr_b32 s9, s3, 31
	s_ashr_i32 s3, s3, 4
	s_add_i32 s3, s3, s9
	s_lshl_b32 s9, s3, 3
	s_sub_i32 s26, 0x48, s9
	s_min_i32 s27, s26, 8
	s_abs_i32 s26, s27
	v_cvt_f32_u32_e32 v0, s26
	s_sub_i32 s29, 0, s26
	s_mulk_i32 s3, 0x48
	s_sub_i32 s2, s2, s3
	v_rcp_iflag_f32_e32 v0, v0
	s_abs_i32 s3, s2
	s_xor_b32 s28, s2, s27
	s_ashr_i32 s28, s28, 31
	v_mul_f32_e32 v0, 0x4f7ffffe, v0
	v_cvt_u32_f32_e32 v0, v0
	s_nop 0
	v_readfirstlane_b32 s30, v0
	s_mul_i32 s29, s29, s30
	s_mul_hi_u32 s29, s30, s29
	s_add_i32 s30, s30, s29
	s_mul_hi_u32 s29, s3, s30
	s_mul_i32 s30, s29, s26
	s_sub_i32 s3, s3, s30
	s_add_i32 s31, s29, 1
	s_sub_i32 s30, s3, s26
	s_cmp_ge_u32 s3, s26
	s_cselect_b32 s29, s31, s29
	s_cselect_b32 s3, s30, s3
	s_add_i32 s30, s29, 1
	s_cmp_ge_u32 s3, s26
	s_cselect_b32 s3, s30, s29
	s_xor_b32 s3, s3, s28
	s_sub_i32 s26, s3, s28
	s_mul_i32 s3, s26, s27
	s_sub_i32 s2, s2, s3
	s_add_i32 s28, s9, s2

; #define PG8_STAGE(bufoff, gbase, voff) do { _Pragma("unroll") for (int _i = 0; _i < 2; ++_i) \
;         __builtin_amdgcn_global_load_lds((const unsigned*)((const char*)(gbase) + (voff)[_i]), (LAS unsigned*)(lds + (bufoff) + ldsw + _i * 8192), 16, 0, 0); } while (0)
; #define PG8_LDA(dst, b, h) do { _Pragma("unroll") for (int m = 0; m < NM; ++m) _Pragma("unroll") for (int k = 0; k < 2; ++k) dst[m][k] = *(const LAS bf16x8*)(lds + PG8_SA(b, h) + aoff + m * 2048 + k * 1024); } while (0)
; #define PG8_LDB(dst, b, h) do { _Pragma("unroll") for (int n = 0; n < 2; ++n) _Pragma("unroll") for (int k = 0; k < 2; ++k) dst[n][k] = *(const LAS bf16x8*)(lds + PG8_SB(b, h) + boff + n * 2048 + k * 1024); } while (0)
; #define PG8_MMA(ai, bj, At, Bt) do { __builtin_amdgcn_s_setprio(1); _Pragma("unroll") for (int m = 0; m < NM; ++m) _Pragma("unroll") for (int n = 0; n < 2; ++n) _Pragma("unroll") for (int k = 0; k < 2; ++k) \
;         acc[ai][bj][m][n] = __builtin_amdgcn_mfma_f32_16x16x32_bf16(Bt[n][k], At[m][k], acc[ai][bj][m][n], 0, 0, 0); __builtin_amdgcn_s_setprio(0); } while (0)
; #define PG8_WAIT_V(n) asm volatile("s_waitcnt vmcnt(" #n ")" ::: "memory")
; #define PG8_WAIT_L(n) asm volatile("s_waitcnt lgkmcnt(" #n ")" ::: "memory")
; #define PG8_BAR __builtin_amdgcn_s_barrier()
; #define PG8_SCHED __builtin_amdgcn_sched_barrier(0)
;     ...
;         for (int t = 0; t < nt; t += 2) {
;             const bool last = (t == nt - 2);
;             const char* a1 = cA + (size_t)(t + 1) * kstep;
;             const char* a2 = last ? nA : cA + (size_t)(t + 2) * kstep; const char* b2 = last ? nB : cB + (size_t)(t + 2) * kstep;
;             const char* a3 = a2 + kstep; const char* b3 = b2 + kstep;
;             if constexpr (SP2) {
;             PG8_LDB(B0, 0, 0); PG8_LDB(B1, 0, 1); PG8_SCHED; PG8_LDA(At, 0, 0); PG8_STAGE(PG8_SA(1, 1), a1 + hstepA, voffA);
;             PG8_WAIT_V(8); PG8_WAIT_L(0); PG8_BAR; PG8_MMA(0, 0, At, B0); PG8_MMA(0, 1, At, B1); PG8_BAR; PG8_SCHED;
;             PG8_LDA(At, 0, 1); PG8_STAGE(PG8_SB(0, 0), b2, voffB); PG8_STAGE(PG8_SB(0, 1), b2 + hstepB, voffB); PG8_STAGE(PG8_SA(0, 0), a2, voffA);
.LBB0_703:
	v_add_u32_e32 v0, s50, v146
	ds_read_b128 v[138:141], v0
	ds_read_b128 v[142:145], v0 offset:1024
	ds_read_b128 v[148:151], v0 offset:2048
	ds_read_b128 v[152:155], v0 offset:3072
	v_add_u32_e32 v0, s54, v146
	ds_read_b128 v[156:159], v0
	ds_read_b128 v[160:163], v0 offset:1024
	ds_read_b128 v[164:167], v0 offset:2048
	ds_read_b128 v[168:171], v0 offset:3072
	s_add_u32 s12, s10, 0xfff80080
	s_addc_u32 s13, s11, -1
	s_cmp_eq_u32 s39, 28
	s_cselect_b32 s37, s2, s13
	s_cselect_b32 s36, s3, s12
	s_cselect_b32 s13, s9, s38
	s_cselect_b32 s12, s27, s29
	s_cselect_b32 s100, -1, 0
	s_andn2_b32 s100, s100, s101
	s_add_i32 m0, s58, 0xc000
	ds_read_b128 v[172:175], v147
	ds_read_b128 v[176:179], v147 offset:1024
	ds_read_b128 v[180:183], v147 offset:2048
	ds_read_b128 v[184:187], v147 offset:3072
	ds_read_b128 v[188:191], v147 offset:4096
	ds_read_b128 v[192:195], v147 offset:5120
	ds_read_b128 v[196:199], v147 offset:6144
	ds_read_b128 v[200:203], v147 offset:7168
	global_load_lds_dwordx4 v134, s[10:11]
	s_add_i32 m0, s58, 0xe000
	s_nop 0
	global_load_lds_dwordx4 v136, s[10:11]
	s_waitcnt vmcnt(8)
	s_waitcnt lgkmcnt(0)
	s_barrier
	s_setprio 1
	s_waitcnt lgkmcnt(0)
	v_mfma_f32_16x16x32_bf16 v[126:129], v[138:141], v[172:175], v[126:129]
	v_mfma_f32_16x16x32_bf16 v[122:125], v[148:151], v[172:175], v[122:125]
	v_mfma_f32_16x16x32_bf16 v[110:113], v[138:141], v[180:183], v[110:113]
	v_mfma_f32_16x16x32_bf16 v[106:109], v[148:151], v[180:183], v[106:109]
	v_mfma_f32_16x16x32_bf16 v[94:97], v[138:141], v[188:191], v[94:97]
	v_mfma_f32_16x16x32_bf16 v[90:93], v[148:151], v[188:191], v[90:93]
	v_mfma_f32_16x16x32_bf16 v[78:81], v[138:141], v[196:199], v[78:81]
	v_mfma_f32_16x16x32_bf16 v[74:77], v[148:151], v[196:199], v[74:77]
	v_mfma_f32_16x16x32_bf16 v[126:129], v[142:145], v[176:179], v[126:129]
	v_mfma_f32_16x16x32_bf16 v[122:125], v[152:155], v[176:179], v[122:125]
	v_mfma_f32_16x16x32_bf16 v[110:113], v[142:145], v[184:187], v[110:113]
	v_mfma_f32_16x16x32_bf16 v[106:109], v[152:155], v[184:187], v[106:109]
	v_mfma_f32_16x16x32_bf16 v[94:97], v[142:145], v[192:195], v[94:97]
	v_mfma_f32_16x16x32_bf16 v[90:93], v[152:155], v[192:195], v[90:93]
	v_mfma_f32_16x16x32_bf16 v[78:81], v[142:145], v[200:203], v[78:81]
	v_mfma_f32_16x16x32_bf16 v[74:77], v[152:155], v[200:203], v[74:77]
	s_setprio 0
	s_setprio 1
	v_mfma_f32_16x16x32_bf16 v[118:121], v[156:159], v[172:175], v[118:121]
	v_mfma_f32_16x16x32_bf16 v[114:117], v[164:167], v[172:175], v[114:117]
	v_mfma_f32_16x16x32_bf16 v[102:105], v[156:159], v[180:183], v[102:105]
	v_mfma_f32_16x16x32_bf16 v[98:101], v[164:167], v[180:183], v[98:101]
	v_mfma_f32_16x16x32_bf16 v[86:89], v[156:159], v[188:191], v[86:89]
	v_mfma_f32_16x16x32_bf16 v[82:85], v[164:167], v[188:191], v[82:85]
	v_mfma_f32_16x16x32_bf16 v[70:73], v[156:159], v[196:199], v[70:73]
	v_mfma_f32_16x16x32_bf16 v[66:69], v[164:167], v[196:199], v[66:69]
	v_mfma_f32_16x16x32_bf16 v[118:121], v[160:163], v[176:179], v[118:121]
	v_mfma_f32_16x16x32_bf16 v[114:117], v[168:171], v[176:179], v[114:117]
	v_mfma_f32_16x16x32_bf16 v[102:105], v[160:163], v[184:187], v[102:105]
	v_mfma_f32_16x16x32_bf16 v[98:101], v[168:171], v[184:187], v[98:101]
	v_mfma_f32_16x16x32_bf16 v[86:89], v[160:163], v[192:195], v[86:89]
	v_mfma_f32_16x16x32_bf16 v[82:85], v[168:171], v[192:195], v[82:85]
	v_mfma_f32_16x16x32_bf16 v[70:73], v[160:163], v[200:203], v[70:73]
	v_mfma_f32_16x16x32_bf16 v[66:69], v[168:171], v[200:203], v[66:69]
	s_setprio 0
	s_barrier
	s_mov_b32 m0, s51
	v_lshl_add_u64 v[204:205], s[12:13], 0, v[130:131]
	s_add_u32 s40, s12, 0x80000
	s_addc_u32 s41, s13, 0
	ds_read_b128 v[172:175], v147 offset:16384
	ds_read_b128 v[176:179], v147 offset:17408
	ds_read_b128 v[180:183], v147 offset:18432
	ds_read_b128 v[184:187], v147 offset:19456
	ds_read_b128 v[188:191], v147 offset:20480
	ds_read_b128 v[192:195], v147 offset:21504
	ds_read_b128 v[196:199], v147 offset:22528
	ds_read_b128 v[200:203], v147 offset:23552
	s_cmp_lg_u32 s100, 0
	s_cbranch_scc1 .Ltl_ia_0s
	global_load_lds_dwordx4 v130, s[12:13]
	v_lshl_add_u64 v[206:207], s[12:13], 0, v[132:133]
	s_mov_b32 m0, s52
	s_nop 0
	global_load_lds_dwordx4 v132, s[12:13]
	s_mov_b32 m0, s56
	v_lshl_add_u64 v[210:211], s[36:37], 0, v[132:133]
	global_load_lds_dwordx4 v130, s[40:41]
	s_mov_b32 m0, s57
	s_nop 0
	global_load_lds_dwordx4 v132, s[40:41]
	v_lshl_add_u64 v[208:209], s[36:37], 0, v[130:131]
	s_mov_b32 m0, s58
	s_nop 0
	global_load_lds_dwordx4 v130, s[36:37]
	s_mov_b32 m0, s59
	s_nop 0
	global_load_lds_dwordx4 v132, s[36:37]
	s_waitcnt vmcnt(8)
	s_branch .Ltl_ia_0d

; #define PG8_STAGE(bufoff, gbase, voff) do { _Pragma("unroll") for (int _i = 0; _i < 2; ++_i) \
;         __builtin_amdgcn_global_load_lds((const unsigned*)((const char*)(gbase) + (voff)[_i]), (LAS unsigned*)(lds + (bufoff) + ldsw + _i * 8192), 16, 0, 0); } while (0)
; #define PG8_LDA(dst, b, h) do { _Pragma("unroll") for (int m = 0; m < NM; ++m) _Pragma("unroll") for (int k = 0; k < 2; ++k) dst[m][k] = *(const LAS bf16x8*)(lds + PG8_SA(b, h) + aoff + m * 2048 + k * 1024); } while (0)
; #define PG8_LDB(dst, b, h) do { _Pragma("unroll") for (int n = 0; n < 2; ++n) _Pragma("unroll") for (int k = 0; k < 2; ++k) dst[n][k] = *(const LAS bf16x8*)(lds + PG8_SB(b, h) + boff + n * 2048 + k * 1024); } while (0)
; #define PG8_MMA(ai, bj, At, Bt) do { __builtin_amdgcn_s_setprio(1); _Pragma("unroll") for (int m = 0; m < NM; ++m) _Pragma("unroll") for (int n = 0; n < 2; ++n) _Pragma("unroll") for (int k = 0; k < 2; ++k) \
;         acc[ai][bj][m][n] = __builtin_amdgcn_mfma_f32_16x16x32_bf16(Bt[n][k], At[m][k], acc[ai][bj][m][n], 0, 0, 0); __builtin_amdgcn_s_setprio(0); } while (0)
; #define PG8_WAIT_V(n) asm volatile("s_waitcnt vmcnt(" #n ")" ::: "memory")
; #define PG8_WAIT_L(n) asm volatile("s_waitcnt lgkmcnt(" #n ")" ::: "memory")
; #define PG8_BAR __builtin_amdgcn_s_barrier()
; #define PG8_SCHED __builtin_amdgcn_sched_barrier(0)
;     ...
;             PG8_LDA(At, 0, 1); PG8_STAGE(PG8_SB(0, 0), b2, voffB); PG8_STAGE(PG8_SB(0, 1), b2 + hstepB, voffB); PG8_STAGE(PG8_SA(0, 0), a2, voffA);
;             PG8_WAIT_V(8); PG8_WAIT_L(0); PG8_BAR; PG8_MMA(1, 0, At, B0); PG8_MMA(1, 1, At, B1); PG8_BAR; PG8_SCHED;
;             PG8_LDB(B0, 1, 0); PG8_LDB(B1, 1, 1); PG8_SCHED; PG8_LDA(At, 1, 0); PG8_STAGE(PG8_SA(0, 1), a2 + hstepA, voffA);
.Ltl_ia_0d:
	s_waitcnt lgkmcnt(0)
	s_barrier
	s_setprio 1
	s_waitcnt lgkmcnt(0)
	v_mfma_f32_16x16x32_bf16 v[62:65], v[138:141], v[172:175], v[62:65]
	v_mfma_f32_16x16x32_bf16 v[58:61], v[148:151], v[172:175], v[58:61]
	v_mfma_f32_16x16x32_bf16 v[46:49], v[138:141], v[180:183], v[46:49]
	v_mfma_f32_16x16x32_bf16 v[42:45], v[148:151], v[180:183], v[42:45]
	v_mfma_f32_16x16x32_bf16 v[30:33], v[138:141], v[188:191], v[30:33]
	v_mfma_f32_16x16x32_bf16 v[26:29], v[148:151], v[188:191], v[26:29]
	v_mfma_f32_16x16x32_bf16 v[14:17], v[138:141], v[196:199], v[14:17]
	v_mfma_f32_16x16x32_bf16 v[10:13], v[148:151], v[196:199], v[10:13]
	v_mfma_f32_16x16x32_bf16 v[62:65], v[142:145], v[176:179], v[62:65]
	v_mfma_f32_16x16x32_bf16 v[58:61], v[152:155], v[176:179], v[58:61]
	v_mfma_f32_16x16x32_bf16 v[46:49], v[142:145], v[184:187], v[46:49]
	v_mfma_f32_16x16x32_bf16 v[42:45], v[152:155], v[184:187], v[42:45]
	v_mfma_f32_16x16x32_bf16 v[30:33], v[142:145], v[192:195], v[30:33]
	v_mfma_f32_16x16x32_bf16 v[26:29], v[152:155], v[192:195], v[26:29]
	v_mfma_f32_16x16x32_bf16 v[14:17], v[142:145], v[200:203], v[14:17]
	v_mfma_f32_16x16x32_bf16 v[10:13], v[152:155], v[200:203], v[10:13]
	s_setprio 0
	s_setprio 1
	v_mfma_f32_16x16x32_bf16 v[54:57], v[156:159], v[172:175], v[54:57]
	v_mfma_f32_16x16x32_bf16 v[50:53], v[164:167], v[172:175], v[50:53]
	v_mfma_f32_16x16x32_bf16 v[38:41], v[156:159], v[180:183], v[38:41]
	v_mfma_f32_16x16x32_bf16 v[34:37], v[164:167], v[180:183], v[34:37]
	v_mfma_f32_16x16x32_bf16 v[22:25], v[156:159], v[188:191], v[22:25]
	v_mfma_f32_16x16x32_bf16 v[18:21], v[164:167], v[188:191], v[18:21]
	v_mfma_f32_16x16x32_bf16 v[6:9], v[156:159], v[196:199], v[6:9]
	v_mfma_f32_16x16x32_bf16 v[2:5], v[164:167], v[196:199], v[2:5]
	v_mfma_f32_16x16x32_bf16 v[54:57], v[160:163], v[176:179], v[54:57]
	v_mfma_f32_16x16x32_bf16 v[50:53], v[168:171], v[176:179], v[50:53]
	v_mfma_f32_16x16x32_bf16 v[38:41], v[160:163], v[184:187], v[38:41]
	v_mfma_f32_16x16x32_bf16 v[34:37], v[168:171], v[184:187], v[34:37]
	v_mfma_f32_16x16x32_bf16 v[22:25], v[160:163], v[192:195], v[22:25]
	v_mfma_f32_16x16x32_bf16 v[18:21], v[168:171], v[192:195], v[18:21]
	v_mfma_f32_16x16x32_bf16 v[6:9], v[160:163], v[200:203], v[6:9]
	v_mfma_f32_16x16x32_bf16 v[2:5], v[168:171], v[200:203], v[2:5]
	s_setprio 0
	s_barrier
	v_add_u32_e32 v0, s64, v146
	ds_read_b128 v[138:141], v0
	ds_read_b128 v[142:145], v0 offset:1024
	ds_read_b128 v[148:151], v0 offset:2048
	ds_read_b128 v[152:155], v0 offset:3072
	v_add_u32_e32 v0, s71, v146
	ds_read_b128 v[156:159], v0
	ds_read_b128 v[160:163], v0 offset:1024
	ds_read_b128 v[164:167], v0 offset:2048
	ds_read_b128 v[168:171], v0 offset:3072
	s_add_u32 s36, s36, 0x80000
	s_addc_u32 s37, s37, 0
	s_mov_b32 m0, s62
	ds_read_b128 v[172:175], v147 offset:32768
	ds_read_b128 v[176:179], v147 offset:33792
	ds_read_b128 v[180:183], v147 offset:34816
	ds_read_b128 v[184:187], v147 offset:35840
	ds_read_b128 v[188:191], v147 offset:36864
	ds_read_b128 v[192:195], v147 offset:37888
	ds_read_b128 v[196:199], v147 offset:38912
	ds_read_b128 v[200:203], v147 offset:39936
	s_cmp_lg_u32 s100, 0
	s_cbranch_scc1 .Ltl_ia_1s
	global_load_lds_dwordx4 v130, s[36:37]
	s_mov_b32 m0, s63
	s_nop 0
	global_load_lds_dwordx4 v132, s[36:37]
	s_waitcnt vmcnt(8)
	s_branch .Ltl_ia_1d

; #define PG8_STAGE(bufoff, gbase, voff) do { _Pragma("unroll") for (int _i = 0; _i < 2; ++_i) \
;         __builtin_amdgcn_global_load_lds((const unsigned*)((const char*)(gbase) + (voff)[_i]), (LAS unsigned*)(lds + (bufoff) + ldsw + _i * 8192), 16, 0, 0); } while (0)
; #define PG8_LDA(dst, b, h) do { _Pragma("unroll") for (int m = 0; m < NM; ++m) _Pragma("unroll") for (int k = 0; k < 2; ++k) dst[m][k] = *(const LAS bf16x8*)(lds + PG8_SA(b, h) + aoff + m * 2048 + k * 1024); } while (0)
; #define PG8_LDB(dst, b, h) do { _Pragma("unroll") for (int n = 0; n < 2; ++n) _Pragma("unroll") for (int k = 0; k < 2; ++k) dst[n][k] = *(const LAS bf16x8*)(lds + PG8_SB(b, h) + boff + n * 2048 + k * 1024); } while (0)
; #define PG8_MMA(ai, bj, At, Bt) do { __builtin_amdgcn_s_setprio(1); _Pragma("unroll") for (int m = 0; m < NM; ++m) _Pragma("unroll") for (int n = 0; n < 2; ++n) _Pragma("unroll") for (int k = 0; k < 2; ++k) \
;         acc[ai][bj][m][n] = __builtin_amdgcn_mfma_f32_16x16x32_bf16(Bt[n][k], At[m][k], acc[ai][bj][m][n], 0, 0, 0); __builtin_amdgcn_s_setprio(0); } while (0)
; #define PG8_WAIT_V(n) asm volatile("s_waitcnt vmcnt(" #n ")" ::: "memory")
; #define PG8_WAIT_L(n) asm volatile("s_waitcnt lgkmcnt(" #n ")" ::: "memory")
; #define PG8_BAR __builtin_amdgcn_s_barrier()
; #define PG8_SCHED __builtin_amdgcn_sched_barrier(0)
;     ...
;             PG8_LDB(B0, 1, 0); PG8_LDB(B1, 1, 1); PG8_SCHED; PG8_LDA(At, 1, 0); PG8_STAGE(PG8_SA(0, 1), a2 + hstepA, voffA);
;             PG8_WAIT_V(8); PG8_WAIT_L(0); PG8_BAR; PG8_MMA(0, 0, At, B0); PG8_MMA(0, 1, At, B1); PG8_BAR; PG8_SCHED;
;             PG8_LDA(At, 1, 1); PG8_STAGE(PG8_SB(1, 0), b3, voffB); PG8_STAGE(PG8_SB(1, 1), b3 + hstepB, voffB); PG8_STAGE(PG8_SA(1, 0), a3, voffA);
.Ltl_ia_1d:
	s_waitcnt lgkmcnt(0)
	s_barrier
	s_setprio 1
	s_waitcnt lgkmcnt(0)
	v_mfma_f32_16x16x32_bf16 v[126:129], v[138:141], v[172:175], v[126:129]
	v_mfma_f32_16x16x32_bf16 v[122:125], v[148:151], v[172:175], v[122:125]
	v_mfma_f32_16x16x32_bf16 v[110:113], v[138:141], v[180:183], v[110:113]
	v_mfma_f32_16x16x32_bf16 v[106:109], v[148:151], v[180:183], v[106:109]
	v_mfma_f32_16x16x32_bf16 v[94:97], v[138:141], v[188:191], v[94:97]
	v_mfma_f32_16x16x32_bf16 v[90:93], v[148:151], v[188:191], v[90:93]
	v_mfma_f32_16x16x32_bf16 v[78:81], v[138:141], v[196:199], v[78:81]
	v_mfma_f32_16x16x32_bf16 v[74:77], v[148:151], v[196:199], v[74:77]
	v_mfma_f32_16x16x32_bf16 v[126:129], v[142:145], v[176:179], v[126:129]
	v_mfma_f32_16x16x32_bf16 v[122:125], v[152:155], v[176:179], v[122:125]
	v_mfma_f32_16x16x32_bf16 v[110:113], v[142:145], v[184:187], v[110:113]
	v_mfma_f32_16x16x32_bf16 v[106:109], v[152:155], v[184:187], v[106:109]
	v_mfma_f32_16x16x32_bf16 v[94:97], v[142:145], v[192:195], v[94:97]
	v_mfma_f32_16x16x32_bf16 v[90:93], v[152:155], v[192:195], v[90:93]
	v_mfma_f32_16x16x32_bf16 v[78:81], v[142:145], v[200:203], v[78:81]
	v_mfma_f32_16x16x32_bf16 v[74:77], v[152:155], v[200:203], v[74:77]
	s_setprio 0
	s_setprio 1
	v_mfma_f32_16x16x32_bf16 v[118:121], v[156:159], v[172:175], v[118:121]
	v_mfma_f32_16x16x32_bf16 v[114:117], v[164:167], v[172:175], v[114:117]
	v_mfma_f32_16x16x32_bf16 v[102:105], v[156:159], v[180:183], v[102:105]
	v_mfma_f32_16x16x32_bf16 v[98:101], v[164:167], v[180:183], v[98:101]
	v_mfma_f32_16x16x32_bf16 v[86:89], v[156:159], v[188:191], v[86:89]
	v_mfma_f32_16x16x32_bf16 v[82:85], v[164:167], v[188:191], v[82:85]
	v_mfma_f32_16x16x32_bf16 v[70:73], v[156:159], v[196:199], v[70:73]
	v_mfma_f32_16x16x32_bf16 v[66:69], v[164:167], v[196:199], v[66:69]
	v_mfma_f32_16x16x32_bf16 v[118:121], v[160:163], v[176:179], v[118:121]
	v_mfma_f32_16x16x32_bf16 v[114:117], v[168:171], v[176:179], v[114:117]
	v_mfma_f32_16x16x32_bf16 v[102:105], v[160:163], v[184:187], v[102:105]
	v_mfma_f32_16x16x32_bf16 v[98:101], v[168:171], v[184:187], v[98:101]
	v_mfma_f32_16x16x32_bf16 v[86:89], v[160:163], v[192:195], v[86:89]
	v_mfma_f32_16x16x32_bf16 v[82:85], v[168:171], v[192:195], v[82:85]
	v_mfma_f32_16x16x32_bf16 v[70:73], v[160:163], v[200:203], v[70:73]
	v_mfma_f32_16x16x32_bf16 v[66:69], v[168:171], v[200:203], v[66:69]
	s_setprio 0
	s_barrier
	s_mov_b32 m0, s65
	v_lshl_add_u64 v[204:205], v[204:205], 0, s[66:67]
	s_add_u32 s12, s12, 0x80080
	s_addc_u32 s13, s13, 0
	ds_read_b128 v[172:175], v147 offset:49152
	ds_read_b128 v[176:179], v147 offset:50176
	ds_read_b128 v[180:183], v147 offset:51200
	ds_read_b128 v[184:187], v147 offset:52224
	ds_read_b128 v[188:191], v147 offset:53248
	ds_read_b128 v[192:195], v147 offset:54272
	ds_read_b128 v[196:199], v147 offset:55296
	ds_read_b128 v[200:203], v147 offset:56320
	s_cmp_lg_u32 s100, 0
	s_cbranch_scc1 .Ltl_ia_2s
	global_load_lds_dwordx4 v[204:205], off
	v_lshl_add_u64 v[204:205], v[206:207], 0, s[66:67]
	s_mov_b32 m0, s68
	s_nop 0
	global_load_lds_dwordx4 v[204:205], off
	s_mov_b32 m0, s72
	s_nop 0
	global_load_lds_dwordx4 v130, s[12:13]
	s_mov_b32 m0, s73
	s_nop 0
	global_load_lds_dwordx4 v132, s[12:13]
	v_lshl_add_u64 v[204:205], v[208:209], 0, s[66:67]
	s_mov_b32 m0, s69
	s_nop 0
	global_load_lds_dwordx4 v[204:205], off
	v_lshl_add_u64 v[204:205], v[210:211], 0, s[66:67]
	s_mov_b32 m0, s70
	s_nop 0
	global_load_lds_dwordx4 v[204:205], off
	s_waitcnt vmcnt(8)
	s_branch .Ltl_ia_2d

; #define PG8_STAGE(bufoff, gbase, voff) do { _Pragma("unroll") for (int _i = 0; _i < 2; ++_i) \
;         __builtin_amdgcn_global_load_lds((const unsigned*)((const char*)(gbase) + (voff)[_i]), (LAS unsigned*)(lds + (bufoff) + ldsw + _i * 8192), 16, 0, 0); } while (0)
; #define PG8_LDA(dst, b, h) do { _Pragma("unroll") for (int m = 0; m < NM; ++m) _Pragma("unroll") for (int k = 0; k < 2; ++k) dst[m][k] = *(const LAS bf16x8*)(lds + PG8_SA(b, h) + aoff + m * 2048 + k * 1024); } while (0)
; #define PG8_MMA(ai, bj, At, Bt) do { __builtin_amdgcn_s_setprio(1); _Pragma("unroll") for (int m = 0; m < NM; ++m) _Pragma("unroll") for (int n = 0; n < 2; ++n) _Pragma("unroll") for (int k = 0; k < 2; ++k) \
;         acc[ai][bj][m][n] = __builtin_amdgcn_mfma_f32_16x16x32_bf16(Bt[n][k], At[m][k], acc[ai][bj][m][n], 0, 0, 0); __builtin_amdgcn_s_setprio(0); } while (0)
; #define PG8_WAIT_V(n) asm volatile("s_waitcnt vmcnt(" #n ")" ::: "memory")
; #define PG8_WAIT_L(n) asm volatile("s_waitcnt lgkmcnt(" #n ")" ::: "memory")
; #define PG8_BAR __builtin_amdgcn_s_barrier()
; #define PG8_SCHED __builtin_amdgcn_sched_barrier(0)
;     ...
;             PG8_WAIT_V(8); PG8_WAIT_L(0); PG8_BAR; PG8_MMA(0, 0, At, B0); PG8_MMA(0, 1, At, B1); PG8_BAR; PG8_SCHED;
;             PG8_LDA(At, 1, 1); PG8_STAGE(PG8_SB(1, 0), b3, voffB); PG8_STAGE(PG8_SB(1, 1), b3 + hstepB, voffB); PG8_STAGE(PG8_SA(1, 0), a3, voffA);
;             PG8_WAIT_V(8); PG8_WAIT_L(0); PG8_BAR; PG8_MMA(1, 0, At, B0); PG8_MMA(1, 1, At, B1); PG8_BAR; PG8_SCHED;
;     ...
;         if constexpr (ALIGN_EPI) { if (wr == 0) PG8_BAR; }
.Ltl_ia_2d:
	s_waitcnt lgkmcnt(0)
	s_barrier
	s_setprio 1
	s_waitcnt lgkmcnt(0)
	v_mfma_f32_16x16x32_bf16 v[62:65], v[138:141], v[172:175], v[62:65]
	v_mfma_f32_16x16x32_bf16 v[58:61], v[148:151], v[172:175], v[58:61]
	v_mfma_f32_16x16x32_bf16 v[46:49], v[138:141], v[180:183], v[46:49]
	v_mfma_f32_16x16x32_bf16 v[42:45], v[148:151], v[180:183], v[42:45]
	v_mfma_f32_16x16x32_bf16 v[30:33], v[138:141], v[188:191], v[30:33]
	v_mfma_f32_16x16x32_bf16 v[26:29], v[148:151], v[188:191], v[26:29]
	v_mfma_f32_16x16x32_bf16 v[14:17], v[138:141], v[196:199], v[14:17]
	v_mfma_f32_16x16x32_bf16 v[10:13], v[148:151], v[196:199], v[10:13]
	v_mfma_f32_16x16x32_bf16 v[62:65], v[142:145], v[176:179], v[62:65]
	v_mfma_f32_16x16x32_bf16 v[58:61], v[152:155], v[176:179], v[58:61]
	v_mfma_f32_16x16x32_bf16 v[46:49], v[142:145], v[184:187], v[46:49]
	v_mfma_f32_16x16x32_bf16 v[42:45], v[152:155], v[184:187], v[42:45]
	v_mfma_f32_16x16x32_bf16 v[30:33], v[142:145], v[192:195], v[30:33]
	v_mfma_f32_16x16x32_bf16 v[26:29], v[152:155], v[192:195], v[26:29]
	v_mfma_f32_16x16x32_bf16 v[14:17], v[142:145], v[200:203], v[14:17]
	v_mfma_f32_16x16x32_bf16 v[10:13], v[152:155], v[200:203], v[10:13]
	s_setprio 0
	s_setprio 1
	v_mfma_f32_16x16x32_bf16 v[54:57], v[156:159], v[172:175], v[54:57]
	v_mfma_f32_16x16x32_bf16 v[50:53], v[164:167], v[172:175], v[50:53]
	v_mfma_f32_16x16x32_bf16 v[38:41], v[156:159], v[180:183], v[38:41]
	v_mfma_f32_16x16x32_bf16 v[34:37], v[164:167], v[180:183], v[34:37]
	v_mfma_f32_16x16x32_bf16 v[22:25], v[156:159], v[188:191], v[22:25]
	v_mfma_f32_16x16x32_bf16 v[18:21], v[164:167], v[188:191], v[18:21]
	v_mfma_f32_16x16x32_bf16 v[6:9], v[156:159], v[196:199], v[6:9]
	v_mfma_f32_16x16x32_bf16 v[2:5], v[164:167], v[196:199], v[2:5]
	v_mfma_f32_16x16x32_bf16 v[54:57], v[160:163], v[176:179], v[54:57]
	v_mfma_f32_16x16x32_bf16 v[50:53], v[168:171], v[176:179], v[50:53]
	v_mfma_f32_16x16x32_bf16 v[38:41], v[160:163], v[184:187], v[38:41]
	v_mfma_f32_16x16x32_bf16 v[34:37], v[168:171], v[184:187], v[34:37]
	v_mfma_f32_16x16x32_bf16 v[22:25], v[160:163], v[192:195], v[22:25]
	v_mfma_f32_16x16x32_bf16 v[18:21], v[168:171], v[192:195], v[18:21]
	v_mfma_f32_16x16x32_bf16 v[6:9], v[160:163], v[200:203], v[6:9]
	v_mfma_f32_16x16x32_bf16 v[2:5], v[168:171], v[200:203], v[2:5]
	s_setprio 0
	s_barrier
	s_add_i32 s39, s39, 2
	s_add_u32 s10, s10, 0x100
	s_addc_u32 s11, s11, 0
	s_add_u32 s29, s29, 0x100
	s_addc_u32 s38, s38, 0
	s_cmp_gt_u32 s39, 29
	s_cbranch_scc0 .LBB0_703
	s_and_b64 vcc, exec, s[18:19]
	s_cbranch_vccz .LBB0_706
	s_barrier

;     __device__ __forceinline__ size_t aoff(const Unit& u) const { return (size_t)u.pm * bm * lda * 2; }
;     __device__ __forceinline__ size_t boff(const Unit& u) const { return (size_t)u.pn * BM * ldb * 2; }
;     __device__ __forceinline__ size_t aoff(const Unit& u) const { return ((size_t)u.pm * BM * lda + (size_t)u.pn * akoff) * 2; }
;     __device__ __forceinline__ size_t boff(const Unit& u) const { return (size_t)u.pn * BM * ldb * 2; }
;     __device__ __forceinline__ size_t aoff(const Unit& u) const { return ((size_t)u.pm * BM * lda + (size_t)(u.pn >> 1) * akoff) * 2; }
;     __device__ __forceinline__ size_t boff(const Unit& u) const { return (size_t)u.pn * BM * ldb * 2; }
;     __device__ bool next(int i, Unit& u) const {
;         const long L = (long)i * G + c; if (L >= nwg) return false;
;         int wgid = (int)L; { const int q = nwg / NXCD, r = nwg % NXCD, xcd = wgid % NXCD, off = wgid / NXCD; wgid = (xcd < r ? xcd * (q + 1) : r * (q + 1) + (xcd - r) * q) + off; }
;         const int nig = WGM * nN, gid = wgid / nig, fm = gid * WGM, gsz = (nM - fm) < WGM ? (nM - fm) : WGM;
;         u.pm = fm + ((wgid % nig) % gsz); u.pn = (wgid % nig) / gsz; return true;
;     }
;     ...
;         const bool has_next = S.next(ui + 1, nxt);
;         const char* nA = has_next ? (const char*)g.A + S.aoff(nxt) : cA; const char* nB = has_next ? (const char*)g.Bt + S.boff(nxt) : cB;
.LBB0_1189:
	s_add_i32 s47, s47, 1
	s_mul_i32 s2, s47, s92
	s_mul_hi_u32 s3, s47, s53
	s_add_i32 s3, s3, s2
	s_mul_i32 s2, s47, s53
	v_readlane_b32 s4, v255, 29
	s_add_u32 s2, s2, s4
	s_addc_u32 s3, s3, s93
	v_mov_b64_e32 v[2:3], 0x1b0
	v_cmp_lt_i64_e64 s[4:5], s[2:3], v[2:3]
	v_mov_b64_e32 v[2:3], 0x1af
	v_cmp_gt_i64_e32 vcc, s[2:3], v[2:3]
	s_nop 3
	s_mov_b32 s101, s4
	s_cbranch_vccnz .LBB0_1191
	s_ashr_i32 s3, s2, 31
	s_lshr_b32 s3, s3, 29
	s_add_i32 s3, s2, s3
	s_ashr_i32 s7, s3, 3
	s_and_b32 s3, s3, -8
	s_sub_i32 s2, s2, s3
	s_cmp_lt_i32 s2, 0
	s_cselect_b32 s3, 55, 54
	s_mul_i32 s2, s2, s3
	s_add_i32 s2, s2, s7
	s_mul_hi_i32 s3, s2, 0x2aaaaaab
	s_lshr_b32 s7, s3, 31
	s_ashr_i32 s3, s3, 3
	s_add_i32 s3, s3, s7
	s_lshl_b32 s7, s3, 3
	s_sub_i32 s9, 0x48, s7
	s_min_i32 s9, s9, 8
	s_abs_i32 s24, s9
	v_cvt_f32_u32_e32 v0, s24
	s_sub_i32 s26, 0, s24
	s_mul_i32 s3, s3, 48
	s_sub_i32 s2, s2, s3
	v_rcp_iflag_f32_e32 v0, v0
	s_abs_i32 s3, s2
	s_xor_b32 s25, s2, s9
	s_ashr_i32 s25, s25, 31
	v_mul_f32_e32 v0, 0x4f7ffffe, v0
	v_cvt_u32_f32_e32 v0, v0
	s_nop 0
	v_readfirstlane_b32 s27, v0
	s_mul_i32 s26, s26, s27
	s_mul_hi_u32 s26, s27, s26
	s_add_i32 s27, s27, s26
	s_mul_hi_u32 s26, s3, s27
	s_mul_i32 s27, s26, s24
	s_sub_i32 s3, s3, s27
	s_add_i32 s28, s26, 1
	s_sub_i32 s27, s3, s24
	s_cmp_ge_u32 s3, s24
	s_cselect_b32 s26, s28, s26
	s_cselect_b32 s3, s27, s3
	s_add_i32 s27, s26, 1
	s_cmp_ge_u32 s3, s24
	s_cselect_b32 s3, s27, s26
	s_xor_b32 s3, s3, s25
	s_sub_i32 s24, s3, s25
	s_mul_i32 s3, s24, s9
	s_sub_i32 s2, s2, s3
	s_add_i32 s26, s7, s2

; #define PG8_STAGE(bufoff, gbase, voff) do { _Pragma("unroll") for (int _i = 0; _i < 2; ++_i) \
;         __builtin_amdgcn_global_load_lds((const unsigned*)((const char*)(gbase) + (voff)[_i]), (LAS unsigned*)(lds + (bufoff) + ldsw + _i * 8192), 16, 0, 0); } while (0)
; #define PG8_LDA(dst, b, h) do { _Pragma("unroll") for (int m = 0; m < NM; ++m) _Pragma("unroll") for (int k = 0; k < 2; ++k) dst[m][k] = *(const LAS bf16x8*)(lds + PG8_SA(b, h) + aoff + m * 2048 + k * 1024); } while (0)
; #define PG8_LDB(dst, b, h) do { _Pragma("unroll") for (int n = 0; n < 2; ++n) _Pragma("unroll") for (int k = 0; k < 2; ++k) dst[n][k] = *(const LAS bf16x8*)(lds + PG8_SB(b, h) + boff + n * 2048 + k * 1024); } while (0)
; #define PG8_MMA(ai, bj, At, Bt) do { __builtin_amdgcn_s_setprio(1); _Pragma("unroll") for (int m = 0; m < NM; ++m) _Pragma("unroll") for (int n = 0; n < 2; ++n) _Pragma("unroll") for (int k = 0; k < 2; ++k) \
;         acc[ai][bj][m][n] = __builtin_amdgcn_mfma_f32_16x16x32_bf16(Bt[n][k], At[m][k], acc[ai][bj][m][n], 0, 0, 0); __builtin_amdgcn_s_setprio(0); } while (0)
; #define PG8_WAIT_V(n) asm volatile("s_waitcnt vmcnt(" #n ")" ::: "memory")
; #define PG8_WAIT_L(n) asm volatile("s_waitcnt lgkmcnt(" #n ")" ::: "memory")
; #define PG8_BAR __builtin_amdgcn_s_barrier()
; #define PG8_SCHED __builtin_amdgcn_sched_barrier(0)
;     ...
;         for (int t = 0; t < nt; t += 2) {
;             const bool last = (t == nt - 2);
;             const char* a1 = cA + (size_t)(t + 1) * kstep;
;             const char* a2 = last ? nA : cA + (size_t)(t + 2) * kstep; const char* b2 = last ? nB : cB + (size_t)(t + 2) * kstep;
;             const char* a3 = a2 + kstep; const char* b3 = b2 + kstep;
;             if constexpr (SP2) {
;             PG8_LDB(B0, 0, 0); PG8_LDB(B1, 0, 1); PG8_SCHED; PG8_LDA(At, 0, 0); PG8_STAGE(PG8_SA(1, 1), a1 + hstepA, voffA);
;             PG8_WAIT_V(8); PG8_WAIT_L(0); PG8_BAR; PG8_MMA(0, 0, At, B0); PG8_MMA(0, 1, At, B1); PG8_BAR; PG8_SCHED;
;             PG8_LDA(At, 0, 1); PG8_STAGE(PG8_SB(0, 0), b2, voffB); PG8_STAGE(PG8_SB(0, 1), b2 + hstepB, voffB); PG8_STAGE(PG8_SA(0, 0), a2, voffA);
.LBB0_1192:
	v_add_u32_e32 v0, s49, v216
	ds_read_b128 v[10:13], v0
	ds_read_b128 v[14:17], v0 offset:1024
	ds_read_b128 v[18:21], v0 offset:2048
	ds_read_b128 v[22:25], v0 offset:3072
	v_add_u32_e32 v0, s58, v216
	ds_read_b128 v[26:29], v0
	ds_read_b128 v[30:33], v0 offset:1024
	ds_read_b128 v[42:45], v0 offset:2048
	ds_read_b128 v[46:49], v0 offset:3072
	s_add_u32 s12, s10, 0xfffe0080
	s_addc_u32 s13, s11, -1
	s_cmp_eq_u32 s54, 4
	s_cselect_b32 s35, s2, s13
	s_cselect_b32 s34, s3, s12
	s_cselect_b32 s13, s7, s52
	s_cselect_b32 s12, s27, s9
	s_cselect_b32 s100, -1, 0
	s_andn2_b32 s100, s100, s101
	s_add_i32 m0, s62, 0xc000
	ds_read_b128 v[50:53], v217
	ds_read_b128 v[54:57], v217 offset:1024
	ds_read_b128 v[58:61], v217 offset:2048
	ds_read_b128 v[62:65], v217 offset:3072
	ds_read_b128 v[178:181], v217 offset:4096
	ds_read_b128 v[182:185], v217 offset:5120
	ds_read_b128 v[198:201], v217 offset:6144
	ds_read_b128 v[208:211], v217 offset:7168
	global_load_lds_dwordx4 v194, s[10:11]
	s_add_i32 m0, s62, 0xe000
	s_nop 0
	global_load_lds_dwordx4 v196, s[10:11]
	s_waitcnt vmcnt(8)
	s_waitcnt lgkmcnt(0)
	s_barrier
	s_setprio 1
	s_waitcnt lgkmcnt(0)
	v_mfma_f32_16x16x32_bf16 v[38:41], v[10:13], v[50:53], v[38:41]
	v_mfma_f32_16x16x32_bf16 v[34:37], v[18:21], v[50:53], v[34:37]
	v_mfma_f32_16x16x32_bf16 v[174:177], v[10:13], v[58:61], v[174:177]
	v_mfma_f32_16x16x32_bf16 v[170:173], v[18:21], v[58:61], v[170:173]
	v_mfma_f32_16x16x32_bf16 v[158:161], v[10:13], v[178:181], v[158:161]
	v_mfma_f32_16x16x32_bf16 v[154:157], v[18:21], v[178:181], v[154:157]
	v_mfma_f32_16x16x32_bf16 v[142:145], v[10:13], v[198:201], v[142:145]
	v_mfma_f32_16x16x32_bf16 v[138:141], v[18:21], v[198:201], v[138:141]
	v_mfma_f32_16x16x32_bf16 v[38:41], v[14:17], v[54:57], v[38:41]
	v_mfma_f32_16x16x32_bf16 v[34:37], v[22:25], v[54:57], v[34:37]
	v_mfma_f32_16x16x32_bf16 v[174:177], v[14:17], v[62:65], v[174:177]
	v_mfma_f32_16x16x32_bf16 v[170:173], v[22:25], v[62:65], v[170:173]
	v_mfma_f32_16x16x32_bf16 v[158:161], v[14:17], v[182:185], v[158:161]
	v_mfma_f32_16x16x32_bf16 v[154:157], v[22:25], v[182:185], v[154:157]
	v_mfma_f32_16x16x32_bf16 v[142:145], v[14:17], v[208:211], v[142:145]
	v_mfma_f32_16x16x32_bf16 v[138:141], v[22:25], v[208:211], v[138:141]
	s_setprio 0
	s_setprio 1
	v_mfma_f32_16x16x32_bf16 v[6:9], v[26:29], v[50:53], v[6:9]
	v_mfma_f32_16x16x32_bf16 v[2:5], v[42:45], v[50:53], v[2:5]
	v_mfma_f32_16x16x32_bf16 v[6:9], v[30:33], v[54:57], v[6:9]
	v_mfma_f32_16x16x32_bf16 v[2:5], v[46:49], v[54:57], v[2:5]
	v_mfma_f32_16x16x32_bf16 v[50:53], v[26:29], v[58:61], v[166:169]
	v_mfma_f32_16x16x32_bf16 v[54:57], v[42:45], v[58:61], v[162:165]
	v_mfma_f32_16x16x32_bf16 v[134:137], v[26:29], v[198:201], v[134:137]
	v_mfma_f32_16x16x32_bf16 v[130:133], v[42:45], v[198:201], v[130:133]
	v_mfma_f32_16x16x32_bf16 v[50:53], v[30:33], v[62:65], v[50:53]
	v_mfma_f32_16x16x32_bf16 v[54:57], v[46:49], v[62:65], v[54:57]
	v_mfma_f32_16x16x32_bf16 v[58:61], v[26:29], v[178:181], v[150:153]
	v_mfma_f32_16x16x32_bf16 v[62:65], v[42:45], v[178:181], v[146:149]
	v_mfma_f32_16x16x32_bf16 v[134:137], v[30:33], v[208:211], v[134:137]
	v_mfma_f32_16x16x32_bf16 v[130:133], v[46:49], v[208:211], v[130:133]
	v_mfma_f32_16x16x32_bf16 v[58:61], v[30:33], v[182:185], v[58:61]
	v_mfma_f32_16x16x32_bf16 v[62:65], v[46:49], v[182:185], v[62:65]
	s_setprio 0
	s_barrier
	s_mov_b32 m0, s50
	v_lshl_add_u64 v[202:203], s[12:13], 0, v[188:189]
	s_add_u32 s56, s12, 0x20000
	s_addc_u32 s57, s13, 0
	ds_read_b128 v[146:149], v217 offset:16384
	ds_read_b128 v[150:153], v217 offset:17408
	ds_read_b128 v[162:165], v217 offset:18432
	ds_read_b128 v[166:169], v217 offset:19456
	ds_read_b128 v[178:181], v217 offset:20480
	ds_read_b128 v[182:185], v217 offset:21504
	ds_read_b128 v[198:201], v217 offset:22528
	ds_read_b128 v[208:211], v217 offset:23552
	s_cmp_lg_u32 s100, 0
	s_cbranch_scc1 .Ltl_qp_0s
	global_load_lds_dwordx4 v188, s[12:13]
	v_lshl_add_u64 v[204:205], s[12:13], 0, v[192:193]
	s_mov_b32 m0, s51
	s_nop 0
	global_load_lds_dwordx4 v192, s[12:13]
	s_mov_b32 m0, s59
	v_lshl_add_u64 v[222:223], s[34:35], 0, v[190:191]
	global_load_lds_dwordx4 v188, s[56:57]
	s_mov_b32 m0, s60
	s_nop 0
	global_load_lds_dwordx4 v192, s[56:57]
	v_lshl_add_u64 v[206:207], s[34:35], 0, v[186:187]
	s_mov_b32 m0, s62
	s_nop 0
	global_load_lds_dwordx4 v186, s[34:35]
	s_mov_b32 m0, s63
	s_nop 0
	global_load_lds_dwordx4 v190, s[34:35]
	s_waitcnt vmcnt(8)
	s_branch .Ltl_qp_0d

; #define PG8_STAGE(bufoff, gbase, voff) do { _Pragma("unroll") for (int _i = 0; _i < 2; ++_i) \
;         __builtin_amdgcn_global_load_lds((const unsigned*)((const char*)(gbase) + (voff)[_i]), (LAS unsigned*)(lds + (bufoff) + ldsw + _i * 8192), 16, 0, 0); } while (0)
; #define PG8_LDA(dst, b, h) do { _Pragma("unroll") for (int m = 0; m < NM; ++m) _Pragma("unroll") for (int k = 0; k < 2; ++k) dst[m][k] = *(const LAS bf16x8*)(lds + PG8_SA(b, h) + aoff + m * 2048 + k * 1024); } while (0)
; #define PG8_LDB(dst, b, h) do { _Pragma("unroll") for (int n = 0; n < 2; ++n) _Pragma("unroll") for (int k = 0; k < 2; ++k) dst[n][k] = *(const LAS bf16x8*)(lds + PG8_SB(b, h) + boff + n * 2048 + k * 1024); } while (0)
; #define PG8_MMA(ai, bj, At, Bt) do { __builtin_amdgcn_s_setprio(1); _Pragma("unroll") for (int m = 0; m < NM; ++m) _Pragma("unroll") for (int n = 0; n < 2; ++n) _Pragma("unroll") for (int k = 0; k < 2; ++k) \
;         acc[ai][bj][m][n] = __builtin_amdgcn_mfma_f32_16x16x32_bf16(Bt[n][k], At[m][k], acc[ai][bj][m][n], 0, 0, 0); __builtin_amdgcn_s_setprio(0); } while (0)
; #define PG8_WAIT_V(n) asm volatile("s_waitcnt vmcnt(" #n ")" ::: "memory")
; #define PG8_WAIT_L(n) asm volatile("s_waitcnt lgkmcnt(" #n ")" ::: "memory")
; #define PG8_BAR __builtin_amdgcn_s_barrier()
; #define PG8_SCHED __builtin_amdgcn_sched_barrier(0)
;     ...
;             PG8_LDA(At, 0, 1); PG8_STAGE(PG8_SB(0, 0), b2, voffB); PG8_STAGE(PG8_SB(0, 1), b2 + hstepB, voffB); PG8_STAGE(PG8_SA(0, 0), a2, voffA);
;             PG8_WAIT_V(8); PG8_WAIT_L(0); PG8_BAR; PG8_MMA(1, 0, At, B0); PG8_MMA(1, 1, At, B1); PG8_BAR; PG8_SCHED;
;             PG8_LDB(B0, 1, 0); PG8_LDB(B1, 1, 1); PG8_SCHED; PG8_LDA(At, 1, 0); PG8_STAGE(PG8_SA(0, 1), a2 + hstepA, voffA);
.Ltl_qp_0d:
	s_waitcnt lgkmcnt(0)
	s_barrier
	s_setprio 1
	s_waitcnt lgkmcnt(0)
	v_mfma_f32_16x16x32_bf16 v[126:129], v[10:13], v[146:149], v[126:129]
	v_mfma_f32_16x16x32_bf16 v[122:125], v[18:21], v[146:149], v[122:125]
	v_mfma_f32_16x16x32_bf16 v[110:113], v[10:13], v[162:165], v[110:113]
	v_mfma_f32_16x16x32_bf16 v[106:109], v[18:21], v[162:165], v[106:109]
	v_mfma_f32_16x16x32_bf16 v[94:97], v[10:13], v[178:181], v[94:97]
	v_mfma_f32_16x16x32_bf16 v[90:93], v[18:21], v[178:181], v[90:93]
	v_mfma_f32_16x16x32_bf16 v[10:13], v[10:13], v[198:201], v[78:81]
	v_mfma_f32_16x16x32_bf16 v[126:129], v[14:17], v[150:153], v[126:129]
	v_mfma_f32_16x16x32_bf16 v[122:125], v[22:25], v[150:153], v[122:125]
	v_mfma_f32_16x16x32_bf16 v[110:113], v[14:17], v[166:169], v[110:113]
	v_mfma_f32_16x16x32_bf16 v[106:109], v[22:25], v[166:169], v[106:109]
	v_mfma_f32_16x16x32_bf16 v[94:97], v[14:17], v[182:185], v[94:97]
	v_mfma_f32_16x16x32_bf16 v[90:93], v[22:25], v[182:185], v[90:93]
	v_mfma_f32_16x16x32_bf16 v[10:13], v[14:17], v[208:211], v[10:13]
	v_mfma_f32_16x16x32_bf16 v[14:17], v[18:21], v[198:201], v[74:77]
	v_mfma_f32_16x16x32_bf16 v[14:17], v[22:25], v[208:211], v[14:17]
	s_setprio 0
	s_setprio 1
	v_mfma_f32_16x16x32_bf16 v[74:77], v[26:29], v[162:165], v[102:105]
	v_mfma_f32_16x16x32_bf16 v[102:105], v[30:33], v[166:169], v[74:77]
	v_mfma_f32_16x16x32_bf16 v[74:77], v[42:45], v[162:165], v[98:101]
	v_mfma_f32_16x16x32_bf16 v[98:101], v[46:49], v[166:169], v[74:77]
	v_mfma_f32_16x16x32_bf16 v[74:77], v[26:29], v[178:181], v[86:89]
	v_mfma_f32_16x16x32_bf16 v[18:21], v[26:29], v[146:149], v[118:121]
	v_mfma_f32_16x16x32_bf16 v[86:89], v[30:33], v[182:185], v[74:77]
	v_mfma_f32_16x16x32_bf16 v[74:77], v[42:45], v[178:181], v[82:85]
	v_mfma_f32_16x16x32_bf16 v[26:29], v[26:29], v[198:201], v[70:73]
	v_mfma_f32_16x16x32_bf16 v[18:21], v[30:33], v[150:153], v[18:21]
	v_mfma_f32_16x16x32_bf16 v[22:25], v[42:45], v[146:149], v[114:117]
	v_mfma_f32_16x16x32_bf16 v[82:85], v[46:49], v[182:185], v[74:77]
	v_mfma_f32_16x16x32_bf16 v[26:29], v[30:33], v[208:211], v[26:29]
	v_mfma_f32_16x16x32_bf16 v[30:33], v[42:45], v[198:201], v[66:69]
	v_mfma_f32_16x16x32_bf16 v[22:25], v[46:49], v[150:153], v[22:25]
	v_mfma_f32_16x16x32_bf16 v[30:33], v[46:49], v[208:211], v[30:33]
	s_setprio 0
	s_barrier
	v_add_u32_e32 v0, s69, v216
	ds_read_b128 v[42:45], v0
	ds_read_b128 v[46:49], v0 offset:1024
	ds_read_b128 v[66:69], v0 offset:2048
	ds_read_b128 v[70:73], v0 offset:3072
	v_add_u32_e32 v0, s74, v216
	ds_read_b128 v[178:181], v0
	ds_read_b128 v[182:185], v0 offset:1024
	ds_read_b128 v[198:201], v0 offset:2048
	ds_read_b128 v[208:211], v0 offset:3072
	s_add_u32 s34, s34, 0x20000
	s_addc_u32 s35, s35, 0
	s_mov_b32 m0, s64
	ds_read_b128 v[74:77], v217 offset:32768
	ds_read_b128 v[78:81], v217 offset:33792
	ds_read_b128 v[114:117], v217 offset:34816
	ds_read_b128 v[118:121], v217 offset:35840
	ds_read_b128 v[146:149], v217 offset:36864
	ds_read_b128 v[212:215], v217 offset:37888
	ds_read_b128 v[218:221], v217 offset:38912
	ds_read_b128 v[226:229], v217 offset:39936
	s_cmp_lg_u32 s100, 0
	s_cbranch_scc1 .Ltl_qp_1s
	global_load_lds_dwordx4 v186, s[34:35]
	s_mov_b32 m0, s68
	s_nop 0
	global_load_lds_dwordx4 v190, s[34:35]
	s_waitcnt vmcnt(8)
	s_branch .Ltl_qp_1d

; #define PG8_STAGE(bufoff, gbase, voff) do { _Pragma("unroll") for (int _i = 0; _i < 2; ++_i) \
;         __builtin_amdgcn_global_load_lds((const unsigned*)((const char*)(gbase) + (voff)[_i]), (LAS unsigned*)(lds + (bufoff) + ldsw + _i * 8192), 16, 0, 0); } while (0)
; #define PG8_LDA(dst, b, h) do { _Pragma("unroll") for (int m = 0; m < NM; ++m) _Pragma("unroll") for (int k = 0; k < 2; ++k) dst[m][k] = *(const LAS bf16x8*)(lds + PG8_SA(b, h) + aoff + m * 2048 + k * 1024); } while (0)
; #define PG8_LDB(dst, b, h) do { _Pragma("unroll") for (int n = 0; n < 2; ++n) _Pragma("unroll") for (int k = 0; k < 2; ++k) dst[n][k] = *(const LAS bf16x8*)(lds + PG8_SB(b, h) + boff + n * 2048 + k * 1024); } while (0)
; #define PG8_MMA(ai, bj, At, Bt) do { __builtin_amdgcn_s_setprio(1); _Pragma("unroll") for (int m = 0; m < NM; ++m) _Pragma("unroll") for (int n = 0; n < 2; ++n) _Pragma("unroll") for (int k = 0; k < 2; ++k) \
;         acc[ai][bj][m][n] = __builtin_amdgcn_mfma_f32_16x16x32_bf16(Bt[n][k], At[m][k], acc[ai][bj][m][n], 0, 0, 0); __builtin_amdgcn_s_setprio(0); } while (0)
; #define PG8_WAIT_V(n) asm volatile("s_waitcnt vmcnt(" #n ")" ::: "memory")
; #define PG8_WAIT_L(n) asm volatile("s_waitcnt lgkmcnt(" #n ")" ::: "memory")
; #define PG8_BAR __builtin_amdgcn_s_barrier()
; #define PG8_SCHED __builtin_amdgcn_sched_barrier(0)
;     ...
;             PG8_LDB(B0, 1, 0); PG8_LDB(B1, 1, 1); PG8_SCHED; PG8_LDA(At, 1, 0); PG8_STAGE(PG8_SA(0, 1), a2 + hstepA, voffA);
;             PG8_WAIT_V(8); PG8_WAIT_L(0); PG8_BAR; PG8_MMA(0, 0, At, B0); PG8_MMA(0, 1, At, B1); PG8_BAR; PG8_SCHED;
;             PG8_LDA(At, 1, 1); PG8_STAGE(PG8_SB(1, 0), b3, voffB); PG8_STAGE(PG8_SB(1, 1), b3 + hstepB, voffB); PG8_STAGE(PG8_SA(1, 0), a3, voffA);
.Ltl_qp_1d:
	s_waitcnt lgkmcnt(0)
	s_barrier
	s_setprio 1
	s_waitcnt lgkmcnt(0)
	v_mfma_f32_16x16x32_bf16 v[150:153], v[42:45], v[114:117], v[174:177]
	v_mfma_f32_16x16x32_bf16 v[174:177], v[46:49], v[118:121], v[150:153]
	v_mfma_f32_16x16x32_bf16 v[150:153], v[66:69], v[114:117], v[170:173]
	v_mfma_f32_16x16x32_bf16 v[170:173], v[70:73], v[118:121], v[150:153]
	v_mfma_f32_16x16x32_bf16 v[150:153], v[42:45], v[146:149], v[158:161]
	v_mfma_f32_16x16x32_bf16 v[38:41], v[42:45], v[74:77], v[38:41]
	v_mfma_f32_16x16x32_bf16 v[34:37], v[66:69], v[74:77], v[34:37]
	v_mfma_f32_16x16x32_bf16 v[158:161], v[46:49], v[212:215], v[150:153]
	v_mfma_f32_16x16x32_bf16 v[150:153], v[66:69], v[146:149], v[154:157]
	v_mfma_f32_16x16x32_bf16 v[142:145], v[42:45], v[218:221], v[142:145]
	v_mfma_f32_16x16x32_bf16 v[138:141], v[66:69], v[218:221], v[138:141]
	v_mfma_f32_16x16x32_bf16 v[38:41], v[46:49], v[78:81], v[38:41]
	v_mfma_f32_16x16x32_bf16 v[34:37], v[70:73], v[78:81], v[34:37]
	v_mfma_f32_16x16x32_bf16 v[154:157], v[70:73], v[212:215], v[150:153]
	v_mfma_f32_16x16x32_bf16 v[142:145], v[46:49], v[226:229], v[142:145]
	v_mfma_f32_16x16x32_bf16 v[138:141], v[70:73], v[226:229], v[138:141]
	s_setprio 0
	s_setprio 1
	v_mfma_f32_16x16x32_bf16 v[50:53], v[178:181], v[114:117], v[50:53]
	v_mfma_f32_16x16x32_bf16 v[166:169], v[182:185], v[118:121], v[50:53]
	v_mfma_f32_16x16x32_bf16 v[50:53], v[198:201], v[114:117], v[54:57]
	v_mfma_f32_16x16x32_bf16 v[162:165], v[208:211], v[118:121], v[50:53]
	v_mfma_f32_16x16x32_bf16 v[50:53], v[178:181], v[146:149], v[58:61]
	v_mfma_f32_16x16x32_bf16 v[150:153], v[182:185], v[212:215], v[50:53]
	v_mfma_f32_16x16x32_bf16 v[50:53], v[198:201], v[146:149], v[62:65]
	v_mfma_f32_16x16x32_bf16 v[146:149], v[208:211], v[212:215], v[50:53]
	v_mfma_f32_16x16x32_bf16 v[50:53], v[178:181], v[218:221], v[134:137]
	v_mfma_f32_16x16x32_bf16 v[6:9], v[178:181], v[74:77], v[6:9]
	v_mfma_f32_16x16x32_bf16 v[2:5], v[198:201], v[74:77], v[2:5]
	v_mfma_f32_16x16x32_bf16 v[134:137], v[182:185], v[226:229], v[50:53]
	v_mfma_f32_16x16x32_bf16 v[50:53], v[198:201], v[218:221], v[130:133]
	v_mfma_f32_16x16x32_bf16 v[6:9], v[182:185], v[78:81], v[6:9]
	v_mfma_f32_16x16x32_bf16 v[2:5], v[208:211], v[78:81], v[2:5]
	v_mfma_f32_16x16x32_bf16 v[130:133], v[208:211], v[226:229], v[50:53]
	s_setprio 0
	s_barrier
	s_mov_b32 m0, s70
	v_lshl_add_u64 v[74:75], v[202:203], 0, s[66:67]
	s_add_u32 s12, s12, 0x20080
	s_addc_u32 s13, s13, 0
	ds_read_b128 v[50:53], v217 offset:49152
	ds_read_b128 v[54:57], v217 offset:50176
	ds_read_b128 v[58:61], v217 offset:51200
	ds_read_b128 v[62:65], v217 offset:52224
	ds_read_b128 v[212:215], v217 offset:53248
	ds_read_b128 v[218:221], v217 offset:54272
	ds_read_b128 v[226:229], v217 offset:55296
	ds_read_b128 v[230:233], v217 offset:56320
	s_cmp_lg_u32 s100, 0
	s_cbranch_scc1 .Ltl_qp_2s
	global_load_lds_dwordx4 v[74:75], off
	v_lshl_add_u64 v[74:75], v[204:205], 0, s[66:67]
	s_mov_b32 m0, s71
	s_nop 0
	global_load_lds_dwordx4 v[74:75], off
	s_mov_b32 m0, s75
	s_nop 0
	global_load_lds_dwordx4 v188, s[12:13]
	s_mov_b32 m0, s80
	s_nop 0
	global_load_lds_dwordx4 v192, s[12:13]
	v_lshl_add_u64 v[74:75], v[206:207], 0, s[66:67]
	s_mov_b32 m0, s72
	s_nop 0
	global_load_lds_dwordx4 v[74:75], off
	v_lshl_add_u64 v[74:75], v[222:223], 0, s[66:67]
	s_mov_b32 m0, s73
	s_nop 0
	global_load_lds_dwordx4 v[74:75], off
	s_waitcnt vmcnt(8)
	s_branch .Ltl_qp_2d

; #define PG8_STAGE(bufoff, gbase, voff) do { _Pragma("unroll") for (int _i = 0; _i < 2; ++_i) \
;         __builtin_amdgcn_global_load_lds((const unsigned*)((const char*)(gbase) + (voff)[_i]), (LAS unsigned*)(lds + (bufoff) + ldsw + _i * 8192), 16, 0, 0); } while (0)
; #define PG8_LDA(dst, b, h) do { _Pragma("unroll") for (int m = 0; m < NM; ++m) _Pragma("unroll") for (int k = 0; k < 2; ++k) dst[m][k] = *(const LAS bf16x8*)(lds + PG8_SA(b, h) + aoff + m * 2048 + k * 1024); } while (0)
; #define PG8_MMA(ai, bj, At, Bt) do { __builtin_amdgcn_s_setprio(1); _Pragma("unroll") for (int m = 0; m < NM; ++m) _Pragma("unroll") for (int n = 0; n < 2; ++n) _Pragma("unroll") for (int k = 0; k < 2; ++k) \
;         acc[ai][bj][m][n] = __builtin_amdgcn_mfma_f32_16x16x32_bf16(Bt[n][k], At[m][k], acc[ai][bj][m][n], 0, 0, 0); __builtin_amdgcn_s_setprio(0); } while (0)
; #define PG8_WAIT_V(n) asm volatile("s_waitcnt vmcnt(" #n ")" ::: "memory")
; #define PG8_WAIT_L(n) asm volatile("s_waitcnt lgkmcnt(" #n ")" ::: "memory")
; #define PG8_BAR __builtin_amdgcn_s_barrier()
; #define PG8_SCHED __builtin_amdgcn_sched_barrier(0)
;     ...
;             PG8_WAIT_V(8); PG8_WAIT_L(0); PG8_BAR; PG8_MMA(0, 0, At, B0); PG8_MMA(0, 1, At, B1); PG8_BAR; PG8_SCHED;
;             PG8_LDA(At, 1, 1); PG8_STAGE(PG8_SB(1, 0), b3, voffB); PG8_STAGE(PG8_SB(1, 1), b3 + hstepB, voffB); PG8_STAGE(PG8_SA(1, 0), a3, voffA);
;             PG8_WAIT_V(8); PG8_WAIT_L(0); PG8_BAR; PG8_MMA(1, 0, At, B0); PG8_MMA(1, 1, At, B1); PG8_BAR; PG8_SCHED;
;     ...
;         if constexpr (ALIGN_EPI) { if (wr == 0) PG8_BAR; }
.Ltl_qp_2d:
	s_waitcnt lgkmcnt(0)
	s_barrier
	s_setprio 1
	s_waitcnt lgkmcnt(0)
	v_mfma_f32_16x16x32_bf16 v[74:77], v[42:45], v[50:53], v[126:129]
	v_mfma_f32_16x16x32_bf16 v[126:129], v[46:49], v[54:57], v[74:77]
	v_mfma_f32_16x16x32_bf16 v[74:77], v[66:69], v[50:53], v[122:125]
	v_mfma_f32_16x16x32_bf16 v[122:125], v[70:73], v[54:57], v[74:77]
	v_mfma_f32_16x16x32_bf16 v[74:77], v[42:45], v[58:61], v[110:113]
	v_mfma_f32_16x16x32_bf16 v[110:113], v[46:49], v[62:65], v[74:77]
	v_mfma_f32_16x16x32_bf16 v[74:77], v[66:69], v[58:61], v[106:109]
	v_mfma_f32_16x16x32_bf16 v[106:109], v[70:73], v[62:65], v[74:77]
	v_mfma_f32_16x16x32_bf16 v[74:77], v[42:45], v[212:215], v[94:97]
	v_mfma_f32_16x16x32_bf16 v[10:13], v[42:45], v[226:229], v[10:13]
	v_mfma_f32_16x16x32_bf16 v[94:97], v[46:49], v[218:221], v[74:77]
	v_mfma_f32_16x16x32_bf16 v[74:77], v[66:69], v[212:215], v[90:93]
	v_mfma_f32_16x16x32_bf16 v[78:81], v[46:49], v[230:233], v[10:13]
	v_mfma_f32_16x16x32_bf16 v[10:13], v[66:69], v[226:229], v[14:17]
	v_mfma_f32_16x16x32_bf16 v[90:93], v[70:73], v[218:221], v[74:77]
	v_mfma_f32_16x16x32_bf16 v[74:77], v[70:73], v[230:233], v[10:13]
	s_setprio 0
	s_setprio 1
	v_mfma_f32_16x16x32_bf16 v[10:13], v[178:181], v[50:53], v[18:21]
	v_mfma_f32_16x16x32_bf16 v[118:121], v[182:185], v[54:57], v[10:13]
	v_mfma_f32_16x16x32_bf16 v[10:13], v[198:201], v[50:53], v[22:25]
	v_mfma_f32_16x16x32_bf16 v[114:117], v[208:211], v[54:57], v[10:13]
	v_mfma_f32_16x16x32_bf16 v[10:13], v[178:181], v[58:61], v[102:105]
	v_mfma_f32_16x16x32_bf16 v[102:105], v[182:185], v[62:65], v[10:13]
	v_mfma_f32_16x16x32_bf16 v[10:13], v[198:201], v[58:61], v[98:101]
	v_mfma_f32_16x16x32_bf16 v[98:101], v[208:211], v[62:65], v[10:13]
	v_mfma_f32_16x16x32_bf16 v[10:13], v[178:181], v[212:215], v[86:89]
	v_mfma_f32_16x16x32_bf16 v[86:89], v[182:185], v[218:221], v[10:13]
	v_mfma_f32_16x16x32_bf16 v[10:13], v[198:201], v[212:215], v[82:85]
	v_mfma_f32_16x16x32_bf16 v[82:85], v[208:211], v[218:221], v[10:13]
	v_mfma_f32_16x16x32_bf16 v[10:13], v[178:181], v[226:229], v[26:29]
	v_mfma_f32_16x16x32_bf16 v[70:73], v[182:185], v[230:233], v[10:13]
	v_mfma_f32_16x16x32_bf16 v[10:13], v[198:201], v[226:229], v[30:33]
	v_mfma_f32_16x16x32_bf16 v[66:69], v[208:211], v[230:233], v[10:13]
	s_setprio 0
	s_barrier
	s_add_i32 s54, s54, 2
	s_add_u32 s10, s10, 0x100
	s_addc_u32 s11, s11, 0
	s_add_u32 s9, s9, 0x100
	s_addc_u32 s52, s52, 0
	s_cmp_gt_u32 s54, 5
	s_cbranch_scc0 .LBB0_1192
	s_and_b64 vcc, exec, s[16:17]
	s_cbranch_vccz .LBB0_1195
	s_barrier

;     __device__ __forceinline__ size_t aoff(const Unit& u) const { return (size_t)u.pm * bm * lda * 2; }
;     __device__ __forceinline__ size_t boff(const Unit& u) const { return (size_t)u.pn * BM * ldb * 2; }
;     __device__ __forceinline__ size_t aoff(const Unit& u) const { return ((size_t)u.pm * BM * lda + (size_t)u.pn * akoff) * 2; }
;     __device__ __forceinline__ size_t boff(const Unit& u) const { return (size_t)u.pn * BM * ldb * 2; }
;     __device__ __forceinline__ size_t aoff(const Unit& u) const { return ((size_t)u.pm * BM * lda + (size_t)(u.pn >> 1) * akoff) * 2; }
;     __device__ __forceinline__ size_t boff(const Unit& u) const { return (size_t)u.pn * BM * ldb * 2; }
;     __device__ bool next(int i, Unit& u) const {
;         const long L = (long)i * G + c; if (L >= nwg) return false;
;         int wgid = (int)L; { const int q = nwg / NXCD, r = nwg % NXCD, xcd = wgid % NXCD, off = wgid / NXCD; wgid = (xcd < r ? xcd * (q + 1) : r * (q + 1) + (xcd - r) * q) + off; }
;         const int nig = WGM * nN, gid = wgid / nig, fm = gid * WGM, gsz = (nM - fm) < WGM ? (nM - fm) : WGM;
;         u.pm = fm + ((wgid % nig) % gsz); u.pn = (wgid % nig) / gsz; return true;
;     }
;     ...
;         const bool has_next = S.next(ui + 1, nxt);
;         const char* nA = has_next ? (const char*)g.A + S.aoff(nxt) : cA; const char* nB = has_next ? (const char*)g.Bt + S.boff(nxt) : cB;
.LBB0_1445:
	s_add_i32 s69, s69, 1
	s_mul_i32 s2, s69, s68
	s_mul_hi_u32 s3, s69, s53
	s_add_i32 s3, s3, s2
	s_mul_i32 s2, s69, s53
	v_readlane_b32 s4, v255, 29
	s_add_u32 s2, s2, s4
	s_addc_u32 s3, s3, s26
	v_mov_b64_e32 v[2:3], 0x200
	v_cmp_lt_i64_e64 s[6:7], s[2:3], v[2:3]
	v_mov_b64_e32 v[2:3], 0x1ff
	v_cmp_gt_i64_e32 vcc, s[2:3], v[2:3]
	s_nop 3
	s_mov_b32 s101, s6
	s_cbranch_vccnz .LBB0_1451
	s_ashr_i32 s3, s2, 31
	s_lshr_b32 s3, s3, 29
	s_add_i32 s4, s2, s3
	s_and_b32 s3, s4, -8
	s_sub_i32 s5, s2, s3
	s_cmp_gt_i32 s5, -1
	s_mov_b64 s[2:3], -1
	s_cbranch_scc0 .LBB0_1448
	s_lshl_b32 s14, s5, 6
	s_mov_b64 s[2:3], 0

; #define PG8_STAGE(bufoff, gbase, voff) do { _Pragma("unroll") for (int _i = 0; _i < 2; ++_i) \
;         __builtin_amdgcn_global_load_lds((const unsigned*)((const char*)(gbase) + (voff)[_i]), (LAS unsigned*)(lds + (bufoff) + ldsw + _i * 8192), 16, 0, 0); } while (0)
; #define PG8_LDA(dst, b, h) do { _Pragma("unroll") for (int m = 0; m < NM; ++m) _Pragma("unroll") for (int k = 0; k < 2; ++k) dst[m][k] = *(const LAS bf16x8*)(lds + PG8_SA(b, h) + aoff + m * 2048 + k * 1024); } while (0)
; #define PG8_LDB(dst, b, h) do { _Pragma("unroll") for (int n = 0; n < 2; ++n) _Pragma("unroll") for (int k = 0; k < 2; ++k) dst[n][k] = *(const LAS bf16x8*)(lds + PG8_SB(b, h) + boff + n * 2048 + k * 1024); } while (0)
; #define PG8_MMA(ai, bj, At, Bt) do { __builtin_amdgcn_s_setprio(1); _Pragma("unroll") for (int m = 0; m < NM; ++m) _Pragma("unroll") for (int n = 0; n < 2; ++n) _Pragma("unroll") for (int k = 0; k < 2; ++k) \
;         acc[ai][bj][m][n] = __builtin_amdgcn_mfma_f32_16x16x32_bf16(Bt[n][k], At[m][k], acc[ai][bj][m][n], 0, 0, 0); __builtin_amdgcn_s_setprio(0); } while (0)
; #define PG8_WAIT_V(n) asm volatile("s_waitcnt vmcnt(" #n ")" ::: "memory")
; #define PG8_WAIT_L(n) asm volatile("s_waitcnt lgkmcnt(" #n ")" ::: "memory")
; #define PG8_BAR __builtin_amdgcn_s_barrier()
; #define PG8_SCHED __builtin_amdgcn_sched_barrier(0)
;     ...
;         for (int t = 0; t < nt; t += 2) {
;             const bool last = (t == nt - 2);
;             const char* a1 = cA + (size_t)(t + 1) * kstep;
;             const char* a2 = last ? nA : cA + (size_t)(t + 2) * kstep; const char* b2 = last ? nB : cB + (size_t)(t + 2) * kstep;
;             const char* a3 = a2 + kstep; const char* b3 = b2 + kstep;
;             if constexpr (SP2) {
;             PG8_LDB(B0, 0, 0); PG8_LDB(B1, 0, 1); PG8_SCHED; PG8_LDA(At, 0, 0); PG8_STAGE(PG8_SA(1, 1), a1 + hstepA, voffA);
;             PG8_WAIT_V(8); PG8_WAIT_L(0); PG8_BAR; PG8_MMA(0, 0, At, B0); PG8_MMA(0, 1, At, B1); PG8_BAR; PG8_SCHED;
;             PG8_LDA(At, 0, 1); PG8_STAGE(PG8_SB(0, 0), b2, voffB); PG8_STAGE(PG8_SB(0, 1), b2 + hstepB, voffB); PG8_STAGE(PG8_SA(0, 0), a2, voffA);
.LBB0_1454:
	v_add_u32_e32 v140, s31, v142
	ds_read_b128 v[144:147], v140
	ds_read_b128 v[148:151], v140 offset:1024
	ds_read_b128 v[152:155], v140 offset:2048
	ds_read_b128 v[156:159], v140 offset:3072
	v_add_u32_e32 v140, s35, v142
	ds_read_b128 v[160:163], v140
	ds_read_b128 v[164:167], v140 offset:1024
	ds_read_b128 v[168:171], v140 offset:2048
	ds_read_b128 v[172:175], v140 offset:3072
	s_add_u32 s6, s20, 0x100
	s_addc_u32 s7, s21, 0
	s_cmp_eq_u32 s73, 4
	s_cselect_b32 s25, s17, s7
	s_cselect_b32 s24, s16, s6
	s_cselect_b32 s23, s2, s60
	s_cselect_b32 s22, s3, s15
	s_cselect_b32 s100, -1, 0
	s_andn2_b32 s100, s100, s101
	s_add_i32 m0, s45, 0xc000
	ds_read_b128 v[176:179], v143
	ds_read_b128 v[180:183], v143 offset:1024
	ds_read_b128 v[184:187], v143 offset:2048
	ds_read_b128 v[188:191], v143 offset:3072
	ds_read_b128 v[192:195], v143 offset:4096
	ds_read_b128 v[196:199], v143 offset:5120
	ds_read_b128 v[200:203], v143 offset:6144
	ds_read_b128 v[208:211], v143 offset:7168
	global_load_lds_dwordx4 v136, s[20:21]
	s_add_i32 m0, s45, 0xe000
	s_nop 0
	global_load_lds_dwordx4 v138, s[20:21]
	s_waitcnt vmcnt(8)
	s_waitcnt lgkmcnt(0)
	s_barrier
	s_setprio 1
	s_waitcnt lgkmcnt(0)
	v_mfma_f32_16x16x32_bf16 v[126:129], v[144:147], v[176:179], v[126:129]
	v_mfma_f32_16x16x32_bf16 v[122:125], v[152:155], v[176:179], v[122:125]
	v_mfma_f32_16x16x32_bf16 v[118:121], v[144:147], v[184:187], v[118:121]
	v_mfma_f32_16x16x32_bf16 v[114:117], v[152:155], v[184:187], v[114:117]
	v_mfma_f32_16x16x32_bf16 v[110:113], v[144:147], v[192:195], v[110:113]
	v_mfma_f32_16x16x32_bf16 v[106:109], v[152:155], v[192:195], v[106:109]
	v_mfma_f32_16x16x32_bf16 v[102:105], v[144:147], v[200:203], v[102:105]
	v_mfma_f32_16x16x32_bf16 v[98:101], v[152:155], v[200:203], v[98:101]
	v_mfma_f32_16x16x32_bf16 v[126:129], v[148:151], v[180:183], v[126:129]
	v_mfma_f32_16x16x32_bf16 v[122:125], v[156:159], v[180:183], v[122:125]
	v_mfma_f32_16x16x32_bf16 v[118:121], v[148:151], v[188:191], v[118:121]
	v_mfma_f32_16x16x32_bf16 v[114:117], v[156:159], v[188:191], v[114:117]
	v_mfma_f32_16x16x32_bf16 v[110:113], v[148:151], v[196:199], v[110:113]
	v_mfma_f32_16x16x32_bf16 v[106:109], v[156:159], v[196:199], v[106:109]
	v_mfma_f32_16x16x32_bf16 v[102:105], v[148:151], v[208:211], v[102:105]
	v_mfma_f32_16x16x32_bf16 v[98:101], v[156:159], v[208:211], v[98:101]
	s_setprio 0
	s_setprio 1
	v_mfma_f32_16x16x32_bf16 v[62:65], v[160:163], v[176:179], v[62:65]
	v_mfma_f32_16x16x32_bf16 v[58:61], v[168:171], v[176:179], v[58:61]
	v_mfma_f32_16x16x32_bf16 v[54:57], v[160:163], v[184:187], v[54:57]
	v_mfma_f32_16x16x32_bf16 v[50:53], v[168:171], v[184:187], v[50:53]
	v_mfma_f32_16x16x32_bf16 v[46:49], v[160:163], v[192:195], v[46:49]
	v_mfma_f32_16x16x32_bf16 v[42:45], v[168:171], v[192:195], v[42:45]
	v_mfma_f32_16x16x32_bf16 v[38:41], v[160:163], v[200:203], v[38:41]
	v_mfma_f32_16x16x32_bf16 v[34:37], v[168:171], v[200:203], v[34:37]
	v_mfma_f32_16x16x32_bf16 v[62:65], v[164:167], v[180:183], v[62:65]
	v_mfma_f32_16x16x32_bf16 v[58:61], v[172:175], v[180:183], v[58:61]
	v_mfma_f32_16x16x32_bf16 v[54:57], v[164:167], v[188:191], v[54:57]
	v_mfma_f32_16x16x32_bf16 v[50:53], v[172:175], v[188:191], v[50:53]
	v_mfma_f32_16x16x32_bf16 v[46:49], v[164:167], v[196:199], v[46:49]
	v_mfma_f32_16x16x32_bf16 v[42:45], v[172:175], v[196:199], v[42:45]
	v_mfma_f32_16x16x32_bf16 v[38:41], v[164:167], v[208:211], v[38:41]
	v_mfma_f32_16x16x32_bf16 v[34:37], v[172:175], v[208:211], v[34:37]
	s_setprio 0
	s_barrier
	s_mov_b32 m0, s33
	v_lshl_add_u64 v[140:141], s[22:23], 0, v[0:1]
	s_add_u32 s20, s22, 0x20000
	s_addc_u32 s21, s23, 0
	ds_read_b128 v[176:179], v143 offset:16384
	ds_read_b128 v[180:183], v143 offset:17408
	ds_read_b128 v[184:187], v143 offset:18432
	ds_read_b128 v[188:191], v143 offset:19456
	ds_read_b128 v[192:195], v143 offset:20480
	ds_read_b128 v[196:199], v143 offset:21504
	ds_read_b128 v[200:203], v143 offset:22528
	ds_read_b128 v[208:211], v143 offset:23552
	s_cmp_lg_u32 s100, 0
	s_cbranch_scc1 .Ltl_kv_0s
	global_load_lds_dwordx4 v0, s[22:23]
	v_lshl_add_u64 v[204:205], s[22:23], 0, v[134:135]
	s_mov_b32 m0, s34
	s_nop 0
	global_load_lds_dwordx4 v134, s[22:23]
	s_mov_b32 m0, s43
	v_lshl_add_u64 v[212:213], s[24:25], 0, v[132:133]
	global_load_lds_dwordx4 v0, s[20:21]
	s_mov_b32 m0, s44
	s_nop 0
	global_load_lds_dwordx4 v134, s[20:21]
	v_lshl_add_u64 v[206:207], s[24:25], 0, v[130:131]
	s_mov_b32 m0, s45
	s_nop 0
	global_load_lds_dwordx4 v130, s[24:25]
	s_mov_b32 m0, s47
	s_nop 0
	global_load_lds_dwordx4 v132, s[24:25]
	s_waitcnt vmcnt(8)
	s_branch .Ltl_kv_0d

; #define PG8_STAGE(bufoff, gbase, voff) do { _Pragma("unroll") for (int _i = 0; _i < 2; ++_i) \
;         __builtin_amdgcn_global_load_lds((const unsigned*)((const char*)(gbase) + (voff)[_i]), (LAS unsigned*)(lds + (bufoff) + ldsw + _i * 8192), 16, 0, 0); } while (0)
; #define PG8_LDA(dst, b, h) do { _Pragma("unroll") for (int m = 0; m < NM; ++m) _Pragma("unroll") for (int k = 0; k < 2; ++k) dst[m][k] = *(const LAS bf16x8*)(lds + PG8_SA(b, h) + aoff + m * 2048 + k * 1024); } while (0)
; #define PG8_LDB(dst, b, h) do { _Pragma("unroll") for (int n = 0; n < 2; ++n) _Pragma("unroll") for (int k = 0; k < 2; ++k) dst[n][k] = *(const LAS bf16x8*)(lds + PG8_SB(b, h) + boff + n * 2048 + k * 1024); } while (0)
; #define PG8_MMA(ai, bj, At, Bt) do { __builtin_amdgcn_s_setprio(1); _Pragma("unroll") for (int m = 0; m < NM; ++m) _Pragma("unroll") for (int n = 0; n < 2; ++n) _Pragma("unroll") for (int k = 0; k < 2; ++k) \
;         acc[ai][bj][m][n] = __builtin_amdgcn_mfma_f32_16x16x32_bf16(Bt[n][k], At[m][k], acc[ai][bj][m][n], 0, 0, 0); __builtin_amdgcn_s_setprio(0); } while (0)
; #define PG8_WAIT_V(n) asm volatile("s_waitcnt vmcnt(" #n ")" ::: "memory")
; #define PG8_WAIT_L(n) asm volatile("s_waitcnt lgkmcnt(" #n ")" ::: "memory")
; #define PG8_BAR __builtin_amdgcn_s_barrier()
; #define PG8_SCHED __builtin_amdgcn_sched_barrier(0)
;     ...
;             PG8_LDA(At, 0, 1); PG8_STAGE(PG8_SB(0, 0), b2, voffB); PG8_STAGE(PG8_SB(0, 1), b2 + hstepB, voffB); PG8_STAGE(PG8_SA(0, 0), a2, voffA);
;             PG8_WAIT_V(8); PG8_WAIT_L(0); PG8_BAR; PG8_MMA(1, 0, At, B0); PG8_MMA(1, 1, At, B1); PG8_BAR; PG8_SCHED;
;             PG8_LDB(B0, 1, 0); PG8_LDB(B1, 1, 1); PG8_SCHED; PG8_LDA(At, 1, 0); PG8_STAGE(PG8_SA(0, 1), a2 + hstepA, voffA);
.Ltl_kv_0d:
	s_waitcnt lgkmcnt(0)
	s_barrier
	s_setprio 1
	s_waitcnt lgkmcnt(0)
	v_mfma_f32_16x16x32_bf16 v[94:97], v[144:147], v[176:179], v[94:97]
	v_mfma_f32_16x16x32_bf16 v[90:93], v[152:155], v[176:179], v[90:93]
	v_mfma_f32_16x16x32_bf16 v[86:89], v[144:147], v[184:187], v[86:89]
	v_mfma_f32_16x16x32_bf16 v[82:85], v[152:155], v[184:187], v[82:85]
	v_mfma_f32_16x16x32_bf16 v[78:81], v[144:147], v[192:195], v[78:81]
	v_mfma_f32_16x16x32_bf16 v[74:77], v[152:155], v[192:195], v[74:77]
	v_mfma_f32_16x16x32_bf16 v[70:73], v[144:147], v[200:203], v[70:73]
	v_mfma_f32_16x16x32_bf16 v[66:69], v[152:155], v[200:203], v[66:69]
	v_mfma_f32_16x16x32_bf16 v[94:97], v[148:151], v[180:183], v[94:97]
	v_mfma_f32_16x16x32_bf16 v[90:93], v[156:159], v[180:183], v[90:93]
	v_mfma_f32_16x16x32_bf16 v[86:89], v[148:151], v[188:191], v[86:89]
	v_mfma_f32_16x16x32_bf16 v[82:85], v[156:159], v[188:191], v[82:85]
	v_mfma_f32_16x16x32_bf16 v[78:81], v[148:151], v[196:199], v[78:81]
	v_mfma_f32_16x16x32_bf16 v[74:77], v[156:159], v[196:199], v[74:77]
	v_mfma_f32_16x16x32_bf16 v[70:73], v[148:151], v[208:211], v[70:73]
	v_mfma_f32_16x16x32_bf16 v[66:69], v[156:159], v[208:211], v[66:69]
	s_setprio 0
	s_setprio 1
	v_mfma_f32_16x16x32_bf16 v[30:33], v[160:163], v[176:179], v[30:33]
	v_mfma_f32_16x16x32_bf16 v[26:29], v[168:171], v[176:179], v[26:29]
	v_mfma_f32_16x16x32_bf16 v[22:25], v[160:163], v[184:187], v[22:25]
	v_mfma_f32_16x16x32_bf16 v[18:21], v[168:171], v[184:187], v[18:21]
	v_mfma_f32_16x16x32_bf16 v[14:17], v[160:163], v[192:195], v[14:17]
	v_mfma_f32_16x16x32_bf16 v[10:13], v[168:171], v[192:195], v[10:13]
	v_mfma_f32_16x16x32_bf16 v[6:9], v[160:163], v[200:203], v[6:9]
	v_mfma_f32_16x16x32_bf16 v[2:5], v[168:171], v[200:203], v[2:5]
	v_mfma_f32_16x16x32_bf16 v[30:33], v[164:167], v[180:183], v[30:33]
	v_mfma_f32_16x16x32_bf16 v[26:29], v[172:175], v[180:183], v[26:29]
	v_mfma_f32_16x16x32_bf16 v[22:25], v[164:167], v[188:191], v[22:25]
	v_mfma_f32_16x16x32_bf16 v[18:21], v[172:175], v[188:191], v[18:21]
	v_mfma_f32_16x16x32_bf16 v[14:17], v[164:167], v[196:199], v[14:17]
	v_mfma_f32_16x16x32_bf16 v[10:13], v[172:175], v[196:199], v[10:13]
	v_mfma_f32_16x16x32_bf16 v[6:9], v[164:167], v[208:211], v[6:9]
	v_mfma_f32_16x16x32_bf16 v[2:5], v[172:175], v[208:211], v[2:5]
	s_setprio 0
	s_barrier
	v_add_u32_e32 v156, s50, v142
	v_add_u32_e32 v172, s57, v142
	ds_read_b128 v[144:147], v156
	ds_read_b128 v[148:151], v156 offset:1024
	ds_read_b128 v[152:155], v156 offset:2048
	ds_read_b128 v[156:159], v156 offset:3072
	ds_read_b128 v[160:163], v172
	ds_read_b128 v[164:167], v172 offset:1024
	ds_read_b128 v[168:171], v172 offset:2048
	ds_read_b128 v[172:175], v172 offset:3072
	s_add_u32 s20, s24, 0x24000
	s_addc_u32 s21, s25, 0
	s_mov_b32 m0, s48
	ds_read_b128 v[176:179], v143 offset:32768
	ds_read_b128 v[180:183], v143 offset:33792
	ds_read_b128 v[184:187], v143 offset:34816
	ds_read_b128 v[188:191], v143 offset:35840
	ds_read_b128 v[192:195], v143 offset:36864
	ds_read_b128 v[196:199], v143 offset:37888
	ds_read_b128 v[200:203], v143 offset:38912
	ds_read_b128 v[208:211], v143 offset:39936
	s_cmp_lg_u32 s100, 0
	s_cbranch_scc1 .Ltl_kv_1s
	global_load_lds_dwordx4 v130, s[20:21]
	s_mov_b32 m0, s49
	s_nop 0
	global_load_lds_dwordx4 v132, s[20:21]
	s_waitcnt vmcnt(8)
	s_branch .Ltl_kv_1d

; #define PG8_STAGE(bufoff, gbase, voff) do { _Pragma("unroll") for (int _i = 0; _i < 2; ++_i) \
;         __builtin_amdgcn_global_load_lds((const unsigned*)((const char*)(gbase) + (voff)[_i]), (LAS unsigned*)(lds + (bufoff) + ldsw + _i * 8192), 16, 0, 0); } while (0)
; #define PG8_LDA(dst, b, h) do { _Pragma("unroll") for (int m = 0; m < NM; ++m) _Pragma("unroll") for (int k = 0; k < 2; ++k) dst[m][k] = *(const LAS bf16x8*)(lds + PG8_SA(b, h) + aoff + m * 2048 + k * 1024); } while (0)
; #define PG8_LDB(dst, b, h) do { _Pragma("unroll") for (int n = 0; n < 2; ++n) _Pragma("unroll") for (int k = 0; k < 2; ++k) dst[n][k] = *(const LAS bf16x8*)(lds + PG8_SB(b, h) + boff + n * 2048 + k * 1024); } while (0)
; #define PG8_MMA(ai, bj, At, Bt) do { __builtin_amdgcn_s_setprio(1); _Pragma("unroll") for (int m = 0; m < NM; ++m) _Pragma("unroll") for (int n = 0; n < 2; ++n) _Pragma("unroll") for (int k = 0; k < 2; ++k) \
;         acc[ai][bj][m][n] = __builtin_amdgcn_mfma_f32_16x16x32_bf16(Bt[n][k], At[m][k], acc[ai][bj][m][n], 0, 0, 0); __builtin_amdgcn_s_setprio(0); } while (0)
; #define PG8_WAIT_V(n) asm volatile("s_waitcnt vmcnt(" #n ")" ::: "memory")
; #define PG8_WAIT_L(n) asm volatile("s_waitcnt lgkmcnt(" #n ")" ::: "memory")
; #define PG8_BAR __builtin_amdgcn_s_barrier()
; #define PG8_SCHED __builtin_amdgcn_sched_barrier(0)
;     ...
;             PG8_LDB(B0, 1, 0); PG8_LDB(B1, 1, 1); PG8_SCHED; PG8_LDA(At, 1, 0); PG8_STAGE(PG8_SA(0, 1), a2 + hstepA, voffA);
;             PG8_WAIT_V(8); PG8_WAIT_L(0); PG8_BAR; PG8_MMA(0, 0, At, B0); PG8_MMA(0, 1, At, B1); PG8_BAR; PG8_SCHED;
;             PG8_LDA(At, 1, 1); PG8_STAGE(PG8_SB(1, 0), b3, voffB); PG8_STAGE(PG8_SB(1, 1), b3 + hstepB, voffB); PG8_STAGE(PG8_SA(1, 0), a3, voffA);
.Ltl_kv_1d:
	s_waitcnt lgkmcnt(0)
	s_barrier
	s_setprio 1
	s_waitcnt lgkmcnt(0)
	v_mfma_f32_16x16x32_bf16 v[126:129], v[144:147], v[176:179], v[126:129]
	v_mfma_f32_16x16x32_bf16 v[122:125], v[152:155], v[176:179], v[122:125]
	v_mfma_f32_16x16x32_bf16 v[118:121], v[144:147], v[184:187], v[118:121]
	v_mfma_f32_16x16x32_bf16 v[114:117], v[152:155], v[184:187], v[114:117]
	v_mfma_f32_16x16x32_bf16 v[110:113], v[144:147], v[192:195], v[110:113]
	v_mfma_f32_16x16x32_bf16 v[106:109], v[152:155], v[192:195], v[106:109]
	v_mfma_f32_16x16x32_bf16 v[102:105], v[144:147], v[200:203], v[102:105]
	v_mfma_f32_16x16x32_bf16 v[98:101], v[152:155], v[200:203], v[98:101]
	v_mfma_f32_16x16x32_bf16 v[126:129], v[148:151], v[180:183], v[126:129]
	v_mfma_f32_16x16x32_bf16 v[122:125], v[156:159], v[180:183], v[122:125]
	v_mfma_f32_16x16x32_bf16 v[118:121], v[148:151], v[188:191], v[118:121]
	v_mfma_f32_16x16x32_bf16 v[114:117], v[156:159], v[188:191], v[114:117]
	v_mfma_f32_16x16x32_bf16 v[110:113], v[148:151], v[196:199], v[110:113]
	v_mfma_f32_16x16x32_bf16 v[106:109], v[156:159], v[196:199], v[106:109]
	v_mfma_f32_16x16x32_bf16 v[102:105], v[148:151], v[208:211], v[102:105]
	v_mfma_f32_16x16x32_bf16 v[98:101], v[156:159], v[208:211], v[98:101]
	s_setprio 0
	s_setprio 1
	v_mfma_f32_16x16x32_bf16 v[62:65], v[160:163], v[176:179], v[62:65]
	v_mfma_f32_16x16x32_bf16 v[58:61], v[168:171], v[176:179], v[58:61]
	v_mfma_f32_16x16x32_bf16 v[54:57], v[160:163], v[184:187], v[54:57]
	v_mfma_f32_16x16x32_bf16 v[50:53], v[168:171], v[184:187], v[50:53]
	v_mfma_f32_16x16x32_bf16 v[46:49], v[160:163], v[192:195], v[46:49]
	v_mfma_f32_16x16x32_bf16 v[42:45], v[168:171], v[192:195], v[42:45]
	v_mfma_f32_16x16x32_bf16 v[38:41], v[160:163], v[200:203], v[38:41]
	v_mfma_f32_16x16x32_bf16 v[34:37], v[168:171], v[200:203], v[34:37]
	v_mfma_f32_16x16x32_bf16 v[62:65], v[164:167], v[180:183], v[62:65]
	v_mfma_f32_16x16x32_bf16 v[58:61], v[172:175], v[180:183], v[58:61]
	v_mfma_f32_16x16x32_bf16 v[54:57], v[164:167], v[188:191], v[54:57]
	v_mfma_f32_16x16x32_bf16 v[50:53], v[172:175], v[188:191], v[50:53]
	v_mfma_f32_16x16x32_bf16 v[46:49], v[164:167], v[196:199], v[46:49]
	v_mfma_f32_16x16x32_bf16 v[42:45], v[172:175], v[196:199], v[42:45]
	v_mfma_f32_16x16x32_bf16 v[38:41], v[164:167], v[208:211], v[38:41]
	v_mfma_f32_16x16x32_bf16 v[34:37], v[172:175], v[208:211], v[34:37]
	s_setprio 0
	s_barrier
	s_mov_b32 m0, s51
	v_lshl_add_u64 v[140:141], v[140:141], 0, s[66:67]
	s_add_u32 s20, s22, 0x20080
	s_addc_u32 s21, s23, 0
	ds_read_b128 v[176:179], v143 offset:49152
	ds_read_b128 v[180:183], v143 offset:50176
	ds_read_b128 v[184:187], v143 offset:51200
	ds_read_b128 v[188:191], v143 offset:52224
	ds_read_b128 v[192:195], v143 offset:53248
	ds_read_b128 v[196:199], v143 offset:54272
	ds_read_b128 v[200:203], v143 offset:55296
	ds_read_b128 v[208:211], v143 offset:56320
	s_cmp_lg_u32 s100, 0
	s_cbranch_scc1 .Ltl_kv_2s
	global_load_lds_dwordx4 v[140:141], off
	v_lshl_add_u64 v[140:141], v[204:205], 0, s[66:67]
	s_mov_b32 m0, s52
	s_nop 0
	global_load_lds_dwordx4 v[140:141], off
	s_mov_b32 m0, s58
	s_nop 0
	global_load_lds_dwordx4 v0, s[20:21]
	s_mov_b32 m0, s59
	s_nop 0
	global_load_lds_dwordx4 v134, s[20:21]
	v_lshl_add_u64 v[140:141], v[206:207], 0, s[66:67]
	s_mov_b32 m0, s54
	s_nop 0
	global_load_lds_dwordx4 v[140:141], off
	v_lshl_add_u64 v[140:141], v[212:213], 0, s[66:67]
	s_mov_b32 m0, s56
	s_nop 0
	global_load_lds_dwordx4 v[140:141], off
	s_waitcnt vmcnt(8)
	s_branch .Ltl_kv_2d

; #define PG8_STAGE(bufoff, gbase, voff) do { _Pragma("unroll") for (int _i = 0; _i < 2; ++_i) \
;         __builtin_amdgcn_global_load_lds((const unsigned*)((const char*)(gbase) + (voff)[_i]), (LAS unsigned*)(lds + (bufoff) + ldsw + _i * 8192), 16, 0, 0); } while (0)
; #define PG8_LDA(dst, b, h) do { _Pragma("unroll") for (int m = 0; m < NM; ++m) _Pragma("unroll") for (int k = 0; k < 2; ++k) dst[m][k] = *(const LAS bf16x8*)(lds + PG8_SA(b, h) + aoff + m * 2048 + k * 1024); } while (0)
; #define PG8_MMA(ai, bj, At, Bt) do { __builtin_amdgcn_s_setprio(1); _Pragma("unroll") for (int m = 0; m < NM; ++m) _Pragma("unroll") for (int n = 0; n < 2; ++n) _Pragma("unroll") for (int k = 0; k < 2; ++k) \
;         acc[ai][bj][m][n] = __builtin_amdgcn_mfma_f32_16x16x32_bf16(Bt[n][k], At[m][k], acc[ai][bj][m][n], 0, 0, 0); __builtin_amdgcn_s_setprio(0); } while (0)
; #define PG8_WAIT_V(n) asm volatile("s_waitcnt vmcnt(" #n ")" ::: "memory")
; #define PG8_WAIT_L(n) asm volatile("s_waitcnt lgkmcnt(" #n ")" ::: "memory")
; #define PG8_BAR __builtin_amdgcn_s_barrier()
; #define PG8_SCHED __builtin_amdgcn_sched_barrier(0)
;     ...
;             PG8_WAIT_V(8); PG8_WAIT_L(0); PG8_BAR; PG8_MMA(0, 0, At, B0); PG8_MMA(0, 1, At, B1); PG8_BAR; PG8_SCHED;
;             PG8_LDA(At, 1, 1); PG8_STAGE(PG8_SB(1, 0), b3, voffB); PG8_STAGE(PG8_SB(1, 1), b3 + hstepB, voffB); PG8_STAGE(PG8_SA(1, 0), a3, voffA);
;             PG8_WAIT_V(8); PG8_WAIT_L(0); PG8_BAR; PG8_MMA(1, 0, At, B0); PG8_MMA(1, 1, At, B1); PG8_BAR; PG8_SCHED;
;     ...
;         if constexpr (ALIGN_EPI) { if (wr == 0) PG8_BAR; }
.Ltl_kv_2d:
	s_waitcnt lgkmcnt(0)
	s_barrier
	s_setprio 1
	s_waitcnt lgkmcnt(0)
	v_mfma_f32_16x16x32_bf16 v[94:97], v[144:147], v[176:179], v[94:97]
	v_mfma_f32_16x16x32_bf16 v[90:93], v[152:155], v[176:179], v[90:93]
	v_mfma_f32_16x16x32_bf16 v[86:89], v[144:147], v[184:187], v[86:89]
	v_mfma_f32_16x16x32_bf16 v[82:85], v[152:155], v[184:187], v[82:85]
	v_mfma_f32_16x16x32_bf16 v[78:81], v[144:147], v[192:195], v[78:81]
	v_mfma_f32_16x16x32_bf16 v[74:77], v[152:155], v[192:195], v[74:77]
	v_mfma_f32_16x16x32_bf16 v[70:73], v[144:147], v[200:203], v[70:73]
	v_mfma_f32_16x16x32_bf16 v[66:69], v[152:155], v[200:203], v[66:69]
	v_mfma_f32_16x16x32_bf16 v[94:97], v[148:151], v[180:183], v[94:97]
	v_mfma_f32_16x16x32_bf16 v[90:93], v[156:159], v[180:183], v[90:93]
	v_mfma_f32_16x16x32_bf16 v[86:89], v[148:151], v[188:191], v[86:89]
	v_mfma_f32_16x16x32_bf16 v[82:85], v[156:159], v[188:191], v[82:85]
	v_mfma_f32_16x16x32_bf16 v[78:81], v[148:151], v[196:199], v[78:81]
	v_mfma_f32_16x16x32_bf16 v[74:77], v[156:159], v[196:199], v[74:77]
	v_mfma_f32_16x16x32_bf16 v[70:73], v[148:151], v[208:211], v[70:73]
	v_mfma_f32_16x16x32_bf16 v[66:69], v[156:159], v[208:211], v[66:69]
	s_setprio 0
	s_setprio 1
	v_mfma_f32_16x16x32_bf16 v[30:33], v[160:163], v[176:179], v[30:33]
	v_mfma_f32_16x16x32_bf16 v[26:29], v[168:171], v[176:179], v[26:29]
	v_mfma_f32_16x16x32_bf16 v[22:25], v[160:163], v[184:187], v[22:25]
	v_mfma_f32_16x16x32_bf16 v[18:21], v[168:171], v[184:187], v[18:21]
	v_mfma_f32_16x16x32_bf16 v[14:17], v[160:163], v[192:195], v[14:17]
	v_mfma_f32_16x16x32_bf16 v[10:13], v[168:171], v[192:195], v[10:13]
	v_mfma_f32_16x16x32_bf16 v[6:9], v[160:163], v[200:203], v[6:9]
	v_mfma_f32_16x16x32_bf16 v[2:5], v[168:171], v[200:203], v[2:5]
	v_mfma_f32_16x16x32_bf16 v[30:33], v[164:167], v[180:183], v[30:33]
	v_mfma_f32_16x16x32_bf16 v[26:29], v[172:175], v[180:183], v[26:29]
	v_mfma_f32_16x16x32_bf16 v[22:25], v[164:167], v[188:191], v[22:25]
	v_mfma_f32_16x16x32_bf16 v[18:21], v[172:175], v[188:191], v[18:21]
	v_mfma_f32_16x16x32_bf16 v[14:17], v[164:167], v[196:199], v[14:17]
	v_mfma_f32_16x16x32_bf16 v[10:13], v[172:175], v[196:199], v[10:13]
	v_mfma_f32_16x16x32_bf16 v[6:9], v[164:167], v[208:211], v[6:9]
	v_mfma_f32_16x16x32_bf16 v[2:5], v[172:175], v[208:211], v[2:5]
	s_setprio 0
	s_barrier
	s_add_i32 s73, s73, 2
	s_add_u32 s15, s15, 0x100
	s_addc_u32 s60, s60, 0
	s_cmp_gt_u32 s73, 5
	s_mov_b64 s[20:21], s[6:7]
	s_cbranch_scc0 .LBB0_1454
	s_and_b64 vcc, exec, s[12:13]
	s_cbranch_vccz .LBB0_1457
	s_barrier

;     __device__ __forceinline__ size_t aoff(const Unit& u) const { return (size_t)u.pm * bm * lda * 2; }
;     __device__ __forceinline__ size_t boff(const Unit& u) const { return (size_t)u.pn * BM * ldb * 2; }
;     __device__ __forceinline__ size_t aoff(const Unit& u) const { return ((size_t)u.pm * BM * lda + (size_t)u.pn * akoff) * 2; }
;     __device__ __forceinline__ size_t boff(const Unit& u) const { return (size_t)u.pn * BM * ldb * 2; }
;     __device__ __forceinline__ size_t aoff(const Unit& u) const { return ((size_t)u.pm * BM * lda + (size_t)(u.pn >> 1) * akoff) * 2; }
;     __device__ __forceinline__ size_t boff(const Unit& u) const { return (size_t)u.pn * BM * ldb * 2; }
;     __device__ bool next(int i, Unit& u) const {
;         const long L = (long)i * G + c; if (L >= nwg) return false;
;         int wgid = (int)L; { const int q = nwg / NXCD, r = nwg % NXCD, xcd = wgid % NXCD, off = wgid / NXCD; wgid = (xcd < r ? xcd * (q + 1) : r * (q + 1) + (xcd - r) * q) + off; }
;         const int nig = WGM * nN, gid = wgid / nig, fm = gid * WGM, gsz = (nM - fm) < WGM ? (nM - fm) : WGM;
;         u.pm = fm + ((wgid % nig) % gsz); u.pn = (wgid % nig) / gsz; return true;
;     }
;     ...
;         const bool has_next = S.next(ui + 1, nxt);
;         const char* nA = has_next ? (const char*)g.A + S.aoff(nxt) : cA; const char* nB = has_next ? (const char*)g.Bt + S.boff(nxt) : cB;
.LBB0_1645:
	s_add_i32 s54, s54, 1
	s_mul_i32 s2, s54, s48
	s_mul_hi_u32 s3, s54, s53
	s_add_i32 s3, s3, s2
	s_mul_i32 s2, s54, s53
	v_readlane_b32 s6, v255, 29
	s_add_u32 s2, s2, s6
	s_addc_u32 s3, s3, s49
	v_mov_b64_e32 v[2:3], 0x300
	v_cmp_lt_i64_e64 s[8:9], s[2:3], v[2:3]
	v_mov_b64_e32 v[2:3], 0x2ff
	v_cmp_gt_i64_e32 vcc, s[2:3], v[2:3]
	s_nop 3
	s_mov_b32 s101, s8
	s_cbranch_vccnz .LBB0_1647
	s_ashr_i32 s3, s2, 31
	s_lshr_b32 s3, s3, 29
	s_add_i32 s3, s2, s3
	s_ashr_i32 s6, s3, 3
	s_and_b32 s3, s3, -8
	s_sub_i32 s2, s2, s3
	s_cmp_lt_i32 s2, 0
	s_movk_i32 s3, 0x61
	s_cselect_b32 s3, s3, 0x60
	s_mul_i32 s2, s2, s3
	s_add_i32 s2, s2, s6
	s_ashr_i32 s3, s2, 31
	s_lshr_b32 s3, s3, 26
	s_add_i32 s3, s2, s3
	s_ashr_i32 s6, s3, 6
	s_lshl_b32 s6, s6, 3
	s_sub_i32 s7, 0x60, s6
	s_min_i32 s7, s7, 8
	s_abs_i32 s14, s7
	v_cvt_f32_u32_e32 v2, s14
	s_sub_i32 s16, 0, s14
	s_andn2_b32 s3, s3, 63
	s_sub_i32 s2, s2, s3
	v_rcp_iflag_f32_e32 v2, v2
	s_abs_i32 s3, s2
	s_xor_b32 s15, s2, s7
	s_ashr_i32 s15, s15, 31
	v_mul_f32_e32 v2, 0x4f7ffffe, v2
	v_cvt_u32_f32_e32 v2, v2
	s_nop 0
	v_readfirstlane_b32 s17, v2
	s_mul_i32 s16, s16, s17
	s_mul_hi_u32 s16, s17, s16
	s_add_i32 s17, s17, s16
	s_mul_hi_u32 s16, s3, s17
	s_mul_i32 s17, s16, s14
	s_sub_i32 s3, s3, s17
	s_add_i32 s18, s16, 1
	s_sub_i32 s17, s3, s14
	s_cmp_ge_u32 s3, s14
	s_cselect_b32 s16, s18, s16
	s_cselect_b32 s3, s17, s3
	s_add_i32 s17, s16, 1
	s_cmp_ge_u32 s3, s14
	s_cselect_b32 s3, s17, s16
	s_xor_b32 s3, s3, s15
	s_sub_i32 s14, s3, s15
	s_mul_i32 s3, s14, s7
	s_sub_i32 s2, s2, s3
	s_add_i32 s56, s6, s2

; #define PG8_STAGE(bufoff, gbase, voff) do { _Pragma("unroll") for (int _i = 0; _i < 2; ++_i) \
;         __builtin_amdgcn_global_load_lds((const unsigned*)((const char*)(gbase) + (voff)[_i]), (LAS unsigned*)(lds + (bufoff) + ldsw + _i * 8192), 16, 0, 0); } while (0)
; #define PG8_LDA(dst, b, h) do { _Pragma("unroll") for (int m = 0; m < NM; ++m) _Pragma("unroll") for (int k = 0; k < 2; ++k) dst[m][k] = *(const LAS bf16x8*)(lds + PG8_SA(b, h) + aoff + m * 2048 + k * 1024); } while (0)
; #define PG8_LDB(dst, b, h) do { _Pragma("unroll") for (int n = 0; n < 2; ++n) _Pragma("unroll") for (int k = 0; k < 2; ++k) dst[n][k] = *(const LAS bf16x8*)(lds + PG8_SB(b, h) + boff + n * 2048 + k * 1024); } while (0)
; #define PG8_MMA(ai, bj, At, Bt) do { __builtin_amdgcn_s_setprio(1); _Pragma("unroll") for (int m = 0; m < NM; ++m) _Pragma("unroll") for (int n = 0; n < 2; ++n) _Pragma("unroll") for (int k = 0; k < 2; ++k) \
;         acc[ai][bj][m][n] = __builtin_amdgcn_mfma_f32_16x16x32_bf16(Bt[n][k], At[m][k], acc[ai][bj][m][n], 0, 0, 0); __builtin_amdgcn_s_setprio(0); } while (0)
; #define PG8_WAIT_V(n) asm volatile("s_waitcnt vmcnt(" #n ")" ::: "memory")
; #define PG8_WAIT_L(n) asm volatile("s_waitcnt lgkmcnt(" #n ")" ::: "memory")
; #define PG8_BAR __builtin_amdgcn_s_barrier()
; #define PG8_SCHED __builtin_amdgcn_sched_barrier(0)
;     ...
;         for (int t = 0; t < nt; t += 2) {
;             const bool last = (t == nt - 2);
;             const char* a1 = cA + (size_t)(t + 1) * kstep;
;             const char* a2 = last ? nA : cA + (size_t)(t + 2) * kstep; const char* b2 = last ? nB : cB + (size_t)(t + 2) * kstep;
;             const char* a3 = a2 + kstep; const char* b3 = b2 + kstep;
;             if constexpr (SP2) {
;             PG8_LDB(B0, 0, 0); PG8_LDB(B1, 0, 1); PG8_SCHED; PG8_LDA(At, 0, 0); PG8_STAGE(PG8_SA(1, 1), a1 + hstepA, voffA);
;             PG8_WAIT_V(8); PG8_WAIT_L(0); PG8_BAR; PG8_MMA(0, 0, At, B0); PG8_MMA(0, 1, At, B1); PG8_BAR; PG8_SCHED;
.LBB0_1650:
	v_add_u32_e32 v102, s21, v166
	v_add_u32_e32 v126, s31, v166
	ds_read_b128 v[90:93], v102
	ds_read_b128 v[94:97], v102 offset:1024
	ds_read_b128 v[98:101], v102 offset:2048
	ds_read_b128 v[102:105], v102 offset:3072
	ds_read_b128 v[114:117], v126
	ds_read_b128 v[118:121], v126 offset:1024
	ds_read_b128 v[122:125], v126 offset:2048
	ds_read_b128 v[126:129], v126 offset:3072
	s_add_u32 s22, s8, 0xfffa0080
	s_addc_u32 s23, s9, -1
	s_cmp_eq_u32 s59, 28
	s_cselect_b32 s25, s17, s23
	s_cselect_b32 s24, s16, s22
	s_cselect_b32 s23, s2, s58
	s_cselect_b32 s22, s3, s15
	s_cselect_b32 s100, -1, 0
	s_andn2_b32 s100, s100, s101
	s_add_i32 m0, s35, 0xc000
	ds_read_b128 v[130:133], v167
	ds_read_b128 v[134:137], v167 offset:1024
	ds_read_b128 v[138:141], v167 offset:2048
	ds_read_b128 v[152:155], v167 offset:3072
	ds_read_b128 v[156:159], v167 offset:4096
	ds_read_b128 v[160:163], v167 offset:5120
	global_load_lds_dwordx4 v148, s[8:9]
	s_add_i32 m0, s35, 0xe000
	s_nop 0
	s_and_b64 vcc, exec, s[10:11]
	s_cbranch_vccz .Lnm3o_skip0
	global_load_lds_dwordx4 v150, s[8:9]
	s_waitcnt vmcnt(8)
	s_branch .Lnm3o_done0

; #define PG8_STAGE(bufoff, gbase, voff) do { _Pragma("unroll") for (int _i = 0; _i < 2; ++_i) \
;         __builtin_amdgcn_global_load_lds((const unsigned*)((const char*)(gbase) + (voff)[_i]), (LAS unsigned*)(lds + (bufoff) + ldsw + _i * 8192), 16, 0, 0); } while (0)
; #define PG8_LDA(dst, b, h) do { _Pragma("unroll") for (int m = 0; m < NM; ++m) _Pragma("unroll") for (int k = 0; k < 2; ++k) dst[m][k] = *(const LAS bf16x8*)(lds + PG8_SA(b, h) + aoff + m * 2048 + k * 1024); } while (0)
; #define PG8_LDB(dst, b, h) do { _Pragma("unroll") for (int n = 0; n < 2; ++n) _Pragma("unroll") for (int k = 0; k < 2; ++k) dst[n][k] = *(const LAS bf16x8*)(lds + PG8_SB(b, h) + boff + n * 2048 + k * 1024); } while (0)
; #define PG8_MMA(ai, bj, At, Bt) do { __builtin_amdgcn_s_setprio(1); _Pragma("unroll") for (int m = 0; m < NM; ++m) _Pragma("unroll") for (int n = 0; n < 2; ++n) _Pragma("unroll") for (int k = 0; k < 2; ++k) \
;         acc[ai][bj][m][n] = __builtin_amdgcn_mfma_f32_16x16x32_bf16(Bt[n][k], At[m][k], acc[ai][bj][m][n], 0, 0, 0); __builtin_amdgcn_s_setprio(0); } while (0)
; #define PG8_WAIT_V(n) asm volatile("s_waitcnt vmcnt(" #n ")" ::: "memory")
; #define PG8_WAIT_L(n) asm volatile("s_waitcnt lgkmcnt(" #n ")" ::: "memory")
; #define PG8_BAR __builtin_amdgcn_s_barrier()
; #define PG8_SCHED __builtin_amdgcn_sched_barrier(0)
;     ...
;             PG8_WAIT_V(8); PG8_WAIT_L(0); PG8_BAR; PG8_MMA(0, 0, At, B0); PG8_MMA(0, 1, At, B1); PG8_BAR; PG8_SCHED;
;             PG8_LDA(At, 0, 1); PG8_STAGE(PG8_SB(0, 0), b2, voffB); PG8_STAGE(PG8_SB(0, 1), b2 + hstepB, voffB); PG8_STAGE(PG8_SA(0, 0), a2, voffA);
;             PG8_WAIT_V(8); PG8_WAIT_L(0); PG8_BAR; PG8_MMA(1, 0, At, B0); PG8_MMA(1, 1, At, B1); PG8_BAR; PG8_SCHED;
;             PG8_LDB(B0, 1, 0); PG8_LDB(B1, 1, 1); PG8_SCHED; PG8_LDA(At, 1, 0); PG8_STAGE(PG8_SA(0, 1), a2 + hstepA, voffA);
;             PG8_WAIT_V(8); PG8_WAIT_L(0); PG8_BAR; PG8_MMA(0, 0, At, B0); PG8_MMA(0, 1, At, B1); PG8_BAR; PG8_SCHED;
.Lnm3o_done0:
	s_waitcnt lgkmcnt(0)
	s_barrier
	s_setprio 1
	s_waitcnt lgkmcnt(0)
	v_mfma_f32_16x16x32_bf16 v[110:113], v[90:93], v[130:133], v[110:113]
	v_mfma_f32_16x16x32_bf16 v[106:109], v[98:101], v[130:133], v[106:109]
	v_mfma_f32_16x16x32_bf16 v[78:81], v[90:93], v[138:141], v[78:81]
	v_mfma_f32_16x16x32_bf16 v[74:77], v[98:101], v[138:141], v[74:77]
	v_mfma_f32_16x16x32_bf16 v[62:65], v[90:93], v[156:159], v[62:65]
	v_mfma_f32_16x16x32_bf16 v[58:61], v[98:101], v[156:159], v[58:61]
	v_mfma_f32_16x16x32_bf16 v[110:113], v[94:97], v[134:137], v[110:113]
	v_mfma_f32_16x16x32_bf16 v[106:109], v[102:105], v[134:137], v[106:109]
	v_mfma_f32_16x16x32_bf16 v[78:81], v[94:97], v[152:155], v[78:81]
	v_mfma_f32_16x16x32_bf16 v[74:77], v[102:105], v[152:155], v[74:77]
	v_mfma_f32_16x16x32_bf16 v[62:65], v[94:97], v[160:163], v[62:65]
	v_mfma_f32_16x16x32_bf16 v[58:61], v[102:105], v[160:163], v[58:61]
	s_setprio 0
	s_setprio 1
	v_mfma_f32_16x16x32_bf16 v[86:89], v[114:117], v[130:133], v[86:89]
	v_mfma_f32_16x16x32_bf16 v[82:85], v[122:125], v[130:133], v[82:85]
	v_mfma_f32_16x16x32_bf16 v[70:73], v[114:117], v[138:141], v[70:73]
	v_mfma_f32_16x16x32_bf16 v[66:69], v[122:125], v[138:141], v[66:69]
	v_mfma_f32_16x16x32_bf16 v[54:57], v[114:117], v[156:159], v[54:57]
	v_mfma_f32_16x16x32_bf16 v[50:53], v[122:125], v[156:159], v[50:53]
	v_mfma_f32_16x16x32_bf16 v[86:89], v[118:121], v[134:137], v[86:89]
	v_mfma_f32_16x16x32_bf16 v[82:85], v[126:129], v[134:137], v[82:85]
	v_mfma_f32_16x16x32_bf16 v[70:73], v[118:121], v[152:155], v[70:73]
	v_mfma_f32_16x16x32_bf16 v[66:69], v[126:129], v[152:155], v[66:69]
	v_mfma_f32_16x16x32_bf16 v[54:57], v[118:121], v[160:163], v[54:57]
	v_mfma_f32_16x16x32_bf16 v[50:53], v[126:129], v[160:163], v[50:53]
	s_setprio 0
	s_barrier
	s_mov_b32 m0, s29
	v_lshl_add_u64 v[164:165], s[22:23], 0, v[0:1]
	s_add_u32 s62, s22, 0x80000
	s_addc_u32 s63, s23, 0
	ds_read_b128 v[130:133], v167 offset:16384
	ds_read_b128 v[134:137], v167 offset:17408
	ds_read_b128 v[138:141], v167 offset:18432
	ds_read_b128 v[152:155], v167 offset:19456
	ds_read_b128 v[156:159], v167 offset:20480
	ds_read_b128 v[160:163], v167 offset:21504
	s_cmp_lg_u32 s100, 0
	s_cbranch_scc1 .Ltl_ou_0s
	global_load_lds_dwordx4 v0, s[22:23]
	v_lshl_add_u64 v[168:169], s[22:23], 0, v[146:147]
	s_mov_b32 m0, s30
	s_nop 0
	global_load_lds_dwordx4 v146, s[22:23]
	s_mov_b32 m0, s33
	v_lshl_add_u64 v[172:173], s[24:25], 0, v[144:145]
	global_load_lds_dwordx4 v0, s[62:63]
	s_mov_b32 m0, s34
	s_nop 0
	global_load_lds_dwordx4 v146, s[62:63]
	v_lshl_add_u64 v[170:171], s[24:25], 0, v[142:143]
	s_mov_b32 m0, s35
	s_nop 0
	global_load_lds_dwordx4 v142, s[24:25]
	s_mov_b32 m0, s36
	s_nop 0
	s_and_b64 vcc, exec, s[10:11]
	s_cbranch_vccz .Lnm3o_skip1
	global_load_lds_dwordx4 v144, s[24:25]
	s_waitcnt vmcnt(8)
	s_branch .Lnm3o_done1
.Lnm3o_skip1:
	s_waitcnt vmcnt(6)
.Lnm3o_done1:
	s_branch .Ltl_ou_0d
.Ltl_ou_0s:
	s_waitcnt vmcnt(0)
.Ltl_ou_0d:
	s_waitcnt lgkmcnt(0)
	s_barrier
	s_setprio 1
	s_waitcnt lgkmcnt(0)
	v_mfma_f32_16x16x32_bf16 v[46:49], v[90:93], v[130:133], v[46:49]
	v_mfma_f32_16x16x32_bf16 v[42:45], v[98:101], v[130:133], v[42:45]
	v_mfma_f32_16x16x32_bf16 v[30:33], v[90:93], v[138:141], v[30:33]
	v_mfma_f32_16x16x32_bf16 v[26:29], v[98:101], v[138:141], v[26:29]
	v_mfma_f32_16x16x32_bf16 v[14:17], v[90:93], v[156:159], v[14:17]
	v_mfma_f32_16x16x32_bf16 v[10:13], v[98:101], v[156:159], v[10:13]
	v_mfma_f32_16x16x32_bf16 v[46:49], v[94:97], v[134:137], v[46:49]
	v_mfma_f32_16x16x32_bf16 v[42:45], v[102:105], v[134:137], v[42:45]
	v_mfma_f32_16x16x32_bf16 v[30:33], v[94:97], v[152:155], v[30:33]
	v_mfma_f32_16x16x32_bf16 v[26:29], v[102:105], v[152:155], v[26:29]
	v_mfma_f32_16x16x32_bf16 v[14:17], v[94:97], v[160:163], v[14:17]
	v_mfma_f32_16x16x32_bf16 v[10:13], v[102:105], v[160:163], v[10:13]
	s_setprio 0
	s_setprio 1
	v_mfma_f32_16x16x32_bf16 v[38:41], v[114:117], v[130:133], v[38:41]
	v_mfma_f32_16x16x32_bf16 v[34:37], v[122:125], v[130:133], v[34:37]
	v_mfma_f32_16x16x32_bf16 v[22:25], v[114:117], v[138:141], v[22:25]
	v_mfma_f32_16x16x32_bf16 v[18:21], v[122:125], v[138:141], v[18:21]
	v_mfma_f32_16x16x32_bf16 v[6:9], v[114:117], v[156:159], v[6:9]
	v_mfma_f32_16x16x32_bf16 v[2:5], v[122:125], v[156:159], v[2:5]
	v_mfma_f32_16x16x32_bf16 v[38:41], v[118:121], v[134:137], v[38:41]
	v_mfma_f32_16x16x32_bf16 v[34:37], v[126:129], v[134:137], v[34:37]
	v_mfma_f32_16x16x32_bf16 v[22:25], v[118:121], v[152:155], v[22:25]
	v_mfma_f32_16x16x32_bf16 v[18:21], v[126:129], v[152:155], v[18:21]
	v_mfma_f32_16x16x32_bf16 v[6:9], v[118:121], v[160:163], v[6:9]
	v_mfma_f32_16x16x32_bf16 v[2:5], v[126:129], v[160:163], v[2:5]
	s_setprio 0
	s_barrier
	v_add_u32_e32 v102, s40, v166
	v_add_u32_e32 v126, s45, v166
	ds_read_b128 v[90:93], v102
	ds_read_b128 v[94:97], v102 offset:1024
	ds_read_b128 v[98:101], v102 offset:2048
	ds_read_b128 v[102:105], v102 offset:3072
	ds_read_b128 v[114:117], v126
	ds_read_b128 v[118:121], v126 offset:1024
	ds_read_b128 v[122:125], v126 offset:2048
	ds_read_b128 v[126:129], v126 offset:3072
	s_add_u32 s24, s24, 0x60000
	s_addc_u32 s25, s25, 0
	s_mov_b32 m0, s37
	ds_read_b128 v[130:133], v167 offset:32768
	ds_read_b128 v[134:137], v167 offset:33792
	ds_read_b128 v[138:141], v167 offset:34816
	ds_read_b128 v[152:155], v167 offset:35840
	ds_read_b128 v[156:159], v167 offset:36864
	ds_read_b128 v[160:163], v167 offset:37888
	s_cmp_lg_u32 s100, 0
	s_cbranch_scc1 .Ltl_ou_1s
	global_load_lds_dwordx4 v142, s[24:25]
	s_mov_b32 m0, s38
	s_nop 0
	s_and_b64 vcc, exec, s[10:11]
	s_cbranch_vccz .Lnm3o_skip2
	global_load_lds_dwordx4 v144, s[24:25]
	s_waitcnt vmcnt(8)
	s_branch .Lnm3o_done2
; #define PG8_STAGE(bufoff, gbase, voff) do { _Pragma("unroll") for (int _i = 0; _i < 2; ++_i) \
;         __builtin_amdgcn_global_load_lds((const unsigned*)((const char*)(gbase) + (voff)[_i]), (LAS unsigned*)(lds + (bufoff) + ldsw + _i * 8192), 16, 0, 0); } while (0)
; #define PG8_LDA(dst, b, h) do { _Pragma("unroll") for (int m = 0; m < NM; ++m) _Pragma("unroll") for (int k = 0; k < 2; ++k) dst[m][k] = *(const LAS bf16x8*)(lds + PG8_SA(b, h) + aoff + m * 2048 + k * 1024); } while (0)
; #define PG8_MMA(ai, bj, At, Bt) do { __builtin_amdgcn_s_setprio(1); _Pragma("unroll") for (int m = 0; m < NM; ++m) _Pragma("unroll") for (int n = 0; n < 2; ++n) _Pragma("unroll") for (int k = 0; k < 2; ++k) \
;         acc[ai][bj][m][n] = __builtin_amdgcn_mfma_f32_16x16x32_bf16(Bt[n][k], At[m][k], acc[ai][bj][m][n], 0, 0, 0); __builtin_amdgcn_s_setprio(0); } while (0)
; #define PG8_WAIT_V(n) asm volatile("s_waitcnt vmcnt(" #n ")" ::: "memory")
; #define PG8_WAIT_L(n) asm volatile("s_waitcnt lgkmcnt(" #n ")" ::: "memory")
; #define PG8_BAR __builtin_amdgcn_s_barrier()
; #define PG8_SCHED __builtin_amdgcn_sched_barrier(0)
;     ...
;             PG8_WAIT_V(8); PG8_WAIT_L(0); PG8_BAR; PG8_MMA(0, 0, At, B0); PG8_MMA(0, 1, At, B1); PG8_BAR; PG8_SCHED;
;             PG8_LDA(At, 1, 1); PG8_STAGE(PG8_SB(1, 0), b3, voffB); PG8_STAGE(PG8_SB(1, 1), b3 + hstepB, voffB); PG8_STAGE(PG8_SA(1, 0), a3, voffA);
;             PG8_WAIT_V(8); PG8_WAIT_L(0); PG8_BAR; PG8_MMA(1, 0, At, B0); PG8_MMA(1, 1, At, B1); PG8_BAR; PG8_SCHED;
;     ...
;         if constexpr (ALIGN_EPI) { if (wr == 0) PG8_BAR; }
.Lnm3o_skip2:
	s_waitcnt vmcnt(6)
.Lnm3o_done2:
	s_branch .Ltl_ou_1d
.Ltl_ou_1s:
	s_waitcnt vmcnt(0)
.Ltl_ou_1d:
	s_waitcnt lgkmcnt(0)
	s_barrier
	s_setprio 1
	s_waitcnt lgkmcnt(0)
	v_mfma_f32_16x16x32_bf16 v[110:113], v[90:93], v[130:133], v[110:113]
	v_mfma_f32_16x16x32_bf16 v[106:109], v[98:101], v[130:133], v[106:109]
	v_mfma_f32_16x16x32_bf16 v[78:81], v[90:93], v[138:141], v[78:81]
	v_mfma_f32_16x16x32_bf16 v[74:77], v[98:101], v[138:141], v[74:77]
	v_mfma_f32_16x16x32_bf16 v[62:65], v[90:93], v[156:159], v[62:65]
	v_mfma_f32_16x16x32_bf16 v[58:61], v[98:101], v[156:159], v[58:61]
	v_mfma_f32_16x16x32_bf16 v[110:113], v[94:97], v[134:137], v[110:113]
	v_mfma_f32_16x16x32_bf16 v[106:109], v[102:105], v[134:137], v[106:109]
	v_mfma_f32_16x16x32_bf16 v[78:81], v[94:97], v[152:155], v[78:81]
	v_mfma_f32_16x16x32_bf16 v[74:77], v[102:105], v[152:155], v[74:77]
	v_mfma_f32_16x16x32_bf16 v[62:65], v[94:97], v[160:163], v[62:65]
	v_mfma_f32_16x16x32_bf16 v[58:61], v[102:105], v[160:163], v[58:61]
	s_setprio 0
	s_setprio 1
	v_mfma_f32_16x16x32_bf16 v[86:89], v[114:117], v[130:133], v[86:89]
	v_mfma_f32_16x16x32_bf16 v[82:85], v[122:125], v[130:133], v[82:85]
	v_mfma_f32_16x16x32_bf16 v[70:73], v[114:117], v[138:141], v[70:73]
	v_mfma_f32_16x16x32_bf16 v[66:69], v[122:125], v[138:141], v[66:69]
	v_mfma_f32_16x16x32_bf16 v[54:57], v[114:117], v[156:159], v[54:57]
	v_mfma_f32_16x16x32_bf16 v[50:53], v[122:125], v[156:159], v[50:53]
	v_mfma_f32_16x16x32_bf16 v[86:89], v[118:121], v[134:137], v[86:89]
	v_mfma_f32_16x16x32_bf16 v[82:85], v[126:129], v[134:137], v[82:85]
	v_mfma_f32_16x16x32_bf16 v[70:73], v[118:121], v[152:155], v[70:73]
	v_mfma_f32_16x16x32_bf16 v[66:69], v[126:129], v[152:155], v[66:69]
	v_mfma_f32_16x16x32_bf16 v[54:57], v[118:121], v[160:163], v[54:57]
	v_mfma_f32_16x16x32_bf16 v[50:53], v[126:129], v[160:163], v[50:53]
	s_setprio 0
	s_barrier
	s_mov_b32 m0, s41
	v_lshl_add_u64 v[164:165], v[164:165], 0, s[66:67]
	s_add_u32 s22, s22, 0x80080
	s_addc_u32 s23, s23, 0
	ds_read_b128 v[130:133], v167 offset:49152
	ds_read_b128 v[134:137], v167 offset:50176
	ds_read_b128 v[138:141], v167 offset:51200
	ds_read_b128 v[152:155], v167 offset:52224
	ds_read_b128 v[156:159], v167 offset:53248
	ds_read_b128 v[160:163], v167 offset:54272
	s_cmp_lg_u32 s100, 0
	s_cbranch_scc1 .Ltl_ou_2s
	global_load_lds_dwordx4 v[164:165], off
	v_lshl_add_u64 v[164:165], v[168:169], 0, s[66:67]
	s_mov_b32 m0, s42
	s_nop 0
	global_load_lds_dwordx4 v[164:165], off
	s_mov_b32 m0, s46
	s_nop 0
	global_load_lds_dwordx4 v0, s[22:23]
	s_mov_b32 m0, s47
	s_nop 0
	global_load_lds_dwordx4 v146, s[22:23]
	v_lshl_add_u64 v[164:165], v[170:171], 0, s[66:67]
	s_mov_b32 m0, s43
	s_nop 0
	global_load_lds_dwordx4 v[164:165], off
	v_lshl_add_u64 v[164:165], v[172:173], 0, s[66:67]
	s_mov_b32 m0, s44
	s_nop 0
	s_and_b64 vcc, exec, s[10:11]
	s_cbranch_vccz .Lnm3o_skip3
	global_load_lds_dwordx4 v[164:165], off
	s_waitcnt vmcnt(8)
	s_branch .Lnm3o_done3
.Lnm3o_skip3:
	s_waitcnt vmcnt(6)
.Lnm3o_done3:
	s_branch .Ltl_ou_2d
.Ltl_ou_2s:
	s_waitcnt vmcnt(0)
.Ltl_ou_2d:
	s_waitcnt lgkmcnt(0)
	s_barrier
	s_setprio 1
	s_waitcnt lgkmcnt(0)
	v_mfma_f32_16x16x32_bf16 v[46:49], v[90:93], v[130:133], v[46:49]
	v_mfma_f32_16x16x32_bf16 v[42:45], v[98:101], v[130:133], v[42:45]
	v_mfma_f32_16x16x32_bf16 v[30:33], v[90:93], v[138:141], v[30:33]
	v_mfma_f32_16x16x32_bf16 v[26:29], v[98:101], v[138:141], v[26:29]
	v_mfma_f32_16x16x32_bf16 v[14:17], v[90:93], v[156:159], v[14:17]
	v_mfma_f32_16x16x32_bf16 v[10:13], v[98:101], v[156:159], v[10:13]
	v_mfma_f32_16x16x32_bf16 v[46:49], v[94:97], v[134:137], v[46:49]
	v_mfma_f32_16x16x32_bf16 v[42:45], v[102:105], v[134:137], v[42:45]
	v_mfma_f32_16x16x32_bf16 v[30:33], v[94:97], v[152:155], v[30:33]
	v_mfma_f32_16x16x32_bf16 v[26:29], v[102:105], v[152:155], v[26:29]
	v_mfma_f32_16x16x32_bf16 v[14:17], v[94:97], v[160:163], v[14:17]
	v_mfma_f32_16x16x32_bf16 v[10:13], v[102:105], v[160:163], v[10:13]
	s_setprio 0
	s_setprio 1
	v_mfma_f32_16x16x32_bf16 v[38:41], v[114:117], v[130:133], v[38:41]
	v_mfma_f32_16x16x32_bf16 v[34:37], v[122:125], v[130:133], v[34:37]
	v_mfma_f32_16x16x32_bf16 v[22:25], v[114:117], v[138:141], v[22:25]
	v_mfma_f32_16x16x32_bf16 v[18:21], v[122:125], v[138:141], v[18:21]
	v_mfma_f32_16x16x32_bf16 v[6:9], v[114:117], v[156:159], v[6:9]
	v_mfma_f32_16x16x32_bf16 v[2:5], v[122:125], v[156:159], v[2:5]
	v_mfma_f32_16x16x32_bf16 v[38:41], v[118:121], v[134:137], v[38:41]
	v_mfma_f32_16x16x32_bf16 v[34:37], v[126:129], v[134:137], v[34:37]
	v_mfma_f32_16x16x32_bf16 v[22:25], v[118:121], v[152:155], v[22:25]
	v_mfma_f32_16x16x32_bf16 v[18:21], v[126:129], v[152:155], v[18:21]
	v_mfma_f32_16x16x32_bf16 v[6:9], v[118:121], v[160:163], v[6:9]
	v_mfma_f32_16x16x32_bf16 v[2:5], v[126:129], v[160:163], v[2:5]
	s_setprio 0
	s_barrier
	s_add_i32 s59, s59, 2
	s_add_u32 s8, s8, 0x100
	s_addc_u32 s9, s9, 0
	s_add_u32 s15, s15, 0x100
	s_addc_u32 s58, s58, 0
	s_cmp_gt_u32 s59, 29
	s_cbranch_scc0 .LBB0_1650
	s_and_b64 vcc, exec, s[10:11]
	s_cbranch_vccz .LBB0_1653
	s_barrier

;     __device__ __forceinline__ size_t aoff(const Unit& u) const { return (size_t)u.pm * bm * lda * 2; }
;     __device__ __forceinline__ size_t boff(const Unit& u) const { return (size_t)u.pn * BM * ldb * 2; }
;     __device__ __forceinline__ size_t aoff(const Unit& u) const { return ((size_t)u.pm * BM * lda + (size_t)u.pn * akoff) * 2; }
;     __device__ __forceinline__ size_t boff(const Unit& u) const { return (size_t)u.pn * BM * ldb * 2; }
;     __device__ __forceinline__ size_t aoff(const Unit& u) const { return ((size_t)u.pm * BM * lda + (size_t)(u.pn >> 1) * akoff) * 2; }
;     __device__ __forceinline__ size_t boff(const Unit& u) const { return (size_t)u.pn * BM * ldb * 2; }
;     __device__ bool next(int i, Unit& u) const {
;         const long L = (long)i * G + c; if (L >= nwg) return false;
;         int wgid = (int)L; { const int q = nwg / NXCD, r = nwg % NXCD, xcd = wgid % NXCD, off = wgid / NXCD; wgid = (xcd < r ? xcd * (q + 1) : r * (q + 1) + (xcd - r) * q) + off; }
;         const int nig = WGM * nN, gid = wgid / nig, fm = gid * WGM, gsz = (nM - fm) < WGM ? (nM - fm) : WGM;
;         u.pm = fm + ((wgid % nig) % gsz); u.pn = (wgid % nig) / gsz; return true;
;     }
;     ...
;         const bool has_next = S.next(ui + 1, nxt);
;         const char* nA = has_next ? (const char*)g.A + S.aoff(nxt) : cA; const char* nB = has_next ? (const char*)g.Bt + S.boff(nxt) : cB;
.LBB0_1770:
	s_add_i32 s78, s78, 1
	s_mul_i32 s2, s78, s89
	s_mul_hi_u32 s3, s78, s53
	s_add_i32 s3, s3, s2
	s_mul_i32 s2, s78, s53
	s_add_u32 s2, s2, s46
	s_addc_u32 s3, s3, s52
	v_mov_b64_e32 v[2:3], 0xc60
	v_cmp_lt_i64_e64 s[6:7], s[2:3], v[2:3]
	v_mov_b64_e32 v[2:3], 0xc5f
	v_cmp_gt_i64_e32 vcc, s[2:3], v[2:3]
	s_nop 3
	s_mov_b32 s101, s6
	s_cbranch_vccnz .LBB0_1772
	s_ashr_i32 s3, s2, 31
	s_lshr_b32 s3, s3, 29
	s_add_i32 s3, s2, s3
	s_ashr_i32 s9, s3, 3
	s_and_b32 s3, s3, -8
	s_sub_i32 s2, s2, s3
	s_cmp_lt_i32 s2, 0
	s_movk_i32 s3, 0x18d
	s_cselect_b32 s3, s3, 0x18c
	s_mul_i32 s2, s2, s3
	s_add_i32 s2, s2, s9
	s_mul_hi_i32 s3, s2, 0x2e8ba2e9
	s_lshr_b32 s9, s3, 31
	s_ashr_i32 s3, s3, 6
	s_add_i32 s3, s3, s9
	s_lshl_b32 s9, s3, 3
	s_sub_i32 s11, 0x48, s9
	s_min_i32 s11, s11, 8
	s_abs_i32 s22, s11
	v_cvt_f32_u32_e32 v0, s22
	s_sub_i32 s36, 0, s22
	s_mulk_i32 s3, 0x160
	s_sub_i32 s2, s2, s3
	v_rcp_iflag_f32_e32 v0, v0
	s_abs_i32 s3, s2
	s_xor_b32 s23, s2, s11
	s_ashr_i32 s23, s23, 31
	v_mul_f32_e32 v0, 0x4f7ffffe, v0
	v_cvt_u32_f32_e32 v0, v0
	s_nop 0
	v_readfirstlane_b32 s37, v0
	s_mul_i32 s36, s36, s37
	s_mul_hi_u32 s36, s37, s36
	s_add_i32 s37, s37, s36
	s_mul_hi_u32 s36, s3, s37
	s_mul_i32 s37, s36, s22
	s_sub_i32 s3, s3, s37
	s_add_i32 s40, s36, 1
	s_sub_i32 s37, s3, s22
	s_cmp_ge_u32 s3, s22
	s_cselect_b32 s36, s40, s36
	s_cselect_b32 s3, s37, s3
	s_add_i32 s37, s36, 1
	s_cmp_ge_u32 s3, s22
	s_cselect_b32 s3, s37, s36
	s_xor_b32 s3, s3, s23
	s_sub_i32 s36, s3, s23
	s_mul_i32 s3, s36, s11
	s_sub_i32 s2, s2, s3
	s_add_i32 s40, s9, s2

; #define PG8_STAGE(bufoff, gbase, voff) do { _Pragma("unroll") for (int _i = 0; _i < 2; ++_i) \
;         __builtin_amdgcn_global_load_lds((const unsigned*)((const char*)(gbase) + (voff)[_i]), (LAS unsigned*)(lds + (bufoff) + ldsw + _i * 8192), 16, 0, 0); } while (0)
; #define PG8_LDA(dst, b, h) do { _Pragma("unroll") for (int m = 0; m < NM; ++m) _Pragma("unroll") for (int k = 0; k < 2; ++k) dst[m][k] = *(const LAS bf16x8*)(lds + PG8_SA(b, h) + aoff + m * 2048 + k * 1024); } while (0)
; #define PG8_LDB(dst, b, h) do { _Pragma("unroll") for (int n = 0; n < 2; ++n) _Pragma("unroll") for (int k = 0; k < 2; ++k) dst[n][k] = *(const LAS bf16x8*)(lds + PG8_SB(b, h) + boff + n * 2048 + k * 1024); } while (0)
; #define PG8_MMA(ai, bj, At, Bt) do { __builtin_amdgcn_s_setprio(1); _Pragma("unroll") for (int m = 0; m < NM; ++m) _Pragma("unroll") for (int n = 0; n < 2; ++n) _Pragma("unroll") for (int k = 0; k < 2; ++k) \
;         acc[ai][bj][m][n] = __builtin_amdgcn_mfma_f32_16x16x32_bf16(Bt[n][k], At[m][k], acc[ai][bj][m][n], 0, 0, 0); __builtin_amdgcn_s_setprio(0); } while (0)
; #define PG8_WAIT_V(n) asm volatile("s_waitcnt vmcnt(" #n ")" ::: "memory")
; #define PG8_WAIT_L(n) asm volatile("s_waitcnt lgkmcnt(" #n ")" ::: "memory")
; #define PG8_BAR __builtin_amdgcn_s_barrier()
; #define PG8_SCHED __builtin_amdgcn_sched_barrier(0)
;     ...
;         for (int t = 0; t < nt; t += 2) {
;             const bool last = (t == nt - 2);
;             const char* a1 = cA + (size_t)(t + 1) * kstep;
;             const char* a2 = last ? nA : cA + (size_t)(t + 2) * kstep; const char* b2 = last ? nB : cB + (size_t)(t + 2) * kstep;
;             const char* a3 = a2 + kstep; const char* b3 = b2 + kstep;
;             if constexpr (SP2) {
;             PG8_LDB(B0, 0, 0); PG8_LDB(B1, 0, 1); PG8_SCHED; PG8_LDA(At, 0, 0); PG8_STAGE(PG8_SA(1, 1), a1 + hstepA, voffA);
;             PG8_WAIT_V(8); PG8_WAIT_L(0); PG8_BAR; PG8_MMA(0, 0, At, B0); PG8_MMA(0, 1, At, B1); PG8_BAR; PG8_SCHED;
;             PG8_LDA(At, 0, 1); PG8_STAGE(PG8_SB(0, 0), b2, voffB); PG8_STAGE(PG8_SB(0, 1), b2 + hstepB, voffB); PG8_STAGE(PG8_SA(0, 0), a2, voffA);
.LBB0_1783:
	v_add_u32_e32 v0, s64, v208
	ds_read_b128 v[130:133], v0
	ds_read_b128 v[134:137], v0 offset:1024
	ds_read_b128 v[138:141], v0 offset:2048
	ds_read_b128 v[142:145], v0 offset:3072
	v_add_u32_e32 v0, s70, v208
	ds_read_b128 v[146:149], v0
	ds_read_b128 v[150:153], v0 offset:1024
	ds_read_b128 v[154:157], v0 offset:2048
	ds_read_b128 v[158:161], v0 offset:3072
	s_add_u32 s14, s12, 0xfff80080
	s_addc_u32 s15, s13, -1
	s_cmp_eq_u32 vcc_lo, 28
	s_cselect_b32 s47, s2, s15
	s_cselect_b32 s46, s3, s14
	s_cselect_b32 s15, s9, s41
	s_cselect_b32 s14, s11, s37
	s_cselect_b32 s100, -1, 0
	s_andn2_b32 s100, s100, s101
	s_add_i32 m0, s73, 0xc000
	ds_read_b128 v[162:165], v209
	ds_read_b128 v[166:169], v209 offset:1024
	ds_read_b128 v[170:173], v209 offset:2048
	ds_read_b128 v[174:177], v209 offset:3072
	ds_read_b128 v[190:193], v209 offset:4096
	ds_read_b128 v[194:197], v209 offset:5120
	ds_read_b128 v[198:201], v209 offset:6144
	ds_read_b128 v[202:205], v209 offset:7168
	global_load_lds_dwordx4 v186, s[12:13]
	s_add_i32 m0, s73, 0xe000
	s_nop 0
	global_load_lds_dwordx4 v188, s[12:13]
	s_waitcnt vmcnt(8)
	s_waitcnt lgkmcnt(0)
	s_barrier
	s_setprio 1
	s_waitcnt lgkmcnt(0)
	v_mfma_f32_16x16x32_bf16 v[126:129], v[130:133], v[162:165], v[126:129]
	v_mfma_f32_16x16x32_bf16 v[94:97], v[138:141], v[162:165], v[94:97]
	v_mfma_f32_16x16x32_bf16 v[110:113], v[130:133], v[170:173], v[110:113]
	v_mfma_f32_16x16x32_bf16 v[70:73], v[138:141], v[170:173], v[70:73]
	v_mfma_f32_16x16x32_bf16 v[106:109], v[130:133], v[190:193], v[106:109]
	v_mfma_f32_16x16x32_bf16 v[66:69], v[138:141], v[190:193], v[66:69]
	v_mfma_f32_16x16x32_bf16 v[118:121], v[130:133], v[198:201], v[118:121]
	v_mfma_f32_16x16x32_bf16 v[86:89], v[138:141], v[198:201], v[86:89]
	v_mfma_f32_16x16x32_bf16 v[126:129], v[134:137], v[166:169], v[126:129]
	v_mfma_f32_16x16x32_bf16 v[94:97], v[142:145], v[166:169], v[94:97]
	v_mfma_f32_16x16x32_bf16 v[110:113], v[134:137], v[174:177], v[110:113]
	v_mfma_f32_16x16x32_bf16 v[70:73], v[142:145], v[174:177], v[70:73]
	v_mfma_f32_16x16x32_bf16 v[106:109], v[134:137], v[194:197], v[106:109]
	v_mfma_f32_16x16x32_bf16 v[66:69], v[142:145], v[194:197], v[66:69]
	v_mfma_f32_16x16x32_bf16 v[118:121], v[134:137], v[202:205], v[118:121]
	v_mfma_f32_16x16x32_bf16 v[86:89], v[142:145], v[202:205], v[86:89]
	s_setprio 0
	s_setprio 1
	v_mfma_f32_16x16x32_bf16 v[122:125], v[146:149], v[162:165], v[122:125]
	v_mfma_f32_16x16x32_bf16 v[90:93], v[154:157], v[162:165], v[90:93]
	v_mfma_f32_16x16x32_bf16 v[102:105], v[146:149], v[170:173], v[102:105]
	v_mfma_f32_16x16x32_bf16 v[62:65], v[154:157], v[170:173], v[62:65]
	v_mfma_f32_16x16x32_bf16 v[98:101], v[146:149], v[190:193], v[98:101]
	v_mfma_f32_16x16x32_bf16 v[58:61], v[154:157], v[190:193], v[58:61]
	v_mfma_f32_16x16x32_bf16 v[114:117], v[146:149], v[198:201], v[114:117]
	v_mfma_f32_16x16x32_bf16 v[82:85], v[154:157], v[198:201], v[82:85]
	v_mfma_f32_16x16x32_bf16 v[122:125], v[150:153], v[166:169], v[122:125]
	v_mfma_f32_16x16x32_bf16 v[90:93], v[158:161], v[166:169], v[90:93]
	v_mfma_f32_16x16x32_bf16 v[102:105], v[150:153], v[174:177], v[102:105]
	v_mfma_f32_16x16x32_bf16 v[62:65], v[158:161], v[174:177], v[62:65]
	v_mfma_f32_16x16x32_bf16 v[98:101], v[150:153], v[194:197], v[98:101]
	v_mfma_f32_16x16x32_bf16 v[58:61], v[158:161], v[194:197], v[58:61]
	v_mfma_f32_16x16x32_bf16 v[114:117], v[150:153], v[202:205], v[114:117]
	v_mfma_f32_16x16x32_bf16 v[82:85], v[158:161], v[202:205], v[82:85]
	s_setprio 0
	s_barrier
	s_mov_b32 m0, s68
	s_add_u32 s22, s14, 0x80000
	s_addc_u32 s23, s15, 0
	ds_read_b128 v[162:165], v209 offset:16384
	ds_read_b128 v[166:169], v209 offset:17408
	ds_read_b128 v[170:173], v209 offset:18432
	ds_read_b128 v[174:177], v209 offset:19456
	ds_read_b128 v[190:193], v209 offset:20480
	ds_read_b128 v[194:197], v209 offset:21504
	ds_read_b128 v[198:201], v209 offset:22528
	ds_read_b128 v[202:205], v209 offset:23552
	s_cmp_lg_u32 s100, 0
	s_cbranch_scc1 .Ltl_up_0s
	global_load_lds_dwordx4 v180, s[14:15]
	s_mov_b32 m0, s69
	s_nop 0
	global_load_lds_dwordx4 v184, s[14:15]
	s_mov_b32 m0, s71
	s_nop 0
	global_load_lds_dwordx4 v180, s[22:23]
	s_mov_b32 m0, s72
	s_nop 0
	global_load_lds_dwordx4 v184, s[22:23]
	s_mov_b32 m0, s73
	s_nop 0
	global_load_lds_dwordx4 v178, s[46:47]
	s_mov_b32 m0, s74
	s_nop 0
	global_load_lds_dwordx4 v182, s[46:47]
	s_waitcnt vmcnt(8)
	s_branch .Ltl_up_0d

; #define PG8_STAGE(bufoff, gbase, voff) do { _Pragma("unroll") for (int _i = 0; _i < 2; ++_i) \
;         __builtin_amdgcn_global_load_lds((const unsigned*)((const char*)(gbase) + (voff)[_i]), (LAS unsigned*)(lds + (bufoff) + ldsw + _i * 8192), 16, 0, 0); } while (0)
; #define PG8_LDA(dst, b, h) do { _Pragma("unroll") for (int m = 0; m < NM; ++m) _Pragma("unroll") for (int k = 0; k < 2; ++k) dst[m][k] = *(const LAS bf16x8*)(lds + PG8_SA(b, h) + aoff + m * 2048 + k * 1024); } while (0)
; #define PG8_LDB(dst, b, h) do { _Pragma("unroll") for (int n = 0; n < 2; ++n) _Pragma("unroll") for (int k = 0; k < 2; ++k) dst[n][k] = *(const LAS bf16x8*)(lds + PG8_SB(b, h) + boff + n * 2048 + k * 1024); } while (0)
; #define PG8_MMA(ai, bj, At, Bt) do { __builtin_amdgcn_s_setprio(1); _Pragma("unroll") for (int m = 0; m < NM; ++m) _Pragma("unroll") for (int n = 0; n < 2; ++n) _Pragma("unroll") for (int k = 0; k < 2; ++k) \
;         acc[ai][bj][m][n] = __builtin_amdgcn_mfma_f32_16x16x32_bf16(Bt[n][k], At[m][k], acc[ai][bj][m][n], 0, 0, 0); __builtin_amdgcn_s_setprio(0); } while (0)
; #define PG8_WAIT_V(n) asm volatile("s_waitcnt vmcnt(" #n ")" ::: "memory")
; #define PG8_WAIT_L(n) asm volatile("s_waitcnt lgkmcnt(" #n ")" ::: "memory")
; #define PG8_BAR __builtin_amdgcn_s_barrier()
; #define PG8_SCHED __builtin_amdgcn_sched_barrier(0)
;     ...
;             PG8_LDA(At, 0, 1); PG8_STAGE(PG8_SB(0, 0), b2, voffB); PG8_STAGE(PG8_SB(0, 1), b2 + hstepB, voffB); PG8_STAGE(PG8_SA(0, 0), a2, voffA);
;             PG8_WAIT_V(8); PG8_WAIT_L(0); PG8_BAR; PG8_MMA(1, 0, At, B0); PG8_MMA(1, 1, At, B1); PG8_BAR; PG8_SCHED;
;             PG8_LDB(B0, 1, 0); PG8_LDB(B1, 1, 1); PG8_SCHED; PG8_LDA(At, 1, 0); PG8_STAGE(PG8_SA(0, 1), a2 + hstepA, voffA);
.Ltl_up_0d:
	s_waitcnt lgkmcnt(0)
	s_barrier
	s_setprio 1
	s_waitcnt lgkmcnt(0)
	v_mfma_f32_16x16x32_bf16 v[46:49], v[130:133], v[162:165], v[46:49]
	v_mfma_f32_16x16x32_bf16 v[22:25], v[138:141], v[162:165], v[22:25]
	v_mfma_f32_16x16x32_bf16 v[42:45], v[130:133], v[170:173], v[42:45]
	v_mfma_f32_16x16x32_bf16 v[18:21], v[138:141], v[170:173], v[18:21]
	v_mfma_f32_16x16x32_bf16 v[38:41], v[130:133], v[190:193], v[38:41]
	v_mfma_f32_16x16x32_bf16 v[14:17], v[138:141], v[190:193], v[14:17]
	v_mfma_f32_16x16x32_bf16 v[78:81], v[130:133], v[198:201], v[78:81]
	v_mfma_f32_16x16x32_bf16 v[54:57], v[138:141], v[198:201], v[54:57]
	v_mfma_f32_16x16x32_bf16 v[46:49], v[134:137], v[166:169], v[46:49]
	v_mfma_f32_16x16x32_bf16 v[22:25], v[142:145], v[166:169], v[22:25]
	v_mfma_f32_16x16x32_bf16 v[42:45], v[134:137], v[174:177], v[42:45]
	v_mfma_f32_16x16x32_bf16 v[18:21], v[142:145], v[174:177], v[18:21]
	v_mfma_f32_16x16x32_bf16 v[38:41], v[134:137], v[194:197], v[38:41]
	v_mfma_f32_16x16x32_bf16 v[14:17], v[142:145], v[194:197], v[14:17]
	v_mfma_f32_16x16x32_bf16 v[78:81], v[134:137], v[202:205], v[78:81]
	v_mfma_f32_16x16x32_bf16 v[54:57], v[142:145], v[202:205], v[54:57]
	s_setprio 0
	s_setprio 1
	v_mfma_f32_16x16x32_bf16 v[34:37], v[146:149], v[162:165], v[34:37]
	v_mfma_f32_16x16x32_bf16 v[10:13], v[154:157], v[162:165], v[10:13]
	v_mfma_f32_16x16x32_bf16 v[30:33], v[146:149], v[170:173], v[30:33]
	v_mfma_f32_16x16x32_bf16 v[6:9], v[154:157], v[170:173], v[6:9]
	v_mfma_f32_16x16x32_bf16 v[26:29], v[146:149], v[190:193], v[26:29]
	v_mfma_f32_16x16x32_bf16 v[2:5], v[154:157], v[190:193], v[2:5]
	v_mfma_f32_16x16x32_bf16 v[74:77], v[146:149], v[198:201], v[74:77]
	v_mfma_f32_16x16x32_bf16 v[50:53], v[154:157], v[198:201], v[50:53]
	v_mfma_f32_16x16x32_bf16 v[34:37], v[150:153], v[166:169], v[34:37]
	v_mfma_f32_16x16x32_bf16 v[10:13], v[158:161], v[166:169], v[10:13]
	v_mfma_f32_16x16x32_bf16 v[30:33], v[150:153], v[174:177], v[30:33]
	v_mfma_f32_16x16x32_bf16 v[6:9], v[158:161], v[174:177], v[6:9]
	v_mfma_f32_16x16x32_bf16 v[26:29], v[150:153], v[194:197], v[26:29]
	v_mfma_f32_16x16x32_bf16 v[2:5], v[158:161], v[194:197], v[2:5]
	v_mfma_f32_16x16x32_bf16 v[74:77], v[150:153], v[202:205], v[74:77]
	v_mfma_f32_16x16x32_bf16 v[50:53], v[158:161], v[202:205], v[50:53]
	s_setprio 0
	s_barrier
	v_add_u32_e32 v0, s94, v208
	ds_read_b128 v[130:133], v0
	ds_read_b128 v[134:137], v0 offset:1024
	ds_read_b128 v[138:141], v0 offset:2048
	ds_read_b128 v[142:145], v0 offset:3072
	v_add_u32_e32 v0, s62, v208
	ds_read_b128 v[146:149], v0
	ds_read_b128 v[150:153], v0 offset:1024
	ds_read_b128 v[154:157], v0 offset:2048
	ds_read_b128 v[158:161], v0 offset:3072
	s_add_u32 s22, s46, 0x80000
	s_addc_u32 s23, s47, 0
	s_mov_b32 m0, s75
	ds_read_b128 v[162:165], v209 offset:32768
	ds_read_b128 v[166:169], v209 offset:33792
	ds_read_b128 v[170:173], v209 offset:34816
	ds_read_b128 v[174:177], v209 offset:35840
	ds_read_b128 v[190:193], v209 offset:36864
	ds_read_b128 v[194:197], v209 offset:37888
	ds_read_b128 v[198:201], v209 offset:38912
	ds_read_b128 v[202:205], v209 offset:39936
	s_cmp_lg_u32 s100, 0
	s_cbranch_scc1 .Ltl_up_1s
	global_load_lds_dwordx4 v178, s[22:23]
	s_mov_b32 m0, s80
	s_nop 0
	global_load_lds_dwordx4 v182, s[22:23]
	s_waitcnt vmcnt(8)
	s_branch .Ltl_up_1d

; #define PG8_STAGE(bufoff, gbase, voff) do { _Pragma("unroll") for (int _i = 0; _i < 2; ++_i) \
;         __builtin_amdgcn_global_load_lds((const unsigned*)((const char*)(gbase) + (voff)[_i]), (LAS unsigned*)(lds + (bufoff) + ldsw + _i * 8192), 16, 0, 0); } while (0)
; #define PG8_LDA(dst, b, h) do { _Pragma("unroll") for (int m = 0; m < NM; ++m) _Pragma("unroll") for (int k = 0; k < 2; ++k) dst[m][k] = *(const LAS bf16x8*)(lds + PG8_SA(b, h) + aoff + m * 2048 + k * 1024); } while (0)
; #define PG8_LDB(dst, b, h) do { _Pragma("unroll") for (int n = 0; n < 2; ++n) _Pragma("unroll") for (int k = 0; k < 2; ++k) dst[n][k] = *(const LAS bf16x8*)(lds + PG8_SB(b, h) + boff + n * 2048 + k * 1024); } while (0)
; #define PG8_MMA(ai, bj, At, Bt) do { __builtin_amdgcn_s_setprio(1); _Pragma("unroll") for (int m = 0; m < NM; ++m) _Pragma("unroll") for (int n = 0; n < 2; ++n) _Pragma("unroll") for (int k = 0; k < 2; ++k) \
;         acc[ai][bj][m][n] = __builtin_amdgcn_mfma_f32_16x16x32_bf16(Bt[n][k], At[m][k], acc[ai][bj][m][n], 0, 0, 0); __builtin_amdgcn_s_setprio(0); } while (0)
; #define PG8_WAIT_V(n) asm volatile("s_waitcnt vmcnt(" #n ")" ::: "memory")
; #define PG8_WAIT_L(n) asm volatile("s_waitcnt lgkmcnt(" #n ")" ::: "memory")
; #define PG8_BAR __builtin_amdgcn_s_barrier()
; #define PG8_SCHED __builtin_amdgcn_sched_barrier(0)
;     ...
;             PG8_LDB(B0, 1, 0); PG8_LDB(B1, 1, 1); PG8_SCHED; PG8_LDA(At, 1, 0); PG8_STAGE(PG8_SA(0, 1), a2 + hstepA, voffA);
;             PG8_WAIT_V(8); PG8_WAIT_L(0); PG8_BAR; PG8_MMA(0, 0, At, B0); PG8_MMA(0, 1, At, B1); PG8_BAR; PG8_SCHED;
;             PG8_LDA(At, 1, 1); PG8_STAGE(PG8_SB(1, 0), b3, voffB); PG8_STAGE(PG8_SB(1, 1), b3 + hstepB, voffB); PG8_STAGE(PG8_SA(1, 0), a3, voffA);
.Ltl_up_1d:
	s_waitcnt lgkmcnt(0)
	s_barrier
	s_setprio 1
	s_waitcnt lgkmcnt(0)
	v_mfma_f32_16x16x32_bf16 v[126:129], v[130:133], v[162:165], v[126:129]
	v_mfma_f32_16x16x32_bf16 v[94:97], v[138:141], v[162:165], v[94:97]
	v_mfma_f32_16x16x32_bf16 v[110:113], v[130:133], v[170:173], v[110:113]
	v_mfma_f32_16x16x32_bf16 v[70:73], v[138:141], v[170:173], v[70:73]
	v_mfma_f32_16x16x32_bf16 v[106:109], v[130:133], v[190:193], v[106:109]
	v_mfma_f32_16x16x32_bf16 v[66:69], v[138:141], v[190:193], v[66:69]
	v_mfma_f32_16x16x32_bf16 v[118:121], v[130:133], v[198:201], v[118:121]
	v_mfma_f32_16x16x32_bf16 v[86:89], v[138:141], v[198:201], v[86:89]
	v_mfma_f32_16x16x32_bf16 v[126:129], v[134:137], v[166:169], v[126:129]
	v_mfma_f32_16x16x32_bf16 v[94:97], v[142:145], v[166:169], v[94:97]
	v_mfma_f32_16x16x32_bf16 v[110:113], v[134:137], v[174:177], v[110:113]
	v_mfma_f32_16x16x32_bf16 v[70:73], v[142:145], v[174:177], v[70:73]
	v_mfma_f32_16x16x32_bf16 v[106:109], v[134:137], v[194:197], v[106:109]
	v_mfma_f32_16x16x32_bf16 v[66:69], v[142:145], v[194:197], v[66:69]
	v_mfma_f32_16x16x32_bf16 v[118:121], v[134:137], v[202:205], v[118:121]
	v_mfma_f32_16x16x32_bf16 v[86:89], v[142:145], v[202:205], v[86:89]
	s_setprio 0
	s_setprio 1
	v_mfma_f32_16x16x32_bf16 v[122:125], v[146:149], v[162:165], v[122:125]
	v_mfma_f32_16x16x32_bf16 v[90:93], v[154:157], v[162:165], v[90:93]
	v_mfma_f32_16x16x32_bf16 v[102:105], v[146:149], v[170:173], v[102:105]
	v_mfma_f32_16x16x32_bf16 v[62:65], v[154:157], v[170:173], v[62:65]
	v_mfma_f32_16x16x32_bf16 v[98:101], v[146:149], v[190:193], v[98:101]
	v_mfma_f32_16x16x32_bf16 v[58:61], v[154:157], v[190:193], v[58:61]
	v_mfma_f32_16x16x32_bf16 v[114:117], v[146:149], v[198:201], v[114:117]
	v_mfma_f32_16x16x32_bf16 v[82:85], v[154:157], v[198:201], v[82:85]
	v_mfma_f32_16x16x32_bf16 v[122:125], v[150:153], v[166:169], v[122:125]
	v_mfma_f32_16x16x32_bf16 v[90:93], v[158:161], v[166:169], v[90:93]
	v_mfma_f32_16x16x32_bf16 v[102:105], v[150:153], v[174:177], v[102:105]
	v_mfma_f32_16x16x32_bf16 v[62:65], v[158:161], v[174:177], v[62:65]
	v_mfma_f32_16x16x32_bf16 v[98:101], v[150:153], v[194:197], v[98:101]
	v_mfma_f32_16x16x32_bf16 v[58:61], v[158:161], v[194:197], v[58:61]
	v_mfma_f32_16x16x32_bf16 v[114:117], v[150:153], v[202:205], v[114:117]
	v_mfma_f32_16x16x32_bf16 v[82:85], v[158:161], v[202:205], v[82:85]
	s_setprio 0
	s_barrier
	s_mov_b32 m0, s51
	s_add_u32 s22, s14, s66
	s_addc_u32 s23, s15, s67
	s_add_u32 s14, s14, 0x80080
	s_addc_u32 s15, s15, 0
	ds_read_b128 v[162:165], v209 offset:49152
	ds_read_b128 v[166:169], v209 offset:50176
	ds_read_b128 v[170:173], v209 offset:51200
	ds_read_b128 v[174:177], v209 offset:52224
	ds_read_b128 v[190:193], v209 offset:53248
	ds_read_b128 v[194:197], v209 offset:54272
	ds_read_b128 v[198:201], v209 offset:55296
	ds_read_b128 v[202:205], v209 offset:56320
	s_cmp_lg_u32 s100, 0
	s_cbranch_scc1 .Ltl_up_2s
	global_load_lds_dwordx4 v180, s[22:23]
	s_mov_b32 m0, s95
	s_nop 0
	global_load_lds_dwordx4 v184, s[22:23]
	s_add_u32 s22, s46, s66
	s_addc_u32 s23, s47, s67
	s_mov_b32 m0, s50
	s_nop 0
	global_load_lds_dwordx4 v180, s[14:15]
	s_mov_b32 m0, s49
	s_nop 0
	global_load_lds_dwordx4 v184, s[14:15]
	s_mov_b32 m0, s58
	s_nop 0
	global_load_lds_dwordx4 v178, s[22:23]
	s_mov_b32 m0, s59
	s_nop 0
	global_load_lds_dwordx4 v182, s[22:23]
	s_waitcnt vmcnt(8)
	s_branch .Ltl_up_2d

; #define PG8_STAGE(bufoff, gbase, voff) do { _Pragma("unroll") for (int _i = 0; _i < 2; ++_i) \
;         __builtin_amdgcn_global_load_lds((const unsigned*)((const char*)(gbase) + (voff)[_i]), (LAS unsigned*)(lds + (bufoff) + ldsw + _i * 8192), 16, 0, 0); } while (0)
; #define PG8_LDA(dst, b, h) do { _Pragma("unroll") for (int m = 0; m < NM; ++m) _Pragma("unroll") for (int k = 0; k < 2; ++k) dst[m][k] = *(const LAS bf16x8*)(lds + PG8_SA(b, h) + aoff + m * 2048 + k * 1024); } while (0)
; #define PG8_MMA(ai, bj, At, Bt) do { __builtin_amdgcn_s_setprio(1); _Pragma("unroll") for (int m = 0; m < NM; ++m) _Pragma("unroll") for (int n = 0; n < 2; ++n) _Pragma("unroll") for (int k = 0; k < 2; ++k) \
;         acc[ai][bj][m][n] = __builtin_amdgcn_mfma_f32_16x16x32_bf16(Bt[n][k], At[m][k], acc[ai][bj][m][n], 0, 0, 0); __builtin_amdgcn_s_setprio(0); } while (0)
; #define PG8_WAIT_V(n) asm volatile("s_waitcnt vmcnt(" #n ")" ::: "memory")
; #define PG8_WAIT_L(n) asm volatile("s_waitcnt lgkmcnt(" #n ")" ::: "memory")
; #define PG8_BAR __builtin_amdgcn_s_barrier()
; #define PG8_SCHED __builtin_amdgcn_sched_barrier(0)
;     ...
;             PG8_WAIT_V(8); PG8_WAIT_L(0); PG8_BAR; PG8_MMA(0, 0, At, B0); PG8_MMA(0, 1, At, B1); PG8_BAR; PG8_SCHED;
;             PG8_LDA(At, 1, 1); PG8_STAGE(PG8_SB(1, 0), b3, voffB); PG8_STAGE(PG8_SB(1, 1), b3 + hstepB, voffB); PG8_STAGE(PG8_SA(1, 0), a3, voffA);
;             PG8_WAIT_V(8); PG8_WAIT_L(0); PG8_BAR; PG8_MMA(1, 0, At, B0); PG8_MMA(1, 1, At, B1); PG8_BAR; PG8_SCHED;
;     ...
;         if constexpr (ALIGN_EPI) { if (wr == 0) PG8_BAR; }
.Ltl_up_2d:
	s_waitcnt lgkmcnt(0)
	s_barrier
	s_setprio 1
	s_waitcnt lgkmcnt(0)
	v_mfma_f32_16x16x32_bf16 v[46:49], v[130:133], v[162:165], v[46:49]
	v_mfma_f32_16x16x32_bf16 v[22:25], v[138:141], v[162:165], v[22:25]
	v_mfma_f32_16x16x32_bf16 v[42:45], v[130:133], v[170:173], v[42:45]
	v_mfma_f32_16x16x32_bf16 v[18:21], v[138:141], v[170:173], v[18:21]
	v_mfma_f32_16x16x32_bf16 v[38:41], v[130:133], v[190:193], v[38:41]
	v_mfma_f32_16x16x32_bf16 v[14:17], v[138:141], v[190:193], v[14:17]
	v_mfma_f32_16x16x32_bf16 v[78:81], v[130:133], v[198:201], v[78:81]
	v_mfma_f32_16x16x32_bf16 v[54:57], v[138:141], v[198:201], v[54:57]
	v_mfma_f32_16x16x32_bf16 v[46:49], v[134:137], v[166:169], v[46:49]
	v_mfma_f32_16x16x32_bf16 v[22:25], v[142:145], v[166:169], v[22:25]
	v_mfma_f32_16x16x32_bf16 v[42:45], v[134:137], v[174:177], v[42:45]
	v_mfma_f32_16x16x32_bf16 v[18:21], v[142:145], v[174:177], v[18:21]
	v_mfma_f32_16x16x32_bf16 v[38:41], v[134:137], v[194:197], v[38:41]
	v_mfma_f32_16x16x32_bf16 v[14:17], v[142:145], v[194:197], v[14:17]
	v_mfma_f32_16x16x32_bf16 v[78:81], v[134:137], v[202:205], v[78:81]
	v_mfma_f32_16x16x32_bf16 v[54:57], v[142:145], v[202:205], v[54:57]
	s_setprio 0
	s_setprio 1
	v_mfma_f32_16x16x32_bf16 v[34:37], v[146:149], v[162:165], v[34:37]
	v_mfma_f32_16x16x32_bf16 v[10:13], v[154:157], v[162:165], v[10:13]
	v_mfma_f32_16x16x32_bf16 v[30:33], v[146:149], v[170:173], v[30:33]
	v_mfma_f32_16x16x32_bf16 v[6:9], v[154:157], v[170:173], v[6:9]
	v_mfma_f32_16x16x32_bf16 v[26:29], v[146:149], v[190:193], v[26:29]
	v_mfma_f32_16x16x32_bf16 v[2:5], v[154:157], v[190:193], v[2:5]
	v_mfma_f32_16x16x32_bf16 v[74:77], v[146:149], v[198:201], v[74:77]
	v_mfma_f32_16x16x32_bf16 v[50:53], v[154:157], v[198:201], v[50:53]
	v_mfma_f32_16x16x32_bf16 v[34:37], v[150:153], v[166:169], v[34:37]
	v_mfma_f32_16x16x32_bf16 v[10:13], v[158:161], v[166:169], v[10:13]
	v_mfma_f32_16x16x32_bf16 v[30:33], v[150:153], v[174:177], v[30:33]
	v_mfma_f32_16x16x32_bf16 v[6:9], v[158:161], v[174:177], v[6:9]
	v_mfma_f32_16x16x32_bf16 v[26:29], v[150:153], v[194:197], v[26:29]
	v_mfma_f32_16x16x32_bf16 v[2:5], v[158:161], v[194:197], v[2:5]
	v_mfma_f32_16x16x32_bf16 v[74:77], v[150:153], v[202:205], v[74:77]
	v_mfma_f32_16x16x32_bf16 v[50:53], v[158:161], v[202:205], v[50:53]
	s_setprio 0
	s_barrier
	s_add_i32 vcc_lo, vcc_lo, 2
	s_add_u32 s12, s12, 0x100
	s_addc_u32 s13, s13, 0
	s_add_u32 s37, s37, 0x100
	s_addc_u32 s41, s41, 0
	s_cmp_gt_u32 vcc_lo, 29
	s_cbranch_scc0 .LBB0_1783
	s_and_b64 vcc, exec, s[24:25]
	s_cbranch_vccz .LBB0_1786
	s_barrier

;     __device__ __forceinline__ size_t aoff(const Unit& u) const { return (size_t)u.pm * bm * lda * 2; }
;     __device__ __forceinline__ size_t boff(const Unit& u) const { return (size_t)u.pn * BM * ldb * 2; }
;     __device__ __forceinline__ size_t aoff(const Unit& u) const { return ((size_t)u.pm * BM * lda + (size_t)u.pn * akoff) * 2; }
;     __device__ __forceinline__ size_t boff(const Unit& u) const { return (size_t)u.pn * BM * ldb * 2; }
;     __device__ __forceinline__ size_t aoff(const Unit& u) const { return ((size_t)u.pm * BM * lda + (size_t)(u.pn >> 1) * akoff) * 2; }
;     __device__ __forceinline__ size_t boff(const Unit& u) const { return (size_t)u.pn * BM * ldb * 2; }
;     __device__ bool next(int i, Unit& u) const {
;         const long L = (long)i * G + c; if (L >= nwg) return false;
;         int wgid = (int)L; { const int q = nwg / NXCD, r = nwg % NXCD, xcd = wgid % NXCD, off = wgid / NXCD; wgid = (xcd < r ? xcd * (q + 1) : r * (q + 1) + (xcd - r) * q) + off; }
;         const int nig = WGM * nN, gid = wgid / nig, fm = gid * WGM, gsz = (nM - fm) < WGM ? (nM - fm) : WGM;
;         u.pm = fm + ((wgid % nig) % gsz); u.pn = (wgid % nig) / gsz; return true;
;     }
;     ...
;         const bool has_next = S.next(ui + 1, nxt);
;         const char* nA = has_next ? (const char*)g.A + S.aoff(nxt) : cA; const char* nB = has_next ? (const char*)g.Bt + S.boff(nxt) : cB;
.LBB0_2151:
	s_add_i32 s54, s54, 1
	s_mul_i32 s2, s54, s48
	s_mul_hi_u32 s3, s54, s53
	s_add_i32 s3, s3, s2
	s_mul_i32 s2, s54, s53
	v_readlane_b32 s4, v255, 29
	s_add_u32 s2, s2, s4
	s_addc_u32 s3, s3, s49
	v_mov_b64_e32 v[2:3], 0x300
	v_cmp_lt_i64_e64 s[6:7], s[2:3], v[2:3]
	v_mov_b64_e32 v[2:3], 0x2ff
	v_cmp_gt_i64_e32 vcc, s[2:3], v[2:3]
	s_nop 3
	s_mov_b32 s101, s6
	s_cbranch_vccnz .LBB0_2153
	s_ashr_i32 s3, s2, 31
	s_lshr_b32 s3, s3, 29
	s_add_i32 s3, s2, s3
	s_ashr_i32 s4, s3, 3
	s_and_b32 s3, s3, -8
	s_sub_i32 s2, s2, s3
	s_cmp_lt_i32 s2, 0
	s_movk_i32 s3, 0x61
	s_cselect_b32 s3, s3, 0x60
	s_mul_i32 s2, s2, s3
	s_add_i32 s2, s2, s4
	s_ashr_i32 s3, s2, 31
	s_lshr_b32 s3, s3, 26
	s_add_i32 s3, s2, s3
	s_ashr_i32 s4, s3, 6
	s_lshl_b32 s4, s4, 3
	s_sub_i32 s5, 0x60, s4
	s_min_i32 s5, s5, 8
	s_abs_i32 s12, s5
	v_cvt_f32_u32_e32 v2, s12
	s_sub_i32 s18, 0, s12
	s_andn2_b32 s3, s3, 63
	s_sub_i32 s2, s2, s3
	v_rcp_iflag_f32_e32 v2, v2
	s_abs_i32 s3, s2
	s_xor_b32 s13, s2, s5
	s_ashr_i32 s13, s13, 31
	v_mul_f32_e32 v2, 0x4f7ffffe, v2
	v_cvt_u32_f32_e32 v2, v2
	s_nop 0
	v_readfirstlane_b32 s19, v2
	s_mul_i32 s18, s18, s19
	s_mul_hi_u32 s18, s19, s18
	s_add_i32 s19, s19, s18
	s_mul_hi_u32 s18, s3, s19
	s_mul_i32 s19, s18, s12
	s_sub_i32 s3, s3, s19
	s_add_i32 s20, s18, 1
	s_sub_i32 s19, s3, s12
	s_cmp_ge_u32 s3, s12
	s_cselect_b32 s18, s20, s18
	s_cselect_b32 s3, s19, s3
	s_add_i32 s19, s18, 1
	s_cmp_ge_u32 s3, s12
	s_cselect_b32 s3, s19, s18
	s_xor_b32 s3, s3, s13
	s_sub_i32 s56, s3, s13
	s_mul_i32 s3, s56, s5
	s_sub_i32 s2, s2, s3
	s_add_i32 s57, s4, s2

; #define PG8_STAGE(bufoff, gbase, voff) do { _Pragma("unroll") for (int _i = 0; _i < 2; ++_i) \
;         __builtin_amdgcn_global_load_lds((const unsigned*)((const char*)(gbase) + (voff)[_i]), (LAS unsigned*)(lds + (bufoff) + ldsw + _i * 8192), 16, 0, 0); } while (0)
; #define PG8_LDA(dst, b, h) do { _Pragma("unroll") for (int m = 0; m < NM; ++m) _Pragma("unroll") for (int k = 0; k < 2; ++k) dst[m][k] = *(const LAS bf16x8*)(lds + PG8_SA(b, h) + aoff + m * 2048 + k * 1024); } while (0)
; #define PG8_LDB(dst, b, h) do { _Pragma("unroll") for (int n = 0; n < 2; ++n) _Pragma("unroll") for (int k = 0; k < 2; ++k) dst[n][k] = *(const LAS bf16x8*)(lds + PG8_SB(b, h) + boff + n * 2048 + k * 1024); } while (0)
; #define PG8_MMA(ai, bj, At, Bt) do { __builtin_amdgcn_s_setprio(1); _Pragma("unroll") for (int m = 0; m < NM; ++m) _Pragma("unroll") for (int n = 0; n < 2; ++n) _Pragma("unroll") for (int k = 0; k < 2; ++k) \
;         acc[ai][bj][m][n] = __builtin_amdgcn_mfma_f32_16x16x32_bf16(Bt[n][k], At[m][k], acc[ai][bj][m][n], 0, 0, 0); __builtin_amdgcn_s_setprio(0); } while (0)
; #define PG8_WAIT_V(n) asm volatile("s_waitcnt vmcnt(" #n ")" ::: "memory")
; #define PG8_WAIT_L(n) asm volatile("s_waitcnt lgkmcnt(" #n ")" ::: "memory")
; #define PG8_BAR __builtin_amdgcn_s_barrier()
; #define PG8_SCHED __builtin_amdgcn_sched_barrier(0)
;     ...
;         for (int t = 0; t < nt; t += 2) {
;             const bool last = (t == nt - 2);
;             const char* a1 = cA + (size_t)(t + 1) * kstep;
;             const char* a2 = last ? nA : cA + (size_t)(t + 2) * kstep; const char* b2 = last ? nB : cB + (size_t)(t + 2) * kstep;
;             const char* a3 = a2 + kstep; const char* b3 = b2 + kstep;
;             if constexpr (SP2) {
;             PG8_LDB(B0, 0, 0); PG8_LDB(B1, 0, 1); PG8_SCHED; PG8_LDA(At, 0, 0); PG8_STAGE(PG8_SA(1, 1), a1 + hstepA, voffA);
;             PG8_WAIT_V(8); PG8_WAIT_L(0); PG8_BAR; PG8_MMA(0, 0, At, B0); PG8_MMA(0, 1, At, B1); PG8_BAR; PG8_SCHED;
.LBB0_2158:
	v_add_u32_e32 v102, s26, v166
	v_add_u32_e32 v126, s29, v166
	ds_read_b128 v[90:93], v102
	ds_read_b128 v[94:97], v102 offset:1024
	ds_read_b128 v[98:101], v102 offset:2048
	ds_read_b128 v[102:105], v102 offset:3072
	ds_read_b128 v[114:117], v126
	ds_read_b128 v[118:121], v126 offset:1024
	ds_read_b128 v[122:125], v126 offset:2048
	ds_read_b128 v[126:129], v126 offset:3072
	s_add_u32 s16, s14, 0x100
	s_addc_u32 s17, s15, 0
	s_cmpk_eq_i32 s60, 0x54
	s_cselect_b32 s21, s7, s17
	s_cselect_b32 s20, s6, s16
	s_cselect_b32 s19, s13, s3
	s_cselect_b32 s18, s12, s2
	s_cselect_b32 s100, -1, 0
	s_andn2_b32 s100, s100, s101
	s_add_i32 m0, s34, 0xc000
	ds_read_b128 v[130:133], v167
	ds_read_b128 v[134:137], v167 offset:1024
	ds_read_b128 v[138:141], v167 offset:2048
	ds_read_b128 v[152:155], v167 offset:3072
	ds_read_b128 v[156:159], v167 offset:4096
	ds_read_b128 v[160:163], v167 offset:5120
	global_load_lds_dwordx4 v148, s[14:15]
	s_add_i32 m0, s34, 0xe000
	s_nop 0
	s_and_b64 vcc, exec, s[8:9]
	s_cbranch_vccz .Lnm3d_skip0
	global_load_lds_dwordx4 v150, s[14:15]
	s_waitcnt vmcnt(8)
	s_branch .Lnm3d_done0

; #define PG8_STAGE(bufoff, gbase, voff) do { _Pragma("unroll") for (int _i = 0; _i < 2; ++_i) \
;         __builtin_amdgcn_global_load_lds((const unsigned*)((const char*)(gbase) + (voff)[_i]), (LAS unsigned*)(lds + (bufoff) + ldsw + _i * 8192), 16, 0, 0); } while (0)
; #define PG8_LDA(dst, b, h) do { _Pragma("unroll") for (int m = 0; m < NM; ++m) _Pragma("unroll") for (int k = 0; k < 2; ++k) dst[m][k] = *(const LAS bf16x8*)(lds + PG8_SA(b, h) + aoff + m * 2048 + k * 1024); } while (0)
; #define PG8_LDB(dst, b, h) do { _Pragma("unroll") for (int n = 0; n < 2; ++n) _Pragma("unroll") for (int k = 0; k < 2; ++k) dst[n][k] = *(const LAS bf16x8*)(lds + PG8_SB(b, h) + boff + n * 2048 + k * 1024); } while (0)
; #define PG8_MMA(ai, bj, At, Bt) do { __builtin_amdgcn_s_setprio(1); _Pragma("unroll") for (int m = 0; m < NM; ++m) _Pragma("unroll") for (int n = 0; n < 2; ++n) _Pragma("unroll") for (int k = 0; k < 2; ++k) \
;         acc[ai][bj][m][n] = __builtin_amdgcn_mfma_f32_16x16x32_bf16(Bt[n][k], At[m][k], acc[ai][bj][m][n], 0, 0, 0); __builtin_amdgcn_s_setprio(0); } while (0)
; #define PG8_WAIT_V(n) asm volatile("s_waitcnt vmcnt(" #n ")" ::: "memory")
; #define PG8_WAIT_L(n) asm volatile("s_waitcnt lgkmcnt(" #n ")" ::: "memory")
; #define PG8_BAR __builtin_amdgcn_s_barrier()
; #define PG8_SCHED __builtin_amdgcn_sched_barrier(0)
;     ...
;             PG8_WAIT_V(8); PG8_WAIT_L(0); PG8_BAR; PG8_MMA(0, 0, At, B0); PG8_MMA(0, 1, At, B1); PG8_BAR; PG8_SCHED;
;             PG8_LDA(At, 0, 1); PG8_STAGE(PG8_SB(0, 0), b2, voffB); PG8_STAGE(PG8_SB(0, 1), b2 + hstepB, voffB); PG8_STAGE(PG8_SA(0, 0), a2, voffA);
;             PG8_WAIT_V(8); PG8_WAIT_L(0); PG8_BAR; PG8_MMA(1, 0, At, B0); PG8_MMA(1, 1, At, B1); PG8_BAR; PG8_SCHED;
;             PG8_LDB(B0, 1, 0); PG8_LDB(B1, 1, 1); PG8_SCHED; PG8_LDA(At, 1, 0); PG8_STAGE(PG8_SA(0, 1), a2 + hstepA, voffA);
;             PG8_WAIT_V(8); PG8_WAIT_L(0); PG8_BAR; PG8_MMA(0, 0, At, B0); PG8_MMA(0, 1, At, B1); PG8_BAR; PG8_SCHED;
.Lnm3d_done0:
	s_waitcnt lgkmcnt(0)
	s_barrier
	s_setprio 1
	s_waitcnt lgkmcnt(0)
	v_mfma_f32_16x16x32_bf16 v[110:113], v[90:93], v[130:133], v[110:113]
	v_mfma_f32_16x16x32_bf16 v[106:109], v[98:101], v[130:133], v[106:109]
	v_mfma_f32_16x16x32_bf16 v[78:81], v[90:93], v[138:141], v[78:81]
	v_mfma_f32_16x16x32_bf16 v[74:77], v[98:101], v[138:141], v[74:77]
	v_mfma_f32_16x16x32_bf16 v[62:65], v[90:93], v[156:159], v[62:65]
	v_mfma_f32_16x16x32_bf16 v[58:61], v[98:101], v[156:159], v[58:61]
	v_mfma_f32_16x16x32_bf16 v[110:113], v[94:97], v[134:137], v[110:113]
	v_mfma_f32_16x16x32_bf16 v[106:109], v[102:105], v[134:137], v[106:109]
	v_mfma_f32_16x16x32_bf16 v[78:81], v[94:97], v[152:155], v[78:81]
	v_mfma_f32_16x16x32_bf16 v[74:77], v[102:105], v[152:155], v[74:77]
	v_mfma_f32_16x16x32_bf16 v[62:65], v[94:97], v[160:163], v[62:65]
	v_mfma_f32_16x16x32_bf16 v[58:61], v[102:105], v[160:163], v[58:61]
	s_setprio 0
	s_setprio 1
	v_mfma_f32_16x16x32_bf16 v[86:89], v[114:117], v[130:133], v[86:89]
	v_mfma_f32_16x16x32_bf16 v[82:85], v[122:125], v[130:133], v[82:85]
	v_mfma_f32_16x16x32_bf16 v[70:73], v[114:117], v[138:141], v[70:73]
	v_mfma_f32_16x16x32_bf16 v[66:69], v[122:125], v[138:141], v[66:69]
	v_mfma_f32_16x16x32_bf16 v[54:57], v[114:117], v[156:159], v[54:57]
	v_mfma_f32_16x16x32_bf16 v[50:53], v[122:125], v[156:159], v[50:53]
	v_mfma_f32_16x16x32_bf16 v[86:89], v[118:121], v[134:137], v[86:89]
	v_mfma_f32_16x16x32_bf16 v[82:85], v[126:129], v[134:137], v[82:85]
	v_mfma_f32_16x16x32_bf16 v[70:73], v[118:121], v[152:155], v[70:73]
	v_mfma_f32_16x16x32_bf16 v[66:69], v[126:129], v[152:155], v[66:69]
	v_mfma_f32_16x16x32_bf16 v[54:57], v[118:121], v[160:163], v[54:57]
	v_mfma_f32_16x16x32_bf16 v[50:53], v[126:129], v[160:163], v[50:53]
	s_setprio 0
	s_barrier
	s_mov_b32 m0, s27
	v_lshl_add_u64 v[164:165], s[18:19], 0, v[0:1]
	s_add_u32 s14, s18, 0x160000
	s_addc_u32 s15, s19, 0
	ds_read_b128 v[130:133], v167 offset:16384
	ds_read_b128 v[134:137], v167 offset:17408
	ds_read_b128 v[138:141], v167 offset:18432
	ds_read_b128 v[152:155], v167 offset:19456
	ds_read_b128 v[156:159], v167 offset:20480
	ds_read_b128 v[160:163], v167 offset:21504
	s_cmp_lg_u32 s100, 0
	s_cbranch_scc1 .Ltl_dn_0s
	global_load_lds_dwordx4 v0, s[18:19]
	v_lshl_add_u64 v[168:169], s[18:19], 0, v[146:147]
	s_mov_b32 m0, s28
	s_nop 0
	global_load_lds_dwordx4 v146, s[18:19]
	s_mov_b32 m0, s30
	v_lshl_add_u64 v[172:173], s[20:21], 0, v[144:145]
	global_load_lds_dwordx4 v0, s[14:15]
	s_mov_b32 m0, s31
	s_nop 0
	global_load_lds_dwordx4 v146, s[14:15]
	v_lshl_add_u64 v[170:171], s[20:21], 0, v[142:143]
	s_mov_b32 m0, s34
	s_nop 0
	global_load_lds_dwordx4 v142, s[20:21]
	s_mov_b32 m0, s35
	s_nop 0
	s_and_b64 vcc, exec, s[8:9]
	s_cbranch_vccz .Lnm3d_skip1
	global_load_lds_dwordx4 v144, s[20:21]
	s_waitcnt vmcnt(8)
	s_branch .Lnm3d_done1
.Lnm3d_skip1:
	s_waitcnt vmcnt(6)
.Lnm3d_done1:
	s_branch .Ltl_dn_0d
.Ltl_dn_0s:
	s_waitcnt vmcnt(0)
.Ltl_dn_0d:
	s_waitcnt lgkmcnt(0)
	s_barrier
	s_setprio 1
	s_waitcnt lgkmcnt(0)
	v_mfma_f32_16x16x32_bf16 v[46:49], v[90:93], v[130:133], v[46:49]
	v_mfma_f32_16x16x32_bf16 v[42:45], v[98:101], v[130:133], v[42:45]
	v_mfma_f32_16x16x32_bf16 v[30:33], v[90:93], v[138:141], v[30:33]
	v_mfma_f32_16x16x32_bf16 v[26:29], v[98:101], v[138:141], v[26:29]
	v_mfma_f32_16x16x32_bf16 v[14:17], v[90:93], v[156:159], v[14:17]
	v_mfma_f32_16x16x32_bf16 v[10:13], v[98:101], v[156:159], v[10:13]
	v_mfma_f32_16x16x32_bf16 v[46:49], v[94:97], v[134:137], v[46:49]
	v_mfma_f32_16x16x32_bf16 v[42:45], v[102:105], v[134:137], v[42:45]
	v_mfma_f32_16x16x32_bf16 v[30:33], v[94:97], v[152:155], v[30:33]
	v_mfma_f32_16x16x32_bf16 v[26:29], v[102:105], v[152:155], v[26:29]
	v_mfma_f32_16x16x32_bf16 v[14:17], v[94:97], v[160:163], v[14:17]
	v_mfma_f32_16x16x32_bf16 v[10:13], v[102:105], v[160:163], v[10:13]
	s_setprio 0
	s_setprio 1
	v_mfma_f32_16x16x32_bf16 v[38:41], v[114:117], v[130:133], v[38:41]
	v_mfma_f32_16x16x32_bf16 v[34:37], v[122:125], v[130:133], v[34:37]
	v_mfma_f32_16x16x32_bf16 v[22:25], v[114:117], v[138:141], v[22:25]
	v_mfma_f32_16x16x32_bf16 v[18:21], v[122:125], v[138:141], v[18:21]
	v_mfma_f32_16x16x32_bf16 v[6:9], v[114:117], v[156:159], v[6:9]
	v_mfma_f32_16x16x32_bf16 v[2:5], v[122:125], v[156:159], v[2:5]
	v_mfma_f32_16x16x32_bf16 v[38:41], v[118:121], v[134:137], v[38:41]
	v_mfma_f32_16x16x32_bf16 v[34:37], v[126:129], v[134:137], v[34:37]
	v_mfma_f32_16x16x32_bf16 v[22:25], v[118:121], v[152:155], v[22:25]
	v_mfma_f32_16x16x32_bf16 v[18:21], v[126:129], v[152:155], v[18:21]
	v_mfma_f32_16x16x32_bf16 v[6:9], v[118:121], v[160:163], v[6:9]
	v_mfma_f32_16x16x32_bf16 v[2:5], v[126:129], v[160:163], v[2:5]
	s_setprio 0
	s_barrier
	v_add_u32_e32 v102, s38, v166
	v_add_u32_e32 v126, s45, v166
	ds_read_b128 v[90:93], v102
	ds_read_b128 v[94:97], v102 offset:1024
	ds_read_b128 v[98:101], v102 offset:2048
	ds_read_b128 v[102:105], v102 offset:3072
	ds_read_b128 v[114:117], v126
	ds_read_b128 v[118:121], v126 offset:1024
	ds_read_b128 v[122:125], v126 offset:2048
	ds_read_b128 v[126:129], v126 offset:3072
	s_add_u32 s14, s20, 0x108000
	s_addc_u32 s15, s21, 0
	s_mov_b32 m0, s36
	ds_read_b128 v[130:133], v167 offset:32768
	ds_read_b128 v[134:137], v167 offset:33792
	ds_read_b128 v[138:141], v167 offset:34816
	ds_read_b128 v[152:155], v167 offset:35840
	ds_read_b128 v[156:159], v167 offset:36864
	ds_read_b128 v[160:163], v167 offset:37888
	s_cmp_lg_u32 s100, 0
	s_cbranch_scc1 .Ltl_dn_1s
	global_load_lds_dwordx4 v142, s[14:15]
	s_mov_b32 m0, s37
	s_nop 0
	s_and_b64 vcc, exec, s[8:9]
	s_cbranch_vccz .Lnm3d_skip2
	global_load_lds_dwordx4 v144, s[14:15]
	s_waitcnt vmcnt(8)
	s_branch .Lnm3d_done2
; #define PG8_STAGE(bufoff, gbase, voff) do { _Pragma("unroll") for (int _i = 0; _i < 2; ++_i) \
;         __builtin_amdgcn_global_load_lds((const unsigned*)((const char*)(gbase) + (voff)[_i]), (LAS unsigned*)(lds + (bufoff) + ldsw + _i * 8192), 16, 0, 0); } while (0)
; #define PG8_LDA(dst, b, h) do { _Pragma("unroll") for (int m = 0; m < NM; ++m) _Pragma("unroll") for (int k = 0; k < 2; ++k) dst[m][k] = *(const LAS bf16x8*)(lds + PG8_SA(b, h) + aoff + m * 2048 + k * 1024); } while (0)
; #define PG8_MMA(ai, bj, At, Bt) do { __builtin_amdgcn_s_setprio(1); _Pragma("unroll") for (int m = 0; m < NM; ++m) _Pragma("unroll") for (int n = 0; n < 2; ++n) _Pragma("unroll") for (int k = 0; k < 2; ++k) \
;         acc[ai][bj][m][n] = __builtin_amdgcn_mfma_f32_16x16x32_bf16(Bt[n][k], At[m][k], acc[ai][bj][m][n], 0, 0, 0); __builtin_amdgcn_s_setprio(0); } while (0)
; #define PG8_WAIT_V(n) asm volatile("s_waitcnt vmcnt(" #n ")" ::: "memory")
; #define PG8_WAIT_L(n) asm volatile("s_waitcnt lgkmcnt(" #n ")" ::: "memory")
; #define PG8_BAR __builtin_amdgcn_s_barrier()
; #define PG8_SCHED __builtin_amdgcn_sched_barrier(0)
;     ...
;             PG8_WAIT_V(8); PG8_WAIT_L(0); PG8_BAR; PG8_MMA(0, 0, At, B0); PG8_MMA(0, 1, At, B1); PG8_BAR; PG8_SCHED;
;             PG8_LDA(At, 1, 1); PG8_STAGE(PG8_SB(1, 0), b3, voffB); PG8_STAGE(PG8_SB(1, 1), b3 + hstepB, voffB); PG8_STAGE(PG8_SA(1, 0), a3, voffA);
;             PG8_WAIT_V(8); PG8_WAIT_L(0); PG8_BAR; PG8_MMA(1, 0, At, B0); PG8_MMA(1, 1, At, B1); PG8_BAR; PG8_SCHED;
;     ...
;         if constexpr (ALIGN_EPI) { if (wr == 0) PG8_BAR; }
.Lnm3d_skip2:
	s_waitcnt vmcnt(6)
.Lnm3d_done2:
	s_branch .Ltl_dn_1d
.Ltl_dn_1s:
	s_waitcnt vmcnt(0)
.Ltl_dn_1d:
	s_waitcnt lgkmcnt(0)
	s_barrier
	s_setprio 1
	s_waitcnt lgkmcnt(0)
	v_mfma_f32_16x16x32_bf16 v[110:113], v[90:93], v[130:133], v[110:113]
	v_mfma_f32_16x16x32_bf16 v[106:109], v[98:101], v[130:133], v[106:109]
	v_mfma_f32_16x16x32_bf16 v[78:81], v[90:93], v[138:141], v[78:81]
	v_mfma_f32_16x16x32_bf16 v[74:77], v[98:101], v[138:141], v[74:77]
	v_mfma_f32_16x16x32_bf16 v[62:65], v[90:93], v[156:159], v[62:65]
	v_mfma_f32_16x16x32_bf16 v[58:61], v[98:101], v[156:159], v[58:61]
	v_mfma_f32_16x16x32_bf16 v[110:113], v[94:97], v[134:137], v[110:113]
	v_mfma_f32_16x16x32_bf16 v[106:109], v[102:105], v[134:137], v[106:109]
	v_mfma_f32_16x16x32_bf16 v[78:81], v[94:97], v[152:155], v[78:81]
	v_mfma_f32_16x16x32_bf16 v[74:77], v[102:105], v[152:155], v[74:77]
	v_mfma_f32_16x16x32_bf16 v[62:65], v[94:97], v[160:163], v[62:65]
	v_mfma_f32_16x16x32_bf16 v[58:61], v[102:105], v[160:163], v[58:61]
	s_setprio 0
	s_setprio 1
	v_mfma_f32_16x16x32_bf16 v[86:89], v[114:117], v[130:133], v[86:89]
	v_mfma_f32_16x16x32_bf16 v[82:85], v[122:125], v[130:133], v[82:85]
	v_mfma_f32_16x16x32_bf16 v[70:73], v[114:117], v[138:141], v[70:73]
	v_mfma_f32_16x16x32_bf16 v[66:69], v[122:125], v[138:141], v[66:69]
	v_mfma_f32_16x16x32_bf16 v[54:57], v[114:117], v[156:159], v[54:57]
	v_mfma_f32_16x16x32_bf16 v[50:53], v[122:125], v[156:159], v[50:53]
	v_mfma_f32_16x16x32_bf16 v[86:89], v[118:121], v[134:137], v[86:89]
	v_mfma_f32_16x16x32_bf16 v[82:85], v[126:129], v[134:137], v[82:85]
	v_mfma_f32_16x16x32_bf16 v[70:73], v[118:121], v[152:155], v[70:73]
	v_mfma_f32_16x16x32_bf16 v[66:69], v[126:129], v[152:155], v[66:69]
	v_mfma_f32_16x16x32_bf16 v[54:57], v[118:121], v[160:163], v[54:57]
	v_mfma_f32_16x16x32_bf16 v[50:53], v[126:129], v[160:163], v[50:53]
	s_setprio 0
	s_barrier
	s_mov_b32 m0, s41
	v_lshl_add_u64 v[164:165], v[164:165], 0, s[66:67]
	s_add_u32 s14, s18, 0x160080
	s_addc_u32 s15, s19, 0
	ds_read_b128 v[130:133], v167 offset:49152
	ds_read_b128 v[134:137], v167 offset:50176
	ds_read_b128 v[138:141], v167 offset:51200
	ds_read_b128 v[152:155], v167 offset:52224
	ds_read_b128 v[156:159], v167 offset:53248
	ds_read_b128 v[160:163], v167 offset:54272
	s_cmp_lg_u32 s100, 0
	s_cbranch_scc1 .Ltl_dn_2s
	global_load_lds_dwordx4 v[164:165], off
	v_lshl_add_u64 v[164:165], v[168:169], 0, s[66:67]
	s_mov_b32 m0, s42
	s_nop 0
	global_load_lds_dwordx4 v[164:165], off
	s_mov_b32 m0, s46
	s_nop 0
	global_load_lds_dwordx4 v0, s[14:15]
	s_mov_b32 m0, s47
	s_nop 0
	global_load_lds_dwordx4 v146, s[14:15]
	v_lshl_add_u64 v[164:165], v[170:171], 0, s[66:67]
	s_mov_b32 m0, s43
	s_nop 0
	global_load_lds_dwordx4 v[164:165], off
	v_lshl_add_u64 v[164:165], v[172:173], 0, s[66:67]
	s_mov_b32 m0, s44
	s_nop 0
	s_and_b64 vcc, exec, s[8:9]
	s_cbranch_vccz .Lnm3d_skip3
	global_load_lds_dwordx4 v[164:165], off
	s_waitcnt vmcnt(8)
	s_branch .Lnm3d_done3
.Lnm3d_skip3:
	s_waitcnt vmcnt(6)
.Lnm3d_done3:
	s_branch .Ltl_dn_2d
.Ltl_dn_2s:
	s_waitcnt vmcnt(0)
.Ltl_dn_2d:
	s_waitcnt lgkmcnt(0)
	s_barrier
	s_setprio 1
	s_waitcnt lgkmcnt(0)
	v_mfma_f32_16x16x32_bf16 v[46:49], v[90:93], v[130:133], v[46:49]
	v_mfma_f32_16x16x32_bf16 v[42:45], v[98:101], v[130:133], v[42:45]
	v_mfma_f32_16x16x32_bf16 v[30:33], v[90:93], v[138:141], v[30:33]
	v_mfma_f32_16x16x32_bf16 v[26:29], v[98:101], v[138:141], v[26:29]
	v_mfma_f32_16x16x32_bf16 v[14:17], v[90:93], v[156:159], v[14:17]
	v_mfma_f32_16x16x32_bf16 v[10:13], v[98:101], v[156:159], v[10:13]
	v_mfma_f32_16x16x32_bf16 v[46:49], v[94:97], v[134:137], v[46:49]
	v_mfma_f32_16x16x32_bf16 v[42:45], v[102:105], v[134:137], v[42:45]
	v_mfma_f32_16x16x32_bf16 v[30:33], v[94:97], v[152:155], v[30:33]
	v_mfma_f32_16x16x32_bf16 v[26:29], v[102:105], v[152:155], v[26:29]
	v_mfma_f32_16x16x32_bf16 v[14:17], v[94:97], v[160:163], v[14:17]
	v_mfma_f32_16x16x32_bf16 v[10:13], v[102:105], v[160:163], v[10:13]
	s_setprio 0
	s_setprio 1
	v_mfma_f32_16x16x32_bf16 v[38:41], v[114:117], v[130:133], v[38:41]
	v_mfma_f32_16x16x32_bf16 v[34:37], v[122:125], v[130:133], v[34:37]
	v_mfma_f32_16x16x32_bf16 v[22:25], v[114:117], v[138:141], v[22:25]
	v_mfma_f32_16x16x32_bf16 v[18:21], v[122:125], v[138:141], v[18:21]
	v_mfma_f32_16x16x32_bf16 v[6:9], v[114:117], v[156:159], v[6:9]
	v_mfma_f32_16x16x32_bf16 v[2:5], v[122:125], v[156:159], v[2:5]
	v_mfma_f32_16x16x32_bf16 v[38:41], v[118:121], v[134:137], v[38:41]
	v_mfma_f32_16x16x32_bf16 v[34:37], v[126:129], v[134:137], v[34:37]
	v_mfma_f32_16x16x32_bf16 v[22:25], v[118:121], v[152:155], v[22:25]
	v_mfma_f32_16x16x32_bf16 v[18:21], v[126:129], v[152:155], v[18:21]
	v_mfma_f32_16x16x32_bf16 v[6:9], v[118:121], v[160:163], v[6:9]
	v_mfma_f32_16x16x32_bf16 v[2:5], v[126:129], v[160:163], v[2:5]
	s_setprio 0
	s_barrier
	s_add_i32 s60, s60, 2
	s_add_u32 s2, s2, 0x100
	s_addc_u32 s3, s3, 0
	s_cmpk_gt_u32 s60, 0x55
	s_mov_b64 s[14:15], s[16:17]
	s_cbranch_scc0 .LBB0_2158
	s_and_b64 vcc, exec, s[8:9]
	s_cbranch_vccz .LBB0_2161
	s_barrier
